# v106: v102 + M0 write placed ahead of the address VALU of each LDS-DMA so the VALU is the required wait state and the s_nop goes (54 sites)
# speedup vs baseline: 1.0033x; 1.0033x over previous
; #define PG8_STAGE(bufoff, gbase, voff) do { _Pragma("unroll") for (int _i = 0; _i < 2; ++_i) \
;         __builtin_amdgcn_global_load_lds((const unsigned*)((const char*)(gbase) + (voff)[_i]), (PG8_LAS unsigned*)(lds + (bufoff) + ldsw + _i * 8192), 16, 0, 0); } while (0)
; #define PG8_LDA(dst, b, h) do { _Pragma("unroll") for (int m = 0; m < 4; ++m) _Pragma("unroll") for (int k = 0; k < 2; ++k) dst[m][k] = *(const PG8_LAS bf16x8*)(lds + PG8_SA(b, h) + aoff + m * 2048 + k * 1024); } while (0)
; #define PG8_LDB(dst, b, h) do { _Pragma("unroll") for (int n = 0; n < 2; ++n) _Pragma("unroll") for (int k = 0; k < 2; ++k) dst[n][k] = *(const PG8_LAS bf16x8*)(lds + PG8_SB(b, h) + boff + n * 2048 + k * 1024); } while (0)
; #define PG8_WAIT_V(n) asm volatile("s_waitcnt vmcnt(" #n ")" ::: "memory")
; #define PG8_WAIT_L(n) asm volatile("s_waitcnt lgkmcnt(" #n ")" ::: "memory")
; #define PG8_BAR __builtin_amdgcn_s_barrier()
; #define PG8_SCHED __builtin_amdgcn_sched_barrier(0)
; template <class Epi, class Sched, bool ALIGN_EPI, int LMASK = -1, int LMASKB = LMASK>
; __device__ __forceinline__ void gemm_phase(PG8_LAS unsigned char* lds, const Gemm g, const Sched& S, const Epi& E) {
;     ...
;         const bool has_next = S.next(ui + 1, nxt);
;         const char* nA = has_next ? (const char*)g.A + (size_t)(nxt.pm & LMASK) * tstepA : cA; const char* nB = has_next ? (const char*)g.Bt + (size_t)nxt.pm * g.b_pm_stride + (size_t)(nxt.pn & LMASKB) * tstepB : cB;
;         for (int t = 0; t < nt; t += 2) {
;             const bool last = (t == nt - 2);
;             const char* a1 = cA + (size_t)(t + 1) * kstepA;
;             const char* a2 = last ? nA : cA + (size_t)(t + 2) * kstepA; const char* b2 = last ? nB : cB + (size_t)(t + 2) * kstepB;
;             const char* a3 = a2 + kstepA; const char* b3 = b2 + kstepB;
;             PG8_LDB(B0, 0, 0); PG8_LDB(B1, 0, 1); PG8_SCHED; PG8_LDA(At, 0, 0); PG8_STAGE(PG8_SA(1, 1), a1 + hstepA, voffA);
;             PG8_WAIT_V(8); PG8_WAIT_L(0); PG8_BAR; PG8_MMA(0, 0, At, B0); PG8_MMA(0, 1, At, B1); PG8_BAR; PG8_SCHED;
;             PG8_LDA(At, 0, 1); PG8_STAGE(PG8_SB(0, 0), b2, voffB); PG8_STAGE(PG8_SB(0, 1), b2 + hstepB, voffB); PG8_STAGE(PG8_SA(0, 0), a2, voffA);
;             PG8_WAIT_V(8); PG8_WAIT_L(0); PG8_BAR; PG8_MMA(1, 0, At, B0); PG8_MMA(1, 1, At, B1); PG8_BAR; PG8_SCHED;
.LBB0_206:
	s_ashr_i32 s17, s16, 31
	s_lshl_b64 s[2:3], s[16:17], 17
	s_add_u32 s20, s1, s2
	s_addc_u32 s21, s33, s3
	s_and_b64 s[2:3], s[4:5], exec
	s_cselect_b32 s29, s21, s23
	s_cselect_b32 s28, s20, s22
	s_lshl_b64 s[2:3], s[16:17], 21
	s_add_u32 s17, s36, s2
	ds_read_b128 v[2:5], v142
	ds_read_b128 v[6:9], v142 offset:1024
	ds_read_b128 v[10:13], v142 offset:2048
	ds_read_b128 v[14:17], v142 offset:3072
	ds_read_b128 v[18:21], v143
	ds_read_b128 v[22:25], v143 offset:1024
	ds_read_b128 v[26:29], v143 offset:2048
	ds_read_b128 v[30:33], v143 offset:3072
	s_addc_u32 s26, s37, s3
	s_ashr_i32 s15, s14, 31
	s_lshl_b64 s[2:3], s[14:15], 17
	s_add_u32 s2, s17, s2
	s_addc_u32 s3, s26, s3
	s_and_b64 s[26:27], s[4:5], exec
	s_cselect_b32 s27, s3, s25
	s_cselect_b32 s26, s2, s24
	s_add_u32 s34, s22, 0x1000
	s_addc_u32 s35, s23, 0
	s_add_u32 s54, s24, 0x1000
	s_addc_u32 s55, s25, 0
	s_add_u32 s30, s22, 0x1800
	s_addc_u32 s31, s23, 0
	s_add_u32 s56, s22, 0x10800
	s_addc_u32 s57, s23, 0
	s_mov_b32 m0, s50
	v_lshl_add_u64 v[66:67], s[56:57], 0, v[130:131]
	ds_read_b128 v[34:37], v144
	ds_read_b128 v[38:41], v144 offset:1024
	ds_read_b128 v[42:45], v144 offset:2048
	ds_read_b128 v[46:49], v144 offset:3072
	ds_read_b128 v[50:53], v144 offset:4096
	ds_read_b128 v[54:57], v144 offset:5120
	ds_read_b128 v[58:61], v144 offset:6144
	ds_read_b128 v[62:65], v144 offset:7168
	global_load_lds_dwordx4 v[66:67], off
	s_mov_b32 m0, s51
	v_lshl_add_u64 v[66:67], s[56:57], 0, v[132:133]
	global_load_lds_dwordx4 v[66:67], off
	s_waitcnt vmcnt(8)
	s_waitcnt lgkmcnt(0)
	s_setprio 1
	s_barrier
	v_mfma_f32_16x16x32_bf16 v[66:69], v[2:5], v[34:37], 0
	v_mfma_f32_16x16x32_bf16 v[70:73], v[10:13], v[34:37], 0
	v_mfma_f32_16x16x32_bf16 v[74:77], v[2:5], v[42:45], 0
	v_mfma_f32_16x16x32_bf16 v[78:81], v[10:13], v[42:45], 0
	v_mfma_f32_16x16x32_bf16 v[82:85], v[2:5], v[50:53], 0
	v_mfma_f32_16x16x32_bf16 v[86:89], v[10:13], v[50:53], 0
	v_mfma_f32_16x16x32_bf16 v[90:93], v[2:5], v[58:61], 0
	v_mfma_f32_16x16x32_bf16 v[94:97], v[10:13], v[58:61], 0
	v_mfma_f32_16x16x32_bf16 v[66:69], v[6:9], v[38:41], v[66:69]
	v_mfma_f32_16x16x32_bf16 v[70:73], v[14:17], v[38:41], v[70:73]
	v_mfma_f32_16x16x32_bf16 v[74:77], v[6:9], v[46:49], v[74:77]
	v_mfma_f32_16x16x32_bf16 v[78:81], v[14:17], v[46:49], v[78:81]
	v_mfma_f32_16x16x32_bf16 v[82:85], v[6:9], v[54:57], v[82:85]
	v_mfma_f32_16x16x32_bf16 v[86:89], v[14:17], v[54:57], v[86:89]
	v_mfma_f32_16x16x32_bf16 v[90:93], v[6:9], v[62:65], v[90:93]
	v_mfma_f32_16x16x32_bf16 v[94:97], v[14:17], v[62:65], v[94:97]
	v_mfma_f32_16x16x32_bf16 v[98:101], v[18:21], v[34:37], 0
	v_mfma_f32_16x16x32_bf16 v[34:37], v[26:29], v[34:37], 0
	v_mfma_f32_16x16x32_bf16 v[98:101], v[22:25], v[38:41], v[98:101]
	v_mfma_f32_16x16x32_bf16 v[34:37], v[30:33], v[38:41], v[34:37]
	v_mfma_f32_16x16x32_bf16 v[38:41], v[18:21], v[42:45], 0
	v_mfma_f32_16x16x32_bf16 v[42:45], v[26:29], v[42:45], 0
	v_mfma_f32_16x16x32_bf16 v[38:41], v[22:25], v[46:49], v[38:41]
	v_mfma_f32_16x16x32_bf16 v[42:45], v[30:33], v[46:49], v[42:45]
	v_mfma_f32_16x16x32_bf16 v[46:49], v[18:21], v[50:53], 0
	v_mfma_f32_16x16x32_bf16 v[50:53], v[26:29], v[50:53], 0
	v_mfma_f32_16x16x32_bf16 v[46:49], v[22:25], v[54:57], v[46:49]
	v_mfma_f32_16x16x32_bf16 v[50:53], v[30:33], v[54:57], v[50:53]
	v_mfma_f32_16x16x32_bf16 v[54:57], v[18:21], v[58:61], 0
	v_mfma_f32_16x16x32_bf16 v[58:61], v[26:29], v[58:61], 0
	v_mfma_f32_16x16x32_bf16 v[54:57], v[22:25], v[62:65], v[54:57]
	v_mfma_f32_16x16x32_bf16 v[58:61], v[30:33], v[62:65], v[58:61]
	s_barrier
	s_setprio 0
	s_mov_b32 m0, s52
	v_lshl_add_u64 v[146:147], s[54:55], 0, v[130:131]
	s_add_i32 s15, s52, 0x2000
	ds_read_b128 v[62:65], v144 offset:16384
	ds_read_b128 v[102:105], v144 offset:17408
	ds_read_b128 v[106:109], v144 offset:18432
	ds_read_b128 v[110:113], v144 offset:19456
	ds_read_b128 v[114:117], v144 offset:20480
	ds_read_b128 v[118:121], v144 offset:21504
	ds_read_b128 v[122:125], v144 offset:22528
	ds_read_b128 v[126:129], v144 offset:23552
	global_load_lds_dwordx4 v[146:147], off
	v_lshl_add_u64 v[146:147], s[54:55], 0, v[132:133]
	s_add_u32 s54, s24, 0x11000
	s_mov_b32 m0, s15
	s_addc_u32 s55, s25, 0
	s_add_i32 s17, s48, s38
	global_load_lds_dwordx4 v[146:147], off
	s_mov_b32 m0, s17
	v_lshl_add_u64 v[146:147], s[54:55], 0, v[130:131]
	global_load_lds_dwordx4 v[146:147], off
	v_lshl_add_u64 v[146:147], s[54:55], 0, v[132:133]
	s_add_i32 s54, s17, 0x2000
	s_mov_b32 m0, s54
	s_nop 0
	global_load_lds_dwordx4 v[146:147], off
	s_mov_b32 m0, s19
	v_lshl_add_u64 v[146:147], s[34:35], 0, v[130:131]
	global_load_lds_dwordx4 v[146:147], off
	s_mov_b32 m0, s39
	v_lshl_add_u64 v[146:147], s[34:35], 0, v[132:133]
	global_load_lds_dwordx4 v[146:147], off
	s_waitcnt vmcnt(8)
	s_waitcnt lgkmcnt(0)
	s_setprio 1
	s_barrier
; #define PG8_STAGE(bufoff, gbase, voff) do { _Pragma("unroll") for (int _i = 0; _i < 2; ++_i) \
;         __builtin_amdgcn_global_load_lds((const unsigned*)((const char*)(gbase) + (voff)[_i]), (PG8_LAS unsigned*)(lds + (bufoff) + ldsw + _i * 8192), 16, 0, 0); } while (0)
; #define PG8_LDA(dst, b, h) do { _Pragma("unroll") for (int m = 0; m < 4; ++m) _Pragma("unroll") for (int k = 0; k < 2; ++k) dst[m][k] = *(const PG8_LAS bf16x8*)(lds + PG8_SA(b, h) + aoff + m * 2048 + k * 1024); } while (0)
; #define PG8_LDB(dst, b, h) do { _Pragma("unroll") for (int n = 0; n < 2; ++n) _Pragma("unroll") for (int k = 0; k < 2; ++k) dst[n][k] = *(const PG8_LAS bf16x8*)(lds + PG8_SB(b, h) + boff + n * 2048 + k * 1024); } while (0)
; #define PG8_MMA(ai, bj, At, Bt) do { __builtin_amdgcn_s_setprio(1); _Pragma("unroll") for (int m = 0; m < 4; ++m) _Pragma("unroll") for (int n = 0; n < 2; ++n) _Pragma("unroll") for (int k = 0; k < 2; ++k) \
;         acc[ai][bj][m][n] = __builtin_amdgcn_mfma_f32_16x16x32_bf16(Bt[n][k], At[m][k], acc[ai][bj][m][n], 0, 0, 0); __builtin_amdgcn_s_setprio(0); } while (0)
; #define PG8_WAIT_V(n) asm volatile("s_waitcnt vmcnt(" #n ")" ::: "memory")
; #define PG8_WAIT_L(n) asm volatile("s_waitcnt lgkmcnt(" #n ")" ::: "memory")
; #define PG8_BAR __builtin_amdgcn_s_barrier()
; #define PG8_SCHED __builtin_amdgcn_sched_barrier(0)
; template <class Epi, class Sched, bool ALIGN_EPI, int LMASK = -1, int LMASKB = LMASK>
; __device__ __forceinline__ void gemm_phase(PG8_LAS unsigned char* lds, const Gemm g, const Sched& S, const Epi& E) {
;     ...
;             PG8_WAIT_V(8); PG8_WAIT_L(0); PG8_BAR; PG8_MMA(1, 0, At, B0); PG8_MMA(1, 1, At, B1); PG8_BAR; PG8_SCHED;
;             PG8_LDB(B0, 1, 0); PG8_LDB(B1, 1, 1); PG8_SCHED; PG8_LDA(At, 1, 0); PG8_STAGE(PG8_SA(0, 1), a2 + hstepA, voffA);
;             PG8_WAIT_V(8); PG8_WAIT_L(0); PG8_BAR; PG8_MMA(0, 0, At, B0); PG8_MMA(0, 1, At, B1); PG8_BAR; PG8_SCHED;
;             PG8_LDA(At, 1, 1); PG8_STAGE(PG8_SB(1, 0), b3, voffB); PG8_STAGE(PG8_SB(1, 1), b3 + hstepB, voffB); PG8_STAGE(PG8_SA(1, 0), a3, voffA);
	v_mfma_f32_16x16x32_bf16 v[146:149], v[2:5], v[62:65], 0
	v_mfma_f32_16x16x32_bf16 v[154:157], v[2:5], v[106:109], 0
	v_mfma_f32_16x16x32_bf16 v[162:165], v[2:5], v[114:117], 0
	v_mfma_f32_16x16x32_bf16 v[2:5], v[2:5], v[122:125], 0
	v_mfma_f32_16x16x32_bf16 v[146:149], v[6:9], v[102:105], v[146:149]
	v_mfma_f32_16x16x32_bf16 v[154:157], v[6:9], v[110:113], v[154:157]
	v_mfma_f32_16x16x32_bf16 v[162:165], v[6:9], v[118:121], v[162:165]
	v_mfma_f32_16x16x32_bf16 v[2:5], v[6:9], v[126:129], v[2:5]
	v_mfma_f32_16x16x32_bf16 v[6:9], v[10:13], v[122:125], 0
	v_mfma_f32_16x16x32_bf16 v[150:153], v[10:13], v[62:65], 0
	v_mfma_f32_16x16x32_bf16 v[158:161], v[10:13], v[106:109], 0
	v_mfma_f32_16x16x32_bf16 v[166:169], v[10:13], v[114:117], 0
	v_mfma_f32_16x16x32_bf16 v[6:9], v[14:17], v[126:129], v[6:9]
	v_mfma_f32_16x16x32_bf16 v[150:153], v[14:17], v[102:105], v[150:153]
	v_mfma_f32_16x16x32_bf16 v[158:161], v[14:17], v[110:113], v[158:161]
	v_mfma_f32_16x16x32_bf16 v[166:169], v[14:17], v[118:121], v[166:169]
	v_mfma_f32_16x16x32_bf16 v[10:13], v[18:21], v[62:65], 0
	v_mfma_f32_16x16x32_bf16 v[14:17], v[26:29], v[62:65], 0
	v_mfma_f32_16x16x32_bf16 v[10:13], v[22:25], v[102:105], v[10:13]
	v_mfma_f32_16x16x32_bf16 v[14:17], v[30:33], v[102:105], v[14:17]
	v_mfma_f32_16x16x32_bf16 v[62:65], v[18:21], v[106:109], 0
	v_mfma_f32_16x16x32_bf16 v[102:105], v[26:29], v[106:109], 0
	v_mfma_f32_16x16x32_bf16 v[106:109], v[18:21], v[114:117], 0
	v_mfma_f32_16x16x32_bf16 v[18:21], v[18:21], v[122:125], 0
	v_mfma_f32_16x16x32_bf16 v[62:65], v[22:25], v[110:113], v[62:65]
	v_mfma_f32_16x16x32_bf16 v[102:105], v[30:33], v[110:113], v[102:105]
	v_mfma_f32_16x16x32_bf16 v[106:109], v[22:25], v[118:121], v[106:109]
	v_mfma_f32_16x16x32_bf16 v[110:113], v[26:29], v[114:117], 0
	v_mfma_f32_16x16x32_bf16 v[18:21], v[22:25], v[126:129], v[18:21]
	v_mfma_f32_16x16x32_bf16 v[22:25], v[26:29], v[122:125], 0
	v_mfma_f32_16x16x32_bf16 v[110:113], v[30:33], v[118:121], v[110:113]
	v_mfma_f32_16x16x32_bf16 v[22:25], v[30:33], v[126:129], v[22:25]
	s_barrier
	s_setprio 0
	s_add_i32 s55, 0, 0x18000
	s_add_i32 s58, 0, 0x1c000
	v_add_u32_e32 v134, s55, v1
	v_add_u32_e32 v222, s58, v1
	ds_read_b128 v[26:29], v134
	ds_read_b128 v[30:33], v134 offset:1024
	ds_read_b128 v[114:117], v134 offset:2048
	ds_read_b128 v[118:121], v134 offset:3072
	ds_read_b128 v[122:125], v222
	ds_read_b128 v[126:129], v222 offset:1024
	ds_read_b128 v[170:173], v222 offset:2048
	ds_read_b128 v[174:177], v222 offset:3072
	s_add_u32 s34, s22, 0x11000
	s_addc_u32 s35, s23, 0
	s_mov_b32 m0, s40
	v_lshl_add_u64 v[210:211], s[34:35], 0, v[130:131]
	ds_read_b128 v[178:181], v144 offset:32768
	ds_read_b128 v[182:185], v144 offset:33792
	ds_read_b128 v[186:189], v144 offset:34816
	ds_read_b128 v[190:193], v144 offset:35840
	ds_read_b128 v[194:197], v144 offset:36864
	ds_read_b128 v[198:201], v144 offset:37888
	ds_read_b128 v[202:205], v144 offset:38912
	ds_read_b128 v[206:209], v144 offset:39936
	global_load_lds_dwordx4 v[210:211], off
	s_mov_b32 m0, s41
	v_lshl_add_u64 v[210:211], s[34:35], 0, v[132:133]
	global_load_lds_dwordx4 v[210:211], off
	s_waitcnt vmcnt(8)
	s_waitcnt lgkmcnt(0)
	s_setprio 1
	s_barrier
	v_mfma_f32_16x16x32_bf16 v[66:69], v[26:29], v[178:181], v[66:69]
	v_mfma_f32_16x16x32_bf16 v[70:73], v[114:117], v[178:181], v[70:73]
	v_mfma_f32_16x16x32_bf16 v[74:77], v[26:29], v[186:189], v[74:77]
	v_mfma_f32_16x16x32_bf16 v[78:81], v[114:117], v[186:189], v[78:81]
	v_mfma_f32_16x16x32_bf16 v[82:85], v[26:29], v[194:197], v[82:85]
	v_mfma_f32_16x16x32_bf16 v[86:89], v[114:117], v[194:197], v[86:89]
	v_mfma_f32_16x16x32_bf16 v[90:93], v[26:29], v[202:205], v[90:93]
	v_mfma_f32_16x16x32_bf16 v[94:97], v[114:117], v[202:205], v[94:97]
	v_mfma_f32_16x16x32_bf16 v[66:69], v[30:33], v[182:185], v[66:69]
	v_mfma_f32_16x16x32_bf16 v[70:73], v[118:121], v[182:185], v[70:73]
	v_mfma_f32_16x16x32_bf16 v[74:77], v[30:33], v[190:193], v[74:77]
	v_mfma_f32_16x16x32_bf16 v[78:81], v[118:121], v[190:193], v[78:81]
	v_mfma_f32_16x16x32_bf16 v[82:85], v[30:33], v[198:201], v[82:85]
	v_mfma_f32_16x16x32_bf16 v[86:89], v[118:121], v[198:201], v[86:89]
	v_mfma_f32_16x16x32_bf16 v[90:93], v[30:33], v[206:209], v[90:93]
	v_mfma_f32_16x16x32_bf16 v[94:97], v[118:121], v[206:209], v[94:97]
	v_mfma_f32_16x16x32_bf16 v[98:101], v[122:125], v[178:181], v[98:101]
	v_mfma_f32_16x16x32_bf16 v[34:37], v[170:173], v[178:181], v[34:37]
	v_mfma_f32_16x16x32_bf16 v[38:41], v[122:125], v[186:189], v[38:41]
	v_mfma_f32_16x16x32_bf16 v[42:45], v[170:173], v[186:189], v[42:45]
	v_mfma_f32_16x16x32_bf16 v[46:49], v[122:125], v[194:197], v[46:49]
	v_mfma_f32_16x16x32_bf16 v[50:53], v[170:173], v[194:197], v[50:53]
	v_mfma_f32_16x16x32_bf16 v[54:57], v[122:125], v[202:205], v[54:57]
	v_mfma_f32_16x16x32_bf16 v[58:61], v[170:173], v[202:205], v[58:61]
	v_mfma_f32_16x16x32_bf16 v[98:101], v[126:129], v[182:185], v[98:101]
	v_mfma_f32_16x16x32_bf16 v[34:37], v[174:177], v[182:185], v[34:37]
	v_mfma_f32_16x16x32_bf16 v[38:41], v[126:129], v[190:193], v[38:41]
	v_mfma_f32_16x16x32_bf16 v[42:45], v[174:177], v[190:193], v[42:45]
	v_mfma_f32_16x16x32_bf16 v[46:49], v[126:129], v[198:201], v[46:49]
	v_mfma_f32_16x16x32_bf16 v[50:53], v[174:177], v[198:201], v[50:53]
	v_mfma_f32_16x16x32_bf16 v[54:57], v[126:129], v[206:209], v[54:57]
	v_mfma_f32_16x16x32_bf16 v[58:61], v[174:177], v[206:209], v[58:61]
	s_barrier
; #define PG8_STAGE(bufoff, gbase, voff) do { _Pragma("unroll") for (int _i = 0; _i < 2; ++_i) \
;         __builtin_amdgcn_global_load_lds((const unsigned*)((const char*)(gbase) + (voff)[_i]), (PG8_LAS unsigned*)(lds + (bufoff) + ldsw + _i * 8192), 16, 0, 0); } while (0)
; #define PG8_LDA(dst, b, h) do { _Pragma("unroll") for (int m = 0; m < 4; ++m) _Pragma("unroll") for (int k = 0; k < 2; ++k) dst[m][k] = *(const PG8_LAS bf16x8*)(lds + PG8_SA(b, h) + aoff + m * 2048 + k * 1024); } while (0)
; #define PG8_LDB(dst, b, h) do { _Pragma("unroll") for (int n = 0; n < 2; ++n) _Pragma("unroll") for (int k = 0; k < 2; ++k) dst[n][k] = *(const PG8_LAS bf16x8*)(lds + PG8_SB(b, h) + boff + n * 2048 + k * 1024); } while (0)
; #define PG8_MMA(ai, bj, At, Bt) do { __builtin_amdgcn_s_setprio(1); _Pragma("unroll") for (int m = 0; m < 4; ++m) _Pragma("unroll") for (int n = 0; n < 2; ++n) _Pragma("unroll") for (int k = 0; k < 2; ++k) \
;         acc[ai][bj][m][n] = __builtin_amdgcn_mfma_f32_16x16x32_bf16(Bt[n][k], At[m][k], acc[ai][bj][m][n], 0, 0, 0); __builtin_amdgcn_s_setprio(0); } while (0)
; #define PG8_BAR __builtin_amdgcn_s_barrier()
; template <class Epi, class Sched, bool ALIGN_EPI, int LMASK = -1, int LMASKB = LMASK>
; __device__ __forceinline__ void gemm_phase(PG8_LAS unsigned char* lds, const Gemm g, const Sched& S, const Epi& E) {
;     ...
;             PG8_LDB(B0, 0, 0); PG8_LDB(B1, 0, 1); PG8_SCHED; PG8_LDA(At, 0, 0); PG8_STAGE(PG8_SA(1, 1), a1 + hstepA, voffA);
;             PG8_WAIT_V(8); PG8_WAIT_L(0); PG8_BAR; PG8_MMA(0, 0, At, B0); PG8_MMA(0, 1, At, B1); PG8_BAR; PG8_SCHED;
;             PG8_LDA(At, 0, 1); PG8_STAGE(PG8_SB(0, 0), b2, voffB); PG8_STAGE(PG8_SB(0, 1), b2 + hstepB, voffB); PG8_STAGE(PG8_SA(0, 0), a2, voffA);
;             PG8_WAIT_V(8); PG8_WAIT_L(0); PG8_BAR; PG8_MMA(1, 0, At, B0); PG8_MMA(1, 1, At, B1); PG8_BAR; PG8_SCHED;
;             PG8_LDB(B0, 1, 0); PG8_LDB(B1, 1, 1); PG8_SCHED; PG8_LDA(At, 1, 0); PG8_STAGE(PG8_SA(0, 1), a2 + hstepA, voffA);
;             PG8_WAIT_V(8); PG8_WAIT_L(0); PG8_BAR; PG8_MMA(0, 0, At, B0); PG8_MMA(0, 1, At, B1); PG8_BAR; PG8_SCHED;
;             PG8_LDA(At, 1, 1); PG8_STAGE(PG8_SB(1, 0), b3, voffB); PG8_STAGE(PG8_SB(1, 1), b3 + hstepB, voffB); PG8_STAGE(PG8_SA(1, 0), a3, voffA);
;             PG8_WAIT_V(8); PG8_WAIT_L(0); PG8_BAR; PG8_MMA(1, 0, At, B0); PG8_MMA(1, 1, At, B1); PG8_BAR; PG8_SCHED;
	s_setprio 0
	s_add_u32 s56, s24, 0x1800
	s_addc_u32 s57, s25, 0
	s_add_i32 s35, s55, s38
	v_lshl_add_u64 v[210:211], s[56:57], 0, v[130:131]
	s_mov_b32 m0, s35
	s_add_i32 s34, s35, 0x2000
	ds_read_b128 v[178:181], v144 offset:49152
	ds_read_b128 v[182:185], v144 offset:50176
	ds_read_b128 v[186:189], v144 offset:51200
	ds_read_b128 v[190:193], v144 offset:52224
	ds_read_b128 v[194:197], v144 offset:53248
	ds_read_b128 v[198:201], v144 offset:54272
	ds_read_b128 v[202:205], v144 offset:55296
	ds_read_b128 v[206:209], v144 offset:56320
	global_load_lds_dwordx4 v[210:211], off
	v_lshl_add_u64 v[210:211], s[56:57], 0, v[132:133]
	s_add_u32 s56, s24, 0x11800
	s_mov_b32 m0, s34
	s_addc_u32 s57, s25, 0
	s_add_i32 s24, s58, s38
	global_load_lds_dwordx4 v[210:211], off
	v_lshl_add_u64 v[210:211], s[56:57], 0, v[130:131]
	s_mov_b32 m0, s24
	s_add_i32 s25, s24, 0x2000
	global_load_lds_dwordx4 v[210:211], off
	s_mov_b32 m0, s25
	v_lshl_add_u64 v[210:211], s[56:57], 0, v[132:133]
	global_load_lds_dwordx4 v[210:211], off
	s_mov_b32 m0, s44
	v_lshl_add_u64 v[210:211], s[30:31], 0, v[130:131]
	global_load_lds_dwordx4 v[210:211], off
	s_mov_b32 m0, s45
	v_lshl_add_u64 v[210:211], s[30:31], 0, v[132:133]
	global_load_lds_dwordx4 v[210:211], off
	s_waitcnt vmcnt(8)
	s_waitcnt lgkmcnt(0)
	s_setprio 1
	s_barrier
	v_mfma_f32_16x16x32_bf16 v[2:5], v[26:29], v[202:205], v[2:5]
	v_mfma_f32_16x16x32_bf16 v[6:9], v[114:117], v[202:205], v[6:9]
	v_mfma_f32_16x16x32_bf16 v[146:149], v[26:29], v[178:181], v[146:149]
	v_mfma_f32_16x16x32_bf16 v[150:153], v[114:117], v[178:181], v[150:153]
	v_mfma_f32_16x16x32_bf16 v[154:157], v[26:29], v[186:189], v[154:157]
	v_mfma_f32_16x16x32_bf16 v[158:161], v[114:117], v[186:189], v[158:161]
	v_mfma_f32_16x16x32_bf16 v[162:165], v[26:29], v[194:197], v[162:165]
	v_mfma_f32_16x16x32_bf16 v[166:169], v[114:117], v[194:197], v[166:169]
	v_mfma_f32_16x16x32_bf16 v[2:5], v[30:33], v[206:209], v[2:5]
	v_mfma_f32_16x16x32_bf16 v[6:9], v[118:121], v[206:209], v[6:9]
	v_mfma_f32_16x16x32_bf16 v[146:149], v[30:33], v[182:185], v[146:149]
	v_mfma_f32_16x16x32_bf16 v[150:153], v[118:121], v[182:185], v[150:153]
	v_mfma_f32_16x16x32_bf16 v[154:157], v[30:33], v[190:193], v[154:157]
	v_mfma_f32_16x16x32_bf16 v[158:161], v[118:121], v[190:193], v[158:161]
	v_mfma_f32_16x16x32_bf16 v[162:165], v[30:33], v[198:201], v[162:165]
	v_mfma_f32_16x16x32_bf16 v[166:169], v[118:121], v[198:201], v[166:169]
	v_mfma_f32_16x16x32_bf16 v[10:13], v[122:125], v[178:181], v[10:13]
	v_mfma_f32_16x16x32_bf16 v[14:17], v[170:173], v[178:181], v[14:17]
	v_mfma_f32_16x16x32_bf16 v[26:29], v[122:125], v[186:189], v[62:65]
	v_mfma_f32_16x16x32_bf16 v[30:33], v[170:173], v[186:189], v[102:105]
	v_mfma_f32_16x16x32_bf16 v[62:65], v[122:125], v[194:197], v[106:109]
	v_mfma_f32_16x16x32_bf16 v[102:105], v[170:173], v[194:197], v[110:113]
	v_mfma_f32_16x16x32_bf16 v[18:21], v[122:125], v[202:205], v[18:21]
	v_mfma_f32_16x16x32_bf16 v[22:25], v[170:173], v[202:205], v[22:25]
	v_mfma_f32_16x16x32_bf16 v[10:13], v[126:129], v[182:185], v[10:13]
	v_mfma_f32_16x16x32_bf16 v[14:17], v[174:177], v[182:185], v[14:17]
	v_mfma_f32_16x16x32_bf16 v[26:29], v[126:129], v[190:193], v[26:29]
	v_mfma_f32_16x16x32_bf16 v[30:33], v[174:177], v[190:193], v[30:33]
	v_mfma_f32_16x16x32_bf16 v[62:65], v[126:129], v[198:201], v[62:65]
	v_mfma_f32_16x16x32_bf16 v[102:105], v[174:177], v[198:201], v[102:105]
	v_mfma_f32_16x16x32_bf16 v[18:21], v[126:129], v[206:209], v[18:21]
	v_mfma_f32_16x16x32_bf16 v[22:25], v[174:177], v[206:209], v[22:25]
	s_barrier
	s_setprio 0
	ds_read_b128 v[106:109], v142
	ds_read_b128 v[110:113], v142 offset:1024
	ds_read_b128 v[114:117], v142 offset:2048
	ds_read_b128 v[118:121], v142 offset:3072
	ds_read_b128 v[122:125], v143
	ds_read_b128 v[126:129], v143 offset:1024
	ds_read_b128 v[170:173], v143 offset:2048
	ds_read_b128 v[174:177], v143 offset:3072
	s_add_u32 s22, s22, 0x11800
	s_addc_u32 s23, s23, 0
	s_mov_b32 m0, s50
	v_lshl_add_u64 v[210:211], s[22:23], 0, v[130:131]
	ds_read_b128 v[178:181], v144
	ds_read_b128 v[182:185], v144 offset:1024
	ds_read_b128 v[186:189], v144 offset:2048
	ds_read_b128 v[190:193], v144 offset:3072
	ds_read_b128 v[194:197], v144 offset:4096
	ds_read_b128 v[198:201], v144 offset:5120
	ds_read_b128 v[202:205], v144 offset:6144
	ds_read_b128 v[206:209], v144 offset:7168
	global_load_lds_dwordx4 v[210:211], off
	s_mov_b32 m0, s51
	v_lshl_add_u64 v[210:211], s[22:23], 0, v[132:133]
	global_load_lds_dwordx4 v[210:211], off
	s_waitcnt vmcnt(8)
	s_waitcnt lgkmcnt(0)
	s_setprio 1
	s_barrier
; #define PG8_STAGE(bufoff, gbase, voff) do { _Pragma("unroll") for (int _i = 0; _i < 2; ++_i) \
;         __builtin_amdgcn_global_load_lds((const unsigned*)((const char*)(gbase) + (voff)[_i]), (PG8_LAS unsigned*)(lds + (bufoff) + ldsw + _i * 8192), 16, 0, 0); } while (0)
; #define PG8_LDA(dst, b, h) do { _Pragma("unroll") for (int m = 0; m < 4; ++m) _Pragma("unroll") for (int k = 0; k < 2; ++k) dst[m][k] = *(const PG8_LAS bf16x8*)(lds + PG8_SA(b, h) + aoff + m * 2048 + k * 1024); } while (0)
; #define PG8_MMA(ai, bj, At, Bt) do { __builtin_amdgcn_s_setprio(1); _Pragma("unroll") for (int m = 0; m < 4; ++m) _Pragma("unroll") for (int n = 0; n < 2; ++n) _Pragma("unroll") for (int k = 0; k < 2; ++k) \
;         acc[ai][bj][m][n] = __builtin_amdgcn_mfma_f32_16x16x32_bf16(Bt[n][k], At[m][k], acc[ai][bj][m][n], 0, 0, 0); __builtin_amdgcn_s_setprio(0); } while (0)
; #define PG8_WAIT_V(n) asm volatile("s_waitcnt vmcnt(" #n ")" ::: "memory")
; #define PG8_WAIT_L(n) asm volatile("s_waitcnt lgkmcnt(" #n ")" ::: "memory")
; #define PG8_BAR __builtin_amdgcn_s_barrier()
; #define PG8_SCHED __builtin_amdgcn_sched_barrier(0)
; template <class Epi, class Sched, bool ALIGN_EPI, int LMASK = -1, int LMASKB = LMASK>
; __device__ __forceinline__ void gemm_phase(PG8_LAS unsigned char* lds, const Gemm g, const Sched& S, const Epi& E) {
;     ...
;             PG8_WAIT_V(8); PG8_WAIT_L(0); PG8_BAR; PG8_MMA(0, 0, At, B0); PG8_MMA(0, 1, At, B1); PG8_BAR; PG8_SCHED;
;             PG8_LDA(At, 0, 1); PG8_STAGE(PG8_SB(0, 0), b2, voffB); PG8_STAGE(PG8_SB(0, 1), b2 + hstepB, voffB); PG8_STAGE(PG8_SA(0, 0), a2, voffA);
;             PG8_WAIT_V(8); PG8_WAIT_L(0); PG8_BAR; PG8_MMA(1, 0, At, B0); PG8_MMA(1, 1, At, B1); PG8_BAR; PG8_SCHED;
	v_mfma_f32_16x16x32_bf16 v[66:69], v[106:109], v[178:181], v[66:69]
	v_mfma_f32_16x16x32_bf16 v[70:73], v[114:117], v[178:181], v[70:73]
	v_mfma_f32_16x16x32_bf16 v[74:77], v[106:109], v[186:189], v[74:77]
	v_mfma_f32_16x16x32_bf16 v[78:81], v[114:117], v[186:189], v[78:81]
	v_mfma_f32_16x16x32_bf16 v[82:85], v[106:109], v[194:197], v[82:85]
	v_mfma_f32_16x16x32_bf16 v[86:89], v[114:117], v[194:197], v[86:89]
	v_mfma_f32_16x16x32_bf16 v[90:93], v[106:109], v[202:205], v[90:93]
	v_mfma_f32_16x16x32_bf16 v[94:97], v[114:117], v[202:205], v[94:97]
	v_mfma_f32_16x16x32_bf16 v[66:69], v[110:113], v[182:185], v[66:69]
	v_mfma_f32_16x16x32_bf16 v[70:73], v[118:121], v[182:185], v[70:73]
	v_mfma_f32_16x16x32_bf16 v[74:77], v[110:113], v[190:193], v[74:77]
	v_mfma_f32_16x16x32_bf16 v[78:81], v[118:121], v[190:193], v[78:81]
	v_mfma_f32_16x16x32_bf16 v[82:85], v[110:113], v[198:201], v[82:85]
	v_mfma_f32_16x16x32_bf16 v[86:89], v[118:121], v[198:201], v[86:89]
	v_mfma_f32_16x16x32_bf16 v[90:93], v[110:113], v[206:209], v[90:93]
	v_mfma_f32_16x16x32_bf16 v[94:97], v[118:121], v[206:209], v[94:97]
	v_mfma_f32_16x16x32_bf16 v[34:37], v[170:173], v[178:181], v[34:37]
	v_mfma_f32_16x16x32_bf16 v[98:101], v[122:125], v[178:181], v[98:101]
	v_mfma_f32_16x16x32_bf16 v[178:181], v[174:177], v[182:185], v[34:37]
	v_mfma_f32_16x16x32_bf16 v[34:37], v[122:125], v[186:189], v[38:41]
	v_mfma_f32_16x16x32_bf16 v[210:213], v[126:129], v[182:185], v[98:101]
	v_mfma_f32_16x16x32_bf16 v[182:185], v[126:129], v[190:193], v[34:37]
	v_mfma_f32_16x16x32_bf16 v[34:37], v[170:173], v[186:189], v[42:45]
	v_mfma_f32_16x16x32_bf16 v[42:45], v[174:177], v[190:193], v[34:37]
	v_mfma_f32_16x16x32_bf16 v[34:37], v[122:125], v[194:197], v[46:49]
	v_mfma_f32_16x16x32_bf16 v[46:49], v[126:129], v[198:201], v[34:37]
	v_mfma_f32_16x16x32_bf16 v[34:37], v[170:173], v[194:197], v[50:53]
	v_mfma_f32_16x16x32_bf16 v[50:53], v[174:177], v[198:201], v[34:37]
	v_mfma_f32_16x16x32_bf16 v[34:37], v[122:125], v[202:205], v[54:57]
	v_mfma_f32_16x16x32_bf16 v[54:57], v[126:129], v[206:209], v[34:37]
	v_mfma_f32_16x16x32_bf16 v[34:37], v[170:173], v[202:205], v[58:61]
	v_mfma_f32_16x16x32_bf16 v[58:61], v[174:177], v[206:209], v[34:37]
	s_barrier
	s_setprio 0
	s_mov_b32 m0, s52
	v_lshl_add_u64 v[246:247], s[26:27], 0, v[130:131]
	s_add_u32 s22, s26, 0x10000
	s_nop 1
	ds_read_b128 v[34:37], v144 offset:16384
	ds_read_b128 v[38:41], v144 offset:17408
	ds_read_b128 v[98:101], v144 offset:18432
	ds_read_b128 v[186:189], v144 offset:19456
	ds_read_b128 v[190:193], v144 offset:20480
	ds_read_b128 v[194:197], v144 offset:21504
	ds_read_b128 v[198:201], v144 offset:22528
	ds_read_b128 v[202:205], v144 offset:23552
	global_load_lds_dwordx4 v[246:247], off
	v_lshl_add_u64 v[248:249], s[26:27], 0, v[132:133]
	s_mov_b32 m0, s15
	s_addc_u32 s23, s27, 0
	global_load_lds_dwordx4 v[248:249], off
	v_lshl_add_u64 v[206:207], s[22:23], 0, v[130:131]
	s_mov_b32 m0, s17
	v_lshl_add_u64 v[250:251], s[28:29], 0, v[130:131]
	global_load_lds_dwordx4 v[206:207], off
	v_lshl_add_u64 v[206:207], s[22:23], 0, v[132:133]
	s_mov_b32 m0, s54
	v_lshl_add_u64 v[252:253], s[28:29], 0, v[132:133]
	global_load_lds_dwordx4 v[206:207], off
	s_mov_b32 m0, s19
	s_nop 0
	global_load_lds_dwordx4 v[250:251], off
	s_mov_b32 m0, s39
	s_nop 0
	global_load_lds_dwordx4 v[252:253], off
	s_waitcnt vmcnt(8)
	s_waitcnt lgkmcnt(0)
	s_setprio 1
	s_barrier
	v_mfma_f32_16x16x32_bf16 v[2:5], v[106:109], v[198:201], v[2:5]
	v_mfma_f32_16x16x32_bf16 v[6:9], v[114:117], v[198:201], v[6:9]
	v_mfma_f32_16x16x32_bf16 v[146:149], v[106:109], v[34:37], v[146:149]
	v_mfma_f32_16x16x32_bf16 v[150:153], v[114:117], v[34:37], v[150:153]
	v_mfma_f32_16x16x32_bf16 v[154:157], v[106:109], v[98:101], v[154:157]
	v_mfma_f32_16x16x32_bf16 v[158:161], v[114:117], v[98:101], v[158:161]
	v_mfma_f32_16x16x32_bf16 v[162:165], v[106:109], v[190:193], v[162:165]
	v_mfma_f32_16x16x32_bf16 v[166:169], v[114:117], v[190:193], v[166:169]
	v_mfma_f32_16x16x32_bf16 v[2:5], v[110:113], v[202:205], v[2:5]
	v_mfma_f32_16x16x32_bf16 v[6:9], v[118:121], v[202:205], v[6:9]
	v_mfma_f32_16x16x32_bf16 v[146:149], v[110:113], v[38:41], v[146:149]
	v_mfma_f32_16x16x32_bf16 v[150:153], v[118:121], v[38:41], v[150:153]
	v_mfma_f32_16x16x32_bf16 v[154:157], v[110:113], v[186:189], v[154:157]
	v_mfma_f32_16x16x32_bf16 v[158:161], v[118:121], v[186:189], v[158:161]
	v_mfma_f32_16x16x32_bf16 v[162:165], v[110:113], v[194:197], v[162:165]
	v_mfma_f32_16x16x32_bf16 v[166:169], v[118:121], v[194:197], v[166:169]
	v_mfma_f32_16x16x32_bf16 v[10:13], v[122:125], v[34:37], v[10:13]
	v_mfma_f32_16x16x32_bf16 v[14:17], v[170:173], v[34:37], v[14:17]
	v_mfma_f32_16x16x32_bf16 v[26:29], v[122:125], v[98:101], v[26:29]
	v_mfma_f32_16x16x32_bf16 v[30:33], v[170:173], v[98:101], v[30:33]
	v_mfma_f32_16x16x32_bf16 v[34:37], v[122:125], v[190:193], v[62:65]
	v_mfma_f32_16x16x32_bf16 v[26:29], v[126:129], v[186:189], v[26:29]
	v_mfma_f32_16x16x32_bf16 v[30:33], v[174:177], v[186:189], v[30:33]
	v_mfma_f32_16x16x32_bf16 v[186:189], v[126:129], v[194:197], v[34:37]
	v_mfma_f32_16x16x32_bf16 v[34:37], v[170:173], v[190:193], v[102:105]
	v_mfma_f32_16x16x32_bf16 v[18:21], v[122:125], v[198:201], v[18:21]
	v_mfma_f32_16x16x32_bf16 v[10:13], v[126:129], v[38:41], v[10:13]
	v_mfma_f32_16x16x32_bf16 v[14:17], v[174:177], v[38:41], v[14:17]
	v_mfma_f32_16x16x32_bf16 v[190:193], v[174:177], v[194:197], v[34:37]
	v_mfma_f32_16x16x32_bf16 v[194:197], v[126:129], v[202:205], v[18:21]
	v_mfma_f32_16x16x32_bf16 v[18:21], v[170:173], v[198:201], v[22:25]
	v_mfma_f32_16x16x32_bf16 v[170:173], v[174:177], v[202:205], v[18:21]
	s_barrier
; #define PG8_STAGE(bufoff, gbase, voff) do { _Pragma("unroll") for (int _i = 0; _i < 2; ++_i) \
;         __builtin_amdgcn_global_load_lds((const unsigned*)((const char*)(gbase) + (voff)[_i]), (PG8_LAS unsigned*)(lds + (bufoff) + ldsw + _i * 8192), 16, 0, 0); } while (0)
; #define PG8_LDA(dst, b, h) do { _Pragma("unroll") for (int m = 0; m < 4; ++m) _Pragma("unroll") for (int k = 0; k < 2; ++k) dst[m][k] = *(const PG8_LAS bf16x8*)(lds + PG8_SA(b, h) + aoff + m * 2048 + k * 1024); } while (0)
; #define PG8_LDB(dst, b, h) do { _Pragma("unroll") for (int n = 0; n < 2; ++n) _Pragma("unroll") for (int k = 0; k < 2; ++k) dst[n][k] = *(const PG8_LAS bf16x8*)(lds + PG8_SB(b, h) + boff + n * 2048 + k * 1024); } while (0)
; #define PG8_MMA(ai, bj, At, Bt) do { __builtin_amdgcn_s_setprio(1); _Pragma("unroll") for (int m = 0; m < 4; ++m) _Pragma("unroll") for (int n = 0; n < 2; ++n) _Pragma("unroll") for (int k = 0; k < 2; ++k) \
;         acc[ai][bj][m][n] = __builtin_amdgcn_mfma_f32_16x16x32_bf16(Bt[n][k], At[m][k], acc[ai][bj][m][n], 0, 0, 0); __builtin_amdgcn_s_setprio(0); } while (0)
; #define PG8_WAIT_V(n) asm volatile("s_waitcnt vmcnt(" #n ")" ::: "memory")
; #define PG8_WAIT_L(n) asm volatile("s_waitcnt lgkmcnt(" #n ")" ::: "memory")
; #define PG8_BAR __builtin_amdgcn_s_barrier()
; #define PG8_SCHED __builtin_amdgcn_sched_barrier(0)
; template <class Epi, class Sched, bool ALIGN_EPI, int LMASK = -1, int LMASKB = LMASK>
; __device__ __forceinline__ void gemm_phase(PG8_LAS unsigned char* lds, const Gemm g, const Sched& S, const Epi& E) {
;     ...
;             PG8_LDB(B0, 1, 0); PG8_LDB(B1, 1, 1); PG8_SCHED; PG8_LDA(At, 1, 0); PG8_STAGE(PG8_SA(0, 1), a2 + hstepA, voffA);
;             PG8_WAIT_V(8); PG8_WAIT_L(0); PG8_BAR; PG8_MMA(0, 0, At, B0); PG8_MMA(0, 1, At, B1); PG8_BAR; PG8_SCHED;
;             PG8_LDA(At, 1, 1); PG8_STAGE(PG8_SB(1, 0), b3, voffB); PG8_STAGE(PG8_SB(1, 1), b3 + hstepB, voffB); PG8_STAGE(PG8_SA(1, 0), a3, voffA);
;             PG8_WAIT_V(8); PG8_WAIT_L(0); PG8_BAR; PG8_MMA(1, 0, At, B0); PG8_MMA(1, 1, At, B1); PG8_BAR; PG8_SCHED;
;         }
;         if constexpr (ALIGN_EPI) { if (wr == 0) PG8_BAR; }
	s_setprio 0
	ds_read_b128 v[62:65], v134
	ds_read_b128 v[174:177], v134 offset:1024
	ds_read_b128 v[198:201], v134 offset:2048
	ds_read_b128 v[202:205], v134 offset:3072
	ds_read_b128 v[206:209], v222
	ds_read_b128 v[214:217], v222 offset:1024
	ds_read_b128 v[218:221], v222 offset:2048
	ds_read_b128 v[222:225], v222 offset:3072
	s_add_u32 s22, s28, 0x10000
	s_addc_u32 s23, s29, 0
	s_mov_b32 m0, s40
	v_lshl_add_u64 v[34:35], s[22:23], 0, v[130:131]
	ds_read_b128 v[18:21], v144 offset:32768
	ds_read_b128 v[22:25], v144 offset:33792
	ds_read_b128 v[110:113], v144 offset:34816
	ds_read_b128 v[226:229], v144 offset:35840
	ds_read_b128 v[230:233], v144 offset:36864
	ds_read_b128 v[234:237], v144 offset:37888
	ds_read_b128 v[238:241], v144 offset:38912
	ds_read_b128 v[242:245], v144 offset:39936
	global_load_lds_dwordx4 v[34:35], off
	s_mov_b32 m0, s41
	v_lshl_add_u64 v[34:35], s[22:23], 0, v[132:133]
	global_load_lds_dwordx4 v[34:35], off
	s_waitcnt vmcnt(8)
	s_waitcnt lgkmcnt(0)
	s_setprio 1
	s_barrier
	v_mfma_f32_16x16x32_bf16 v[34:37], v[62:65], v[18:21], v[66:69]
	v_mfma_f32_16x16x32_bf16 v[114:117], v[174:177], v[22:25], v[34:37]
	v_mfma_f32_16x16x32_bf16 v[34:37], v[198:201], v[18:21], v[70:73]
	v_mfma_f32_16x16x32_bf16 v[118:121], v[202:205], v[22:25], v[34:37]
	v_mfma_f32_16x16x32_bf16 v[34:37], v[62:65], v[110:113], v[74:77]
	v_mfma_f32_16x16x32_bf16 v[98:101], v[174:177], v[226:229], v[34:37]
	v_mfma_f32_16x16x32_bf16 v[34:37], v[198:201], v[110:113], v[78:81]
	v_mfma_f32_16x16x32_bf16 v[102:105], v[202:205], v[226:229], v[34:37]
	v_mfma_f32_16x16x32_bf16 v[34:37], v[62:65], v[230:233], v[82:85]
	v_mfma_f32_16x16x32_bf16 v[66:69], v[174:177], v[234:237], v[34:37]
	v_mfma_f32_16x16x32_bf16 v[34:37], v[198:201], v[230:233], v[86:89]
	v_mfma_f32_16x16x32_bf16 v[70:73], v[202:205], v[234:237], v[34:37]
	v_mfma_f32_16x16x32_bf16 v[34:37], v[62:65], v[238:241], v[90:93]
	v_mfma_f32_16x16x32_bf16 v[38:41], v[198:201], v[238:241], v[94:97]
	v_mfma_f32_16x16x32_bf16 v[34:37], v[174:177], v[242:245], v[34:37]
	v_mfma_f32_16x16x32_bf16 v[38:41], v[202:205], v[242:245], v[38:41]
	v_mfma_f32_16x16x32_bf16 v[74:77], v[206:209], v[18:21], v[210:213]
	v_mfma_f32_16x16x32_bf16 v[18:21], v[218:221], v[18:21], v[178:181]
	v_mfma_f32_16x16x32_bf16 v[126:129], v[222:225], v[22:25], v[18:21]
	v_mfma_f32_16x16x32_bf16 v[18:21], v[206:209], v[110:113], v[182:185]
	v_mfma_f32_16x16x32_bf16 v[106:109], v[214:217], v[226:229], v[18:21]
	v_mfma_f32_16x16x32_bf16 v[18:21], v[218:221], v[110:113], v[42:45]
	v_mfma_f32_16x16x32_bf16 v[110:113], v[222:225], v[226:229], v[18:21]
	v_mfma_f32_16x16x32_bf16 v[18:21], v[206:209], v[230:233], v[46:49]
	v_mfma_f32_16x16x32_bf16 v[122:125], v[214:217], v[22:25], v[74:77]
	v_mfma_f32_16x16x32_bf16 v[74:77], v[214:217], v[234:237], v[18:21]
	v_mfma_f32_16x16x32_bf16 v[18:21], v[218:221], v[230:233], v[50:53]
	v_mfma_f32_16x16x32_bf16 v[78:81], v[222:225], v[234:237], v[18:21]
	v_mfma_f32_16x16x32_bf16 v[18:21], v[206:209], v[238:241], v[54:57]
	v_mfma_f32_16x16x32_bf16 v[42:45], v[214:217], v[242:245], v[18:21]
	v_mfma_f32_16x16x32_bf16 v[18:21], v[218:221], v[238:241], v[58:61]
	v_mfma_f32_16x16x32_bf16 v[46:49], v[222:225], v[242:245], v[18:21]
	s_barrier
	s_setprio 0
	s_mov_b32 m0, s35
	s_nop 3
	v_lshl_add_u64 v[18:19], v[246:247], 0, s[8:9]
	s_add_u32 s22, s26, 0x10800
	ds_read_b128 v[58:61], v144 offset:49152
	ds_read_b128 v[94:97], v144 offset:50176
	ds_read_b128 v[178:181], v144 offset:51200
	ds_read_b128 v[182:185], v144 offset:52224
	ds_read_b128 v[210:213], v144 offset:53248
	ds_read_b128 v[226:229], v144 offset:54272
	ds_read_b128 v[230:233], v144 offset:55296
	ds_read_b128 v[234:237], v144 offset:56320
	global_load_lds_dwordx4 v[18:19], off
	v_lshl_add_u64 v[18:19], v[248:249], 0, s[8:9]
	s_mov_b32 m0, s34
	s_addc_u32 s23, s27, 0
	global_load_lds_dwordx4 v[18:19], off
	s_mov_b32 m0, s24
	v_lshl_add_u64 v[18:19], s[22:23], 0, v[130:131]
	global_load_lds_dwordx4 v[18:19], off
	s_mov_b32 m0, s25
	v_lshl_add_u64 v[18:19], s[22:23], 0, v[132:133]
	global_load_lds_dwordx4 v[18:19], off
	s_mov_b32 m0, s44
	v_lshl_add_u64 v[18:19], v[250:251], 0, s[8:9]
	global_load_lds_dwordx4 v[18:19], off
	s_mov_b32 m0, s45
	v_lshl_add_u64 v[18:19], v[252:253], 0, s[8:9]
	global_load_lds_dwordx4 v[18:19], off
	s_waitcnt vmcnt(8)
	s_waitcnt lgkmcnt(0)
	s_setprio 1
	s_barrier
	v_mfma_f32_16x16x32_bf16 v[18:21], v[62:65], v[58:61], v[146:149]
	v_mfma_f32_16x16x32_bf16 v[82:85], v[174:177], v[94:97], v[18:21]
	v_mfma_f32_16x16x32_bf16 v[18:21], v[198:201], v[58:61], v[150:153]
	v_mfma_f32_16x16x32_bf16 v[86:89], v[202:205], v[94:97], v[18:21]
	v_mfma_f32_16x16x32_bf16 v[18:21], v[62:65], v[178:181], v[154:157]
	v_mfma_f32_16x16x32_bf16 v[50:53], v[174:177], v[182:185], v[18:21]
	v_mfma_f32_16x16x32_bf16 v[18:21], v[198:201], v[178:181], v[158:161]
	v_mfma_f32_16x16x32_bf16 v[54:57], v[202:205], v[182:185], v[18:21]
	v_mfma_f32_16x16x32_bf16 v[18:21], v[62:65], v[210:213], v[162:165]
	v_mfma_f32_16x16x32_bf16 v[22:25], v[198:201], v[210:213], v[166:169]
	v_mfma_f32_16x16x32_bf16 v[2:5], v[62:65], v[230:233], v[2:5]
	v_mfma_f32_16x16x32_bf16 v[6:9], v[198:201], v[230:233], v[6:9]
	v_mfma_f32_16x16x32_bf16 v[18:21], v[174:177], v[226:229], v[18:21]
	v_mfma_f32_16x16x32_bf16 v[22:25], v[202:205], v[226:229], v[22:25]
	v_mfma_f32_16x16x32_bf16 v[2:5], v[174:177], v[234:237], v[2:5]
	v_mfma_f32_16x16x32_bf16 v[6:9], v[202:205], v[234:237], v[6:9]
	v_mfma_f32_16x16x32_bf16 v[10:13], v[206:209], v[58:61], v[10:13]
	v_mfma_f32_16x16x32_bf16 v[90:93], v[214:217], v[94:97], v[10:13]
	v_mfma_f32_16x16x32_bf16 v[10:13], v[218:221], v[58:61], v[14:17]
	v_mfma_f32_16x16x32_bf16 v[94:97], v[222:225], v[94:97], v[10:13]
	v_mfma_f32_16x16x32_bf16 v[10:13], v[206:209], v[178:181], v[26:29]
	v_mfma_f32_16x16x32_bf16 v[58:61], v[214:217], v[182:185], v[10:13]
	v_mfma_f32_16x16x32_bf16 v[10:13], v[218:221], v[178:181], v[30:33]
	v_mfma_f32_16x16x32_bf16 v[62:65], v[222:225], v[182:185], v[10:13]
	v_mfma_f32_16x16x32_bf16 v[10:13], v[206:209], v[210:213], v[186:189]
	v_mfma_f32_16x16x32_bf16 v[26:29], v[214:217], v[226:229], v[10:13]
	v_mfma_f32_16x16x32_bf16 v[10:13], v[218:221], v[210:213], v[190:193]
	v_mfma_f32_16x16x32_bf16 v[30:33], v[222:225], v[226:229], v[10:13]
	v_mfma_f32_16x16x32_bf16 v[10:13], v[206:209], v[230:233], v[194:197]
	v_mfma_f32_16x16x32_bf16 v[14:17], v[218:221], v[230:233], v[170:173]
	v_mfma_f32_16x16x32_bf16 v[10:13], v[214:217], v[234:237], v[10:13]
	v_mfma_f32_16x16x32_bf16 v[14:17], v[222:225], v[234:237], v[14:17]
	s_barrier
	s_setprio 0
	s_andn2_b64 vcc, exec, s[10:11]
	s_cbranch_vccnz .LBB0_208
	s_barrier

; #define PG8_STAGE(bufoff, gbase, voff) do { _Pragma("unroll") for (int _i = 0; _i < 2; ++_i) \
;         __builtin_amdgcn_global_load_lds((const unsigned*)((const char*)(gbase) + (voff)[_i]), (PG8_LAS unsigned*)(lds + (bufoff) + ldsw + _i * 8192), 16, 0, 0); } while (0)
; #define PG8_LDA(dst, b, h) do { _Pragma("unroll") for (int m = 0; m < 4; ++m) _Pragma("unroll") for (int k = 0; k < 2; ++k) dst[m][k] = *(const PG8_LAS bf16x8*)(lds + PG8_SA(b, h) + aoff + m * 2048 + k * 1024); } while (0)
; #define PG8_LDB(dst, b, h) do { _Pragma("unroll") for (int n = 0; n < 2; ++n) _Pragma("unroll") for (int k = 0; k < 2; ++k) dst[n][k] = *(const PG8_LAS bf16x8*)(lds + PG8_SB(b, h) + boff + n * 2048 + k * 1024); } while (0)
; #define PG8_MMA(ai, bj, At, Bt) do { __builtin_amdgcn_s_setprio(1); _Pragma("unroll") for (int m = 0; m < 4; ++m) _Pragma("unroll") for (int n = 0; n < 2; ++n) _Pragma("unroll") for (int k = 0; k < 2; ++k) \
;         acc[ai][bj][m][n] = __builtin_amdgcn_mfma_f32_16x16x32_bf16(Bt[n][k], At[m][k], acc[ai][bj][m][n], 0, 0, 0); __builtin_amdgcn_s_setprio(0); } while (0)
; #define PG8_WAIT_V(n) asm volatile("s_waitcnt vmcnt(" #n ")" ::: "memory")
; template <class Epi, class Sched, bool ALIGN_EPI, int LMASK = -1, int LMASKB = LMASK>
; __device__ __forceinline__ void gemm_phase(PG8_LAS unsigned char* lds, const Gemm g, const Sched& S, const Epi& E) {
;     ...
;         const char* nA = has_next ? (const char*)g.A + (size_t)(nxt.pm & LMASK) * tstepA : cA; const char* nB = has_next ? (const char*)g.Bt + (size_t)nxt.pm * g.b_pm_stride + (size_t)(nxt.pn & LMASKB) * tstepB : cB;
;         for (int t = 0; t < nt; t += 2) {
;             const bool last = (t == nt - 2);
;             const char* a1 = cA + (size_t)(t + 1) * kstepA;
;             const char* a2 = last ? nA : cA + (size_t)(t + 2) * kstepA; const char* b2 = last ? nB : cB + (size_t)(t + 2) * kstepB;
;             const char* a3 = a2 + kstepA; const char* b3 = b2 + kstepB;
;             PG8_LDB(B0, 0, 0); PG8_LDB(B1, 0, 1); PG8_SCHED; PG8_LDA(At, 0, 0); PG8_STAGE(PG8_SA(1, 1), a1 + hstepA, voffA);
;             PG8_WAIT_V(8); PG8_WAIT_L(0); PG8_BAR; PG8_MMA(0, 0, At, B0); PG8_MMA(0, 1, At, B1); PG8_BAR; PG8_SCHED;
;             PG8_LDA(At, 0, 1); PG8_STAGE(PG8_SB(0, 0), b2, voffB); PG8_STAGE(PG8_SB(0, 1), b2 + hstepB, voffB); PG8_STAGE(PG8_SA(0, 0), a2, voffA);
.LBB0_284:
	s_add_u32 s10, s8, 0xfff00800
	s_addc_u32 s11, s9, -1
	s_add_i32 s55, 0, 0x10000
	s_cmp_eq_u32 s54, 60
	s_cselect_b32 s37, s0, s11
	s_cselect_b32 s36, s1, s10
	s_cselect_b32 s11, s2, s29
	s_cselect_b32 s10, s7, s27
	s_add_i32 s58, 0, 0x14000
	v_add_u32_e32 v142, s55, v161
	v_add_u32_e32 v154, s58, v161
	ds_read_b128 v[130:133], v142
	ds_read_b128 v[134:137], v142 offset:1024
	ds_read_b128 v[138:141], v142 offset:2048
	ds_read_b128 v[142:145], v142 offset:3072
	ds_read_b128 v[172:175], v154
	ds_read_b128 v[188:191], v154 offset:1024
	ds_read_b128 v[218:221], v154 offset:2048
	ds_read_b128 v[222:225], v154 offset:3072
	v_lshl_add_u64 v[154:155], s[8:9], 0, v[150:151]
	s_add_i32 m0, s45, 0xc000
	ds_read_b128 v[226:229], v171
	ds_read_b128 v[230:233], v171 offset:1024
	ds_read_b128 v[234:237], v171 offset:2048
	ds_read_b128 v[238:241], v171 offset:3072
	ds_read_b128 v[242:245], v171 offset:4096
	ds_read_b128 v[246:249], v171 offset:5120
	ds_read_b128 v[250:253], v171 offset:6144
	ds_read_b128 v[206:209], v171 offset:7168
	global_load_lds_dwordx4 v[154:155], off
	s_add_i32 m0, s45, 0xe000
	v_lshl_add_u64 v[154:155], s[8:9], 0, v[152:153]
	global_load_lds_dwordx4 v[154:155], off
	s_waitcnt vmcnt(8)
	s_waitcnt lgkmcnt(0)
	s_setprio 1
	s_barrier
	v_mfma_f32_16x16x32_bf16 v[126:129], v[130:133], v[226:229], v[126:129]
	v_mfma_f32_16x16x32_bf16 v[122:125], v[138:141], v[226:229], v[122:125]
	v_mfma_f32_16x16x32_bf16 v[118:121], v[130:133], v[234:237], v[118:121]
	v_mfma_f32_16x16x32_bf16 v[110:113], v[138:141], v[234:237], v[110:113]
	v_mfma_f32_16x16x32_bf16 v[102:105], v[130:133], v[242:245], v[102:105]
	v_mfma_f32_16x16x32_bf16 v[94:97], v[138:141], v[242:245], v[94:97]
	v_mfma_f32_16x16x32_bf16 v[86:89], v[130:133], v[250:253], v[86:89]
	v_mfma_f32_16x16x32_bf16 v[78:81], v[138:141], v[250:253], v[78:81]
	v_mfma_f32_16x16x32_bf16 v[126:129], v[134:137], v[230:233], v[126:129]
	v_mfma_f32_16x16x32_bf16 v[122:125], v[142:145], v[230:233], v[122:125]
	v_mfma_f32_16x16x32_bf16 v[118:121], v[134:137], v[238:241], v[118:121]
	v_mfma_f32_16x16x32_bf16 v[110:113], v[142:145], v[238:241], v[110:113]
	v_mfma_f32_16x16x32_bf16 v[102:105], v[134:137], v[246:249], v[102:105]
	v_mfma_f32_16x16x32_bf16 v[94:97], v[142:145], v[246:249], v[94:97]
	v_mfma_f32_16x16x32_bf16 v[86:89], v[134:137], v[206:209], v[86:89]
	v_mfma_f32_16x16x32_bf16 v[78:81], v[142:145], v[206:209], v[78:81]
	v_mfma_f32_16x16x32_bf16 v[114:117], v[172:175], v[226:229], v[114:117]
	v_mfma_f32_16x16x32_bf16 v[106:109], v[218:221], v[226:229], v[106:109]
	v_mfma_f32_16x16x32_bf16 v[98:101], v[172:175], v[234:237], v[98:101]
	v_mfma_f32_16x16x32_bf16 v[90:93], v[218:221], v[234:237], v[90:93]
	v_mfma_f32_16x16x32_bf16 v[82:85], v[172:175], v[242:245], v[82:85]
	v_mfma_f32_16x16x32_bf16 v[74:77], v[218:221], v[242:245], v[74:77]
	v_mfma_f32_16x16x32_bf16 v[70:73], v[172:175], v[250:253], v[70:73]
	v_mfma_f32_16x16x32_bf16 v[66:69], v[218:221], v[250:253], v[66:69]
	v_mfma_f32_16x16x32_bf16 v[114:117], v[188:191], v[230:233], v[114:117]
	v_mfma_f32_16x16x32_bf16 v[106:109], v[222:225], v[230:233], v[106:109]
	v_mfma_f32_16x16x32_bf16 v[98:101], v[188:191], v[238:241], v[98:101]
	v_mfma_f32_16x16x32_bf16 v[90:93], v[222:225], v[238:241], v[90:93]
	v_mfma_f32_16x16x32_bf16 v[82:85], v[188:191], v[246:249], v[82:85]
	v_mfma_f32_16x16x32_bf16 v[74:77], v[222:225], v[246:249], v[74:77]
	v_mfma_f32_16x16x32_bf16 v[70:73], v[188:191], v[206:209], v[70:73]
	v_mfma_f32_16x16x32_bf16 v[66:69], v[222:225], v[206:209], v[66:69]
	s_barrier
	s_setprio 0
	s_add_i32 s55, s55, s43
	v_lshl_add_u64 v[154:155], s[10:11], 0, v[148:149]
	s_mov_b32 m0, s55
	ds_read_b128 v[206:209], v171 offset:16384
	ds_read_b128 v[226:229], v171 offset:17408
	ds_read_b128 v[230:233], v171 offset:18432
	ds_read_b128 v[234:237], v171 offset:19456
	ds_read_b128 v[238:241], v171 offset:20480
	ds_read_b128 v[242:245], v171 offset:21504
	ds_read_b128 v[246:249], v171 offset:22528
	ds_read_b128 v[250:253], v171 offset:23552
	global_load_lds_dwordx4 v[154:155], off
	s_add_i32 m0, s55, 0x2000
	s_add_u32 s56, s10, 0x100000
	v_lshl_add_u64 v[176:177], s[10:11], 0, v[146:147]
	s_addc_u32 s57, s11, 0
	s_add_i32 s55, s58, s43
	global_load_lds_dwordx4 v[176:177], off
	v_lshl_add_u64 v[194:195], s[56:57], 0, v[148:149]
	s_mov_b32 m0, s55
	v_lshl_add_u64 v[210:211], s[36:37], 0, v[146:147]
	global_load_lds_dwordx4 v[194:195], off
	s_add_i32 m0, s55, 0x2000
	v_lshl_add_u64 v[194:195], s[56:57], 0, v[146:147]
	global_load_lds_dwordx4 v[194:195], off
	s_mov_b32 m0, s45
	v_lshl_add_u64 v[194:195], s[36:37], 0, v[148:149]
	global_load_lds_dwordx4 v[194:195], off
	s_mov_b32 m0, s46
	s_nop 0
	global_load_lds_dwordx4 v[210:211], off
	s_waitcnt vmcnt(8)
	s_waitcnt lgkmcnt(0)
	s_setprio 1
	s_barrier
; #define PG8_STAGE(bufoff, gbase, voff) do { _Pragma("unroll") for (int _i = 0; _i < 2; ++_i) \
;         __builtin_amdgcn_global_load_lds((const unsigned*)((const char*)(gbase) + (voff)[_i]), (PG8_LAS unsigned*)(lds + (bufoff) + ldsw + _i * 8192), 16, 0, 0); } while (0)
; #define PG8_LDA(dst, b, h) do { _Pragma("unroll") for (int m = 0; m < 4; ++m) _Pragma("unroll") for (int k = 0; k < 2; ++k) dst[m][k] = *(const PG8_LAS bf16x8*)(lds + PG8_SA(b, h) + aoff + m * 2048 + k * 1024); } while (0)
; #define PG8_LDB(dst, b, h) do { _Pragma("unroll") for (int n = 0; n < 2; ++n) _Pragma("unroll") for (int k = 0; k < 2; ++k) dst[n][k] = *(const PG8_LAS bf16x8*)(lds + PG8_SB(b, h) + boff + n * 2048 + k * 1024); } while (0)
; #define PG8_MMA(ai, bj, At, Bt) do { __builtin_amdgcn_s_setprio(1); _Pragma("unroll") for (int m = 0; m < 4; ++m) _Pragma("unroll") for (int n = 0; n < 2; ++n) _Pragma("unroll") for (int k = 0; k < 2; ++k) \
;         acc[ai][bj][m][n] = __builtin_amdgcn_mfma_f32_16x16x32_bf16(Bt[n][k], At[m][k], acc[ai][bj][m][n], 0, 0, 0); __builtin_amdgcn_s_setprio(0); } while (0)
; #define PG8_WAIT_V(n) asm volatile("s_waitcnt vmcnt(" #n ")" ::: "memory")
; #define PG8_WAIT_L(n) asm volatile("s_waitcnt lgkmcnt(" #n ")" ::: "memory")
; #define PG8_BAR __builtin_amdgcn_s_barrier()
; #define PG8_SCHED __builtin_amdgcn_sched_barrier(0)
; template <class Epi, class Sched, bool ALIGN_EPI, int LMASK = -1, int LMASKB = LMASK>
; __device__ __forceinline__ void gemm_phase(PG8_LAS unsigned char* lds, const Gemm g, const Sched& S, const Epi& E) {
;     ...
;             PG8_WAIT_V(8); PG8_WAIT_L(0); PG8_BAR; PG8_MMA(0, 0, At, B0); PG8_MMA(0, 1, At, B1); PG8_BAR; PG8_SCHED;
;             PG8_LDA(At, 0, 1); PG8_STAGE(PG8_SB(0, 0), b2, voffB); PG8_STAGE(PG8_SB(0, 1), b2 + hstepB, voffB); PG8_STAGE(PG8_SA(0, 0), a2, voffA);
;             PG8_WAIT_V(8); PG8_WAIT_L(0); PG8_BAR; PG8_MMA(1, 0, At, B0); PG8_MMA(1, 1, At, B1); PG8_BAR; PG8_SCHED;
;             PG8_LDB(B0, 1, 0); PG8_LDB(B1, 1, 1); PG8_SCHED; PG8_LDA(At, 1, 0); PG8_STAGE(PG8_SA(0, 1), a2 + hstepA, voffA);
;             PG8_WAIT_V(8); PG8_WAIT_L(0); PG8_BAR; PG8_MMA(0, 0, At, B0); PG8_MMA(0, 1, At, B1); PG8_BAR; PG8_SCHED;
	v_mfma_f32_16x16x32_bf16 v[62:65], v[130:133], v[206:209], v[62:65]
	v_mfma_f32_16x16x32_bf16 v[58:61], v[138:141], v[206:209], v[58:61]
	v_mfma_f32_16x16x32_bf16 v[54:57], v[130:133], v[230:233], v[54:57]
	v_mfma_f32_16x16x32_bf16 v[46:49], v[138:141], v[230:233], v[46:49]
	v_mfma_f32_16x16x32_bf16 v[38:41], v[130:133], v[238:241], v[38:41]
	v_mfma_f32_16x16x32_bf16 v[30:33], v[138:141], v[238:241], v[30:33]
	v_mfma_f32_16x16x32_bf16 v[22:25], v[130:133], v[246:249], v[22:25]
	v_mfma_f32_16x16x32_bf16 v[14:17], v[138:141], v[246:249], v[14:17]
	v_mfma_f32_16x16x32_bf16 v[62:65], v[134:137], v[226:229], v[62:65]
	v_mfma_f32_16x16x32_bf16 v[58:61], v[142:145], v[226:229], v[58:61]
	v_mfma_f32_16x16x32_bf16 v[54:57], v[134:137], v[234:237], v[54:57]
	v_mfma_f32_16x16x32_bf16 v[46:49], v[142:145], v[234:237], v[46:49]
	v_mfma_f32_16x16x32_bf16 v[38:41], v[134:137], v[242:245], v[38:41]
	v_mfma_f32_16x16x32_bf16 v[30:33], v[142:145], v[242:245], v[30:33]
	v_mfma_f32_16x16x32_bf16 v[22:25], v[134:137], v[250:253], v[22:25]
	v_mfma_f32_16x16x32_bf16 v[14:17], v[142:145], v[250:253], v[14:17]
	v_mfma_f32_16x16x32_bf16 v[50:53], v[172:175], v[206:209], v[50:53]
	v_mfma_f32_16x16x32_bf16 v[42:45], v[218:221], v[206:209], v[42:45]
	v_mfma_f32_16x16x32_bf16 v[34:37], v[172:175], v[230:233], v[34:37]
	v_mfma_f32_16x16x32_bf16 v[26:29], v[218:221], v[230:233], v[26:29]
	v_mfma_f32_16x16x32_bf16 v[18:21], v[172:175], v[238:241], v[18:21]
	v_mfma_f32_16x16x32_bf16 v[10:13], v[218:221], v[238:241], v[10:13]
	v_mfma_f32_16x16x32_bf16 v[6:9], v[172:175], v[246:249], v[6:9]
	v_mfma_f32_16x16x32_bf16 v[2:5], v[218:221], v[246:249], v[2:5]
	v_mfma_f32_16x16x32_bf16 v[50:53], v[188:191], v[226:229], v[50:53]
	v_mfma_f32_16x16x32_bf16 v[42:45], v[222:225], v[226:229], v[42:45]
	v_mfma_f32_16x16x32_bf16 v[34:37], v[188:191], v[234:237], v[34:37]
	v_mfma_f32_16x16x32_bf16 v[26:29], v[222:225], v[234:237], v[26:29]
	v_mfma_f32_16x16x32_bf16 v[18:21], v[188:191], v[242:245], v[18:21]
	v_mfma_f32_16x16x32_bf16 v[10:13], v[222:225], v[242:245], v[10:13]
	v_mfma_f32_16x16x32_bf16 v[6:9], v[188:191], v[250:253], v[6:9]
	v_mfma_f32_16x16x32_bf16 v[2:5], v[222:225], v[250:253], v[2:5]
	s_barrier
	s_setprio 0
	s_add_i32 s55, 0, 0x18000
	s_add_i32 s56, 0, 0x1c000
	v_add_u32_e32 v142, s55, v161
	v_add_u32_e32 v156, s56, v161
	ds_read_b128 v[130:133], v142
	ds_read_b128 v[134:137], v142 offset:1024
	ds_read_b128 v[138:141], v142 offset:2048
	ds_read_b128 v[142:145], v142 offset:3072
	ds_read_b128 v[172:175], v156
	ds_read_b128 v[188:191], v156 offset:1024
	ds_read_b128 v[206:209], v156 offset:2048
	ds_read_b128 v[218:221], v156 offset:3072
	s_add_u32 s36, s36, 0x100000
	s_addc_u32 s37, s37, 0
	s_mov_b32 m0, s47
	v_lshl_add_u64 v[212:213], s[36:37], 0, v[148:149]
	ds_read_b128 v[222:225], v171 offset:32768
	ds_read_b128 v[226:229], v171 offset:33792
	ds_read_b128 v[230:233], v171 offset:34816
	ds_read_b128 v[234:237], v171 offset:35840
	ds_read_b128 v[238:241], v171 offset:36864
	ds_read_b128 v[242:245], v171 offset:37888
	ds_read_b128 v[246:249], v171 offset:38912
	ds_read_b128 v[250:253], v171 offset:39936
	global_load_lds_dwordx4 v[212:213], off
	s_mov_b32 m0, s48
	v_lshl_add_u64 v[212:213], s[36:37], 0, v[146:147]
	global_load_lds_dwordx4 v[212:213], off
	s_waitcnt vmcnt(8)
	s_waitcnt lgkmcnt(0)
	s_setprio 1
	s_barrier
	v_mfma_f32_16x16x32_bf16 v[126:129], v[130:133], v[222:225], v[126:129]
	v_mfma_f32_16x16x32_bf16 v[122:125], v[138:141], v[222:225], v[122:125]
	v_mfma_f32_16x16x32_bf16 v[118:121], v[130:133], v[230:233], v[118:121]
	v_mfma_f32_16x16x32_bf16 v[110:113], v[138:141], v[230:233], v[110:113]
	v_mfma_f32_16x16x32_bf16 v[102:105], v[130:133], v[238:241], v[102:105]
	v_mfma_f32_16x16x32_bf16 v[94:97], v[138:141], v[238:241], v[94:97]
	v_mfma_f32_16x16x32_bf16 v[86:89], v[130:133], v[246:249], v[86:89]
	v_mfma_f32_16x16x32_bf16 v[78:81], v[138:141], v[246:249], v[78:81]
	v_mfma_f32_16x16x32_bf16 v[126:129], v[134:137], v[226:229], v[126:129]
	v_mfma_f32_16x16x32_bf16 v[122:125], v[142:145], v[226:229], v[122:125]
	v_mfma_f32_16x16x32_bf16 v[118:121], v[134:137], v[234:237], v[118:121]
	v_mfma_f32_16x16x32_bf16 v[110:113], v[142:145], v[234:237], v[110:113]
	v_mfma_f32_16x16x32_bf16 v[102:105], v[134:137], v[242:245], v[102:105]
	v_mfma_f32_16x16x32_bf16 v[94:97], v[142:145], v[242:245], v[94:97]
	v_mfma_f32_16x16x32_bf16 v[86:89], v[134:137], v[250:253], v[86:89]
	v_mfma_f32_16x16x32_bf16 v[78:81], v[142:145], v[250:253], v[78:81]
	v_mfma_f32_16x16x32_bf16 v[114:117], v[172:175], v[222:225], v[114:117]
	v_mfma_f32_16x16x32_bf16 v[106:109], v[206:209], v[222:225], v[106:109]
	v_mfma_f32_16x16x32_bf16 v[98:101], v[172:175], v[230:233], v[98:101]
	v_mfma_f32_16x16x32_bf16 v[90:93], v[206:209], v[230:233], v[90:93]
	v_mfma_f32_16x16x32_bf16 v[82:85], v[172:175], v[238:241], v[82:85]
	v_mfma_f32_16x16x32_bf16 v[74:77], v[206:209], v[238:241], v[74:77]
	v_mfma_f32_16x16x32_bf16 v[70:73], v[172:175], v[246:249], v[70:73]
	v_mfma_f32_16x16x32_bf16 v[66:69], v[206:209], v[246:249], v[66:69]
	v_mfma_f32_16x16x32_bf16 v[114:117], v[188:191], v[226:229], v[114:117]
	v_mfma_f32_16x16x32_bf16 v[106:109], v[218:221], v[226:229], v[106:109]
	v_mfma_f32_16x16x32_bf16 v[98:101], v[188:191], v[234:237], v[98:101]
	v_mfma_f32_16x16x32_bf16 v[90:93], v[218:221], v[234:237], v[90:93]
	v_mfma_f32_16x16x32_bf16 v[82:85], v[188:191], v[242:245], v[82:85]
	v_mfma_f32_16x16x32_bf16 v[74:77], v[218:221], v[242:245], v[74:77]
	v_mfma_f32_16x16x32_bf16 v[70:73], v[188:191], v[250:253], v[70:73]
	v_mfma_f32_16x16x32_bf16 v[66:69], v[218:221], v[250:253], v[66:69]
	s_barrier
; #define PG8_STAGE(bufoff, gbase, voff) do { _Pragma("unroll") for (int _i = 0; _i < 2; ++_i) \
;         __builtin_amdgcn_global_load_lds((const unsigned*)((const char*)(gbase) + (voff)[_i]), (PG8_LAS unsigned*)(lds + (bufoff) + ldsw + _i * 8192), 16, 0, 0); } while (0)
; #define PG8_LDA(dst, b, h) do { _Pragma("unroll") for (int m = 0; m < 4; ++m) _Pragma("unroll") for (int k = 0; k < 2; ++k) dst[m][k] = *(const PG8_LAS bf16x8*)(lds + PG8_SA(b, h) + aoff + m * 2048 + k * 1024); } while (0)
; #define PG8_MMA(ai, bj, At, Bt) do { __builtin_amdgcn_s_setprio(1); _Pragma("unroll") for (int m = 0; m < 4; ++m) _Pragma("unroll") for (int n = 0; n < 2; ++n) _Pragma("unroll") for (int k = 0; k < 2; ++k) \
;         acc[ai][bj][m][n] = __builtin_amdgcn_mfma_f32_16x16x32_bf16(Bt[n][k], At[m][k], acc[ai][bj][m][n], 0, 0, 0); __builtin_amdgcn_s_setprio(0); } while (0)
; #define PG8_WAIT_V(n) asm volatile("s_waitcnt vmcnt(" #n ")" ::: "memory")
; #define PG8_WAIT_L(n) asm volatile("s_waitcnt lgkmcnt(" #n ")" ::: "memory")
; #define PG8_BAR __builtin_amdgcn_s_barrier()
; #define PG8_SCHED __builtin_amdgcn_sched_barrier(0)
; template <class Epi, class Sched, bool ALIGN_EPI, int LMASK = -1, int LMASKB = LMASK>
; __device__ __forceinline__ void gemm_phase(PG8_LAS unsigned char* lds, const Gemm g, const Sched& S, const Epi& E) {
;     ...
;             PG8_LDA(At, 1, 1); PG8_STAGE(PG8_SB(1, 0), b3, voffB); PG8_STAGE(PG8_SB(1, 1), b3 + hstepB, voffB); PG8_STAGE(PG8_SA(1, 0), a3, voffA);
;             PG8_WAIT_V(8); PG8_WAIT_L(0); PG8_BAR; PG8_MMA(1, 0, At, B0); PG8_MMA(1, 1, At, B1); PG8_BAR; PG8_SCHED;
;         }
	s_setprio 0
	s_add_i32 s36, s55, s43
	v_lshl_add_u64 v[154:155], v[154:155], 0, s[80:81]
	s_mov_b32 m0, s36
	ds_read_b128 v[222:225], v171 offset:49152
	ds_read_b128 v[226:229], v171 offset:50176
	ds_read_b128 v[230:233], v171 offset:51200
	ds_read_b128 v[234:237], v171 offset:52224
	ds_read_b128 v[238:241], v171 offset:53248
	ds_read_b128 v[242:245], v171 offset:54272
	ds_read_b128 v[246:249], v171 offset:55296
	ds_read_b128 v[250:253], v171 offset:56320
	global_load_lds_dwordx4 v[154:155], off
	s_add_i32 m0, s36, 0x2000
	s_add_u32 s10, s10, 0x100800
	v_lshl_add_u64 v[154:155], v[176:177], 0, s[80:81]
	s_addc_u32 s11, s11, 0
	s_add_i32 s36, s56, s43
	global_load_lds_dwordx4 v[154:155], off
	s_mov_b32 m0, s36
	v_lshl_add_u64 v[154:155], s[10:11], 0, v[148:149]
	global_load_lds_dwordx4 v[154:155], off
	s_add_i32 m0, s36, 0x2000
	v_lshl_add_u64 v[154:155], s[10:11], 0, v[146:147]
	global_load_lds_dwordx4 v[154:155], off
	s_mov_b32 m0, s49
	v_lshl_add_u64 v[154:155], v[194:195], 0, s[80:81]
	global_load_lds_dwordx4 v[154:155], off
	s_mov_b32 m0, s50
	v_lshl_add_u64 v[154:155], v[210:211], 0, s[80:81]
	global_load_lds_dwordx4 v[154:155], off
	s_waitcnt vmcnt(8)
	s_waitcnt lgkmcnt(0)
	s_setprio 1
	s_barrier
	v_mfma_f32_16x16x32_bf16 v[62:65], v[130:133], v[222:225], v[62:65]
	v_mfma_f32_16x16x32_bf16 v[58:61], v[138:141], v[222:225], v[58:61]
	v_mfma_f32_16x16x32_bf16 v[54:57], v[130:133], v[230:233], v[54:57]
	v_mfma_f32_16x16x32_bf16 v[46:49], v[138:141], v[230:233], v[46:49]
	v_mfma_f32_16x16x32_bf16 v[38:41], v[130:133], v[238:241], v[38:41]
	v_mfma_f32_16x16x32_bf16 v[30:33], v[138:141], v[238:241], v[30:33]
	v_mfma_f32_16x16x32_bf16 v[22:25], v[130:133], v[246:249], v[22:25]
	v_mfma_f32_16x16x32_bf16 v[14:17], v[138:141], v[246:249], v[14:17]
	v_mfma_f32_16x16x32_bf16 v[62:65], v[134:137], v[226:229], v[62:65]
	v_mfma_f32_16x16x32_bf16 v[58:61], v[142:145], v[226:229], v[58:61]
	v_mfma_f32_16x16x32_bf16 v[54:57], v[134:137], v[234:237], v[54:57]
	v_mfma_f32_16x16x32_bf16 v[46:49], v[142:145], v[234:237], v[46:49]
	v_mfma_f32_16x16x32_bf16 v[38:41], v[134:137], v[242:245], v[38:41]
	v_mfma_f32_16x16x32_bf16 v[30:33], v[142:145], v[242:245], v[30:33]
	v_mfma_f32_16x16x32_bf16 v[22:25], v[134:137], v[250:253], v[22:25]
	v_mfma_f32_16x16x32_bf16 v[14:17], v[142:145], v[250:253], v[14:17]
	v_mfma_f32_16x16x32_bf16 v[50:53], v[172:175], v[222:225], v[50:53]
	v_mfma_f32_16x16x32_bf16 v[42:45], v[206:209], v[222:225], v[42:45]
	v_mfma_f32_16x16x32_bf16 v[34:37], v[172:175], v[230:233], v[34:37]
	v_mfma_f32_16x16x32_bf16 v[26:29], v[206:209], v[230:233], v[26:29]
	v_mfma_f32_16x16x32_bf16 v[18:21], v[172:175], v[238:241], v[18:21]
	v_mfma_f32_16x16x32_bf16 v[10:13], v[206:209], v[238:241], v[10:13]
	v_mfma_f32_16x16x32_bf16 v[6:9], v[172:175], v[246:249], v[6:9]
	v_mfma_f32_16x16x32_bf16 v[2:5], v[206:209], v[246:249], v[2:5]
	v_mfma_f32_16x16x32_bf16 v[50:53], v[188:191], v[226:229], v[50:53]
	v_mfma_f32_16x16x32_bf16 v[42:45], v[218:221], v[226:229], v[42:45]
	v_mfma_f32_16x16x32_bf16 v[34:37], v[188:191], v[234:237], v[34:37]
	v_mfma_f32_16x16x32_bf16 v[26:29], v[218:221], v[234:237], v[26:29]
	v_mfma_f32_16x16x32_bf16 v[18:21], v[188:191], v[242:245], v[18:21]
	v_mfma_f32_16x16x32_bf16 v[10:13], v[218:221], v[242:245], v[10:13]
	v_mfma_f32_16x16x32_bf16 v[6:9], v[188:191], v[250:253], v[6:9]
	v_mfma_f32_16x16x32_bf16 v[2:5], v[218:221], v[250:253], v[2:5]
	s_barrier
	s_setprio 0
	s_add_i32 s54, s54, 2
	s_add_u32 s8, s8, 0x1000
	s_addc_u32 s9, s9, 0
	s_add_u32 s27, s27, 0x1000
	s_addc_u32 s29, s29, 0
	s_cmp_gt_u32 s54, 61
	s_cbranch_scc0 .LBB0_284
	s_and_b64 vcc, exec, s[22:23]
	s_cbranch_vccz .LBB0_287
	s_barrier

; #define LAS __attribute__((address_space(3)))
; __device__ __forceinline__ void dil_tile(const bf16* __restrict__ P, bf16* MIX, float* LSE, int T, LAS char* vimg, int lane) {
;     ...
;     const int r32 = lane & 31, hi = lane >> 5;
;     const int bh = T >> 7, within = T & 127, b = bh / 9, head = bh - 9 * b, gi = head / 3, dsh = 2 * gi;
;     const int L32 = 128 >> dsh, r = within >> (7 - dsh), i0 = (within & (L32 - 1)) << 5, j0 = i0 - 128;
;     const size_t row0 = (size_t)b * SEQ + r;
;     bf16x8 qf[8];
;     { const bf16* qp = P + (row0 + ((size_t)(i0 + r32) << dsh)) * LDP + C_QB + head * 128 + 8 * hi;
; #pragma unroll
;       for (int s = 0; s < 8; ++s) qf[s] = *(const bf16x8*)(qp + 16 * s); }
;     f32x16 S[5];
; #pragma unroll
;     for (int kt = 0; kt < 5; ++kt) {
;         int ln = lane; asm volatile("" : "+v"(ln));
; #pragma unroll
;         for (int it = 0; it < 8; ++it) { const int rr = (ln >> 4) + 4 * it, c16 = ln & 15; const int key = j0 + 32 * kt + rr, kc = key < 0 ? 0 : key;
;             __builtin_amdgcn_global_load_lds((const unsigned*)(P + (row0 + ((size_t)kc << dsh)) * LDP + C_KB + head * 128 + 8 * (c16 ^ (rr & 15))), (LAS unsigned*)(vimg + it * 1024), 16, 0, 0); }
.LBB0_400:
	s_ashr_i32 s5, s0, 7
	s_mul_hi_i32 s4, s5, 0x38e38e39
	s_lshr_b32 s13, s4, 31
	s_ashr_i32 s4, s4, 1
	s_add_i32 s4, s4, s13
	s_mul_i32 s13, s4, -9
	s_add_i32 s18, s13, s5
	s_mul_hi_i32 s5, s18, 0x55555556
	s_lshr_b32 s13, s5, 31
	s_add_i32 s5, s5, s13
	s_lshl_b32 s24, s5, 1
	s_lshr_b32 s5, 0x80, s24
	s_and_b32 s12, s0, 0x7f
	s_add_i32 s5, s5, -1
	v_mov_b32_e32 v151, v148
	s_and_b32 s5, s5, s12
	s_sub_i32 s13, 7, s24
	v_and_b32_e32 v150, 31, v151
	s_lshl_b32 s25, s5, 5
	s_ashr_i32 s5, s4, 31
	s_lshr_b32 s14, s12, s13
	s_lshl_b64 s[12:13], s[4:5], 12
	v_or_b32_e32 v178, s25, v150
	s_or_b32 s12, s12, s14
	v_lshlrev_b64 v[2:3], s24, v[178:179]
	v_lshl_add_u64 v[110:111], v[2:3], 0, s[12:13]
	v_mov_b64_e32 v[70:71], s[6:7]
	v_mad_u64_u32 v[2:3], s[4:5], v110, s33, v[70:71]
	v_mov_b32_e32 v4, v3
	s_lshl_b32 s14, s18, 7
	v_ashrrev_i32_e32 v149, 5, v151
	v_mad_u64_u32 v[4:5], s[4:5], v111, s33, v[4:5]
	s_ashr_i32 s15, s14, 31
	v_mov_b32_e32 v3, v4
	s_lshl_b64 s[16:17], s[14:15], 1
	v_lshlrev_b32_e32 v4, 3, v149
	v_lshl_add_u64 v[2:3], v[2:3], 0, s[16:17]
	v_ashrrev_i32_e32 v5, 31, v4
	v_lshl_add_u64 v[2:3], v[4:5], 1, v[2:3]
	s_mov_b64 s[4:5], 0x1800
	v_lshl_add_u64 v[4:5], v[2:3], 0, s[4:5]
	s_movk_i32 s4, 0x1000
	v_add_co_u32_e32 v2, vcc, s4, v2
	v_mov_b32_e32 v8, v151
	s_nop 0
	v_addc_co_u32_e32 v3, vcc, 0, v3, vcc
	global_load_dwordx4 v[106:109], v[4:5], off offset:32
	global_load_dwordx4 v[102:105], v[4:5], off offset:64
	global_load_dwordx4 v[98:101], v[4:5], off offset:96
	global_load_dwordx4 v[94:97], v[4:5], off offset:128
	global_load_dwordx4 v[90:93], v[4:5], off offset:160
	global_load_dwordx4 v[86:89], v[4:5], off offset:192
	global_load_dwordx4 v[66:69], v[2:3], off offset:2048
	global_load_dwordx4 v[82:85], v[4:5], off offset:224
	s_add_i32 s28, s25, 0xffffff80
	v_mov_b32_e32 v3, v179
	v_ashrrev_i32_e32 v9, 4, v8
	v_add_u32_e32 v10, s28, v9
	v_max_i32_e32 v2, 0, v10
	v_lshlrev_b64 v[2:3], s24, v[2:3]
	v_lshl_add_u64 v[2:3], v[2:3], 0, s[12:13]
	v_mad_u64_u32 v[4:5], s[4:5], v2, s33, v[70:71]
	v_mov_b32_e32 v2, v5
	v_mad_u64_u32 v[2:3], s[4:5], v3, s33, v[2:3]
	v_mov_b32_e32 v5, v2
	v_lshl_add_u64 v[2:3], v[4:5], 0, s[16:17]
	v_xor_b32_e32 v4, v9, v8
	v_lshlrev_b32_e32 v4, 4, v4
	v_and_b32_e32 v4, 0xf0, v4
	v_mov_b32_e32 v5, v179
	v_lshl_add_u64 v[2:3], v[2:3], 0, v[4:5]
	s_mov_b32 m0, s2
	v_lshl_add_u64 v[2:3], v[2:3], 0, s[82:83]
	v_add_u32_e32 v11, 4, v9
	global_load_lds_dwordx4 v[2:3], off
	v_add_u32_e32 v2, s28, v11
	v_max_i32_e32 v2, 0, v2
	v_mov_b32_e32 v3, v179
	v_lshlrev_b64 v[2:3], s24, v[2:3]
	v_lshl_add_u64 v[2:3], v[2:3], 0, s[12:13]
	v_mad_u64_u32 v[6:7], s[4:5], v2, s33, v[70:71]
	v_mov_b32_e32 v2, v7
	v_mad_u64_u32 v[2:3], s[4:5], v3, s33, v[2:3]
	v_mov_b32_e32 v7, v2
	v_lshl_add_u64 v[2:3], v[6:7], 0, s[16:17]
	v_xor_b32_e32 v6, v11, v8
	v_lshlrev_b32_e32 v6, 4, v6
	v_and_b32_e32 v6, 0xf0, v6
	v_mov_b32_e32 v7, v179
	v_lshl_add_u64 v[2:3], v[2:3], 0, v[6:7]
	s_add_i32 s4, s2, 0x400
	v_lshl_add_u64 v[2:3], v[2:3], 0, s[82:83]
	s_mov_b32 m0, s4
	v_add_u32_e32 v11, 8, v9
	global_load_lds_dwordx4 v[2:3], off
	v_add_u32_e32 v2, s28, v11
	v_max_i32_e32 v2, 0, v2
	v_mov_b32_e32 v3, v179
	v_lshlrev_b64 v[2:3], s24, v[2:3]
	v_lshl_add_u64 v[2:3], v[2:3], 0, s[12:13]
	v_mad_u64_u32 v[6:7], s[26:27], v2, s33, v[70:71]
	v_mov_b32_e32 v2, v7
	v_mad_u64_u32 v[2:3], s[26:27], v3, s33, v[2:3]
	v_mov_b32_e32 v7, v2
	v_lshl_add_u64 v[2:3], v[6:7], 0, s[16:17]
	v_xor_b32_e32 v6, v11, v8
	v_lshlrev_b32_e32 v6, 4, v6
	v_and_b32_e32 v6, 0xf0, v6
	v_mov_b32_e32 v7, v179
	v_lshl_add_u64 v[2:3], v[2:3], 0, v[6:7]
	v_lshl_add_u64 v[2:3], v[2:3], 0, s[82:83]
	s_mov_b32 m0, s3
	v_add_u32_e32 v11, 12, v9
	global_load_lds_dwordx4 v[2:3], off
	v_add_u32_e32 v2, s28, v11
	v_max_i32_e32 v2, 0, v2
	v_mov_b32_e32 v3, v179
	v_lshlrev_b64 v[2:3], s24, v[2:3]
	v_lshl_add_u64 v[2:3], v[2:3], 0, s[12:13]
	v_mad_u64_u32 v[6:7], s[26:27], v2, s33, v[70:71]
	v_mov_b32_e32 v2, v7
	v_mad_u64_u32 v[2:3], s[26:27], v3, s33, v[2:3]
	v_mov_b32_e32 v7, v2
	v_lshl_add_u64 v[2:3], v[6:7], 0, s[16:17]
	v_xor_b32_e32 v6, v11, v8
	v_lshlrev_b32_e32 v6, 4, v6
	v_and_b32_e32 v6, 0xf0, v6
	v_mov_b32_e32 v7, v179
	v_lshl_add_u64 v[2:3], v[2:3], 0, v[6:7]
	v_lshl_add_u64 v[2:3], v[2:3], 0, s[82:83]
	s_mov_b32 m0, s20
	s_add_i32 s5, s2, 0x1000
	global_load_lds_dwordx4 v[2:3], off
	v_max_i32_e32 v2, -16, v10
	v_add_u32_e32 v2, 16, v2
	v_mov_b32_e32 v3, v179
	v_lshlrev_b64 v[2:3], s24, v[2:3]
	v_lshl_add_u64 v[2:3], v[2:3], 0, s[12:13]
	v_mad_u64_u32 v[6:7], s[26:27], v2, s33, v[70:71]
	v_mov_b32_e32 v2, v7
	v_mad_u64_u32 v[2:3], s[26:27], v3, s33, v[2:3]
	v_mov_b32_e32 v7, v2
	v_lshl_add_u64 v[2:3], v[6:7], 0, s[16:17]
	v_lshl_add_u64 v[2:3], v[2:3], 0, v[4:5]
	v_lshl_add_u64 v[2:3], v[2:3], 0, s[82:83]
	s_mov_b32 m0, s5
	v_add_u32_e32 v6, 20, v9
	global_load_lds_dwordx4 v[2:3], off
	v_add_u32_e32 v2, s28, v6
	v_max_i32_e32 v2, 0, v2
	v_mov_b32_e32 v3, v179
	v_lshlrev_b64 v[2:3], s24, v[2:3]
	v_lshl_add_u64 v[2:3], v[2:3], 0, s[12:13]
	v_mad_u64_u32 v[4:5], s[26:27], v2, s33, v[70:71]
	v_mov_b32_e32 v2, v5
	v_mad_u64_u32 v[2:3], s[26:27], v3, s33, v[2:3]
	v_mov_b32_e32 v5, v2
	v_lshl_add_u64 v[2:3], v[4:5], 0, s[16:17]
	v_xor_b32_e32 v4, v6, v8
	v_lshlrev_b32_e32 v4, 4, v4
	v_and_b32_e32 v4, 0xf0, v4
	v_mov_b32_e32 v5, v179
	v_lshl_add_u64 v[2:3], v[2:3], 0, v[4:5]
	v_lshl_add_u64 v[2:3], v[2:3], 0, s[82:83]
	s_mov_b32 m0, s21
	v_add_u32_e32 v6, 24, v9
	global_load_lds_dwordx4 v[2:3], off
	v_add_u32_e32 v2, s28, v6
	v_max_i32_e32 v2, 0, v2
	v_mov_b32_e32 v3, v179
	v_lshlrev_b64 v[2:3], s24, v[2:3]
	v_lshl_add_u64 v[2:3], v[2:3], 0, s[12:13]
	v_mad_u64_u32 v[4:5], s[26:27], v2, s33, v[70:71]
	v_mov_b32_e32 v2, v5
	v_mad_u64_u32 v[2:3], s[26:27], v3, s33, v[2:3]
	v_mov_b32_e32 v5, v2
	v_lshl_add_u64 v[2:3], v[4:5], 0, s[16:17]
	v_xor_b32_e32 v4, v6, v8
	v_lshlrev_b32_e32 v4, 4, v4
	v_and_b32_e32 v4, 0xf0, v4
	v_mov_b32_e32 v5, v179
	v_lshl_add_u64 v[2:3], v[2:3], 0, v[4:5]
	v_lshl_add_u64 v[2:3], v[2:3], 0, s[82:83]
	s_mov_b32 m0, s22
	v_add_u32_e32 v6, 28, v9
	global_load_lds_dwordx4 v[2:3], off
	v_add_u32_e32 v2, s28, v6
	v_max_i32_e32 v2, 0, v2
	v_mov_b32_e32 v3, v179
	v_lshlrev_b64 v[2:3], s24, v[2:3]
	v_lshl_add_u64 v[2:3], v[2:3], 0, s[12:13]
	v_mad_u64_u32 v[4:5], s[26:27], v2, s33, v[70:71]
	v_mov_b32_e32 v2, v5
	v_mad_u64_u32 v[2:3], s[26:27], v3, s33, v[2:3]
	v_mov_b32_e32 v5, v2
	v_lshl_add_u64 v[2:3], v[4:5], 0, s[16:17]
	v_xor_b32_e32 v4, v6, v8
	v_lshlrev_b32_e32 v4, 4, v4
	v_and_b32_e32 v4, 0xf0, v4
	v_mov_b32_e32 v5, v179
	v_lshl_add_u64 v[2:3], v[2:3], 0, v[4:5]
	v_lshl_add_u64 v[2:3], v[2:3], 0, s[82:83]
	s_mov_b32 m0, s23
	v_lshl_add_u32 v26, v150, 8, s2
	global_load_lds_dwordx4 v[2:3], off
	v_bitop3_b32 v2, v149, v151, 15 bitop3:0x78
	s_waitcnt vmcnt(0)
; #define LAS __attribute__((address_space(3)))
; __device__ __forceinline__ void dil_tile(const bf16* __restrict__ P, bf16* MIX, float* LSE, int T, LAS char* vimg, int lane) {
;     ...
;         int ln = lane; asm volatile("" : "+v"(ln));
; #pragma unroll
;         for (int it = 0; it < 8; ++it) { const int rr = (ln >> 4) + 4 * it, c16 = ln & 15; const int key = j0 + 32 * kt + rr, kc = key < 0 ? 0 : key;
;             __builtin_amdgcn_global_load_lds((const unsigned*)(P + (row0 + ((size_t)kc << dsh)) * LDP + C_KB + head * 128 + 8 * (c16 ^ (rr & 15))), (LAS unsigned*)(vimg + it * 1024), 16, 0, 0); }
;         asm volatile("s_waitcnt vmcnt(0)" ::: "memory");
;         bf16x8 kf[8];
; #pragma unroll
;         for (int s = 0; s < 8; ++s) kf[s] = *(const LAS bf16x8*)(vimg + r32 * 256 + (((2 * s + hi) ^ (r32 & 15)) << 4));
;         asm volatile("s_waitcnt lgkmcnt(0)" ::: "memory");
;         f32x16 a = {};
; #pragma unroll
;         for (int s = 0; s < 8; ++s) a = __builtin_amdgcn_mfma_f32_32x32x16_bf16(kf[s], qf[s], a, 0, 0, 0);
	v_lshl_add_u32 v73, v2, 4, v26
	ds_read_b128 v[2:5], v73
	v_add_u32_e32 v6, 2, v149
	v_bitop3_b32 v6, v6, v151, 15 bitop3:0x78
	v_lshl_add_u32 v72, v6, 4, v26
	ds_read_b128 v[18:21], v72
	s_waitcnt vmcnt(0) lgkmcnt(0)
	v_mfma_f32_32x32x16_bf16 v[2:17], v[2:5], v[66:69], 0
	v_add_u32_e32 v22, 4, v149
	v_bitop3_b32 v22, v22, v151, 15 bitop3:0x78
	v_lshl_add_u32 v112, v22, 4, v26
	v_add_u32_e32 v22, 6, v149
	v_bitop3_b32 v22, v22, v151, 15 bitop3:0x78
	v_lshl_add_u32 v113, v22, 4, v26
	ds_read_b128 v[22:25], v113
	v_mfma_f32_32x32x16_bf16 v[2:17], v[18:21], v[106:109], v[2:17]
	ds_read_b128 v[18:21], v112
	s_add_i32 s27, s25, 0xffffffa0
	s_mov_b32 m0, s2
	s_sub_i32 s26, s25, 64
	s_sub_i32 s15, s25, 32
	s_waitcnt lgkmcnt(0)
	v_mfma_f32_32x32x16_bf16 v[2:17], v[18:21], v[102:105], v[2:17]
	v_add_u32_e32 v18, 8, v149
	v_bitop3_b32 v18, v18, v151, 15 bitop3:0x78
	v_lshl_add_u32 v114, v18, 4, v26
	ds_read_b128 v[18:21], v114
	v_mfma_f32_32x32x16_bf16 v[2:17], v[22:25], v[98:101], v[2:17]
	v_add_u32_e32 v22, 10, v149
	v_bitop3_b32 v22, v22, v151, 15 bitop3:0x78
	v_lshl_add_u32 v115, v22, 4, v26
	ds_read_b128 v[22:25], v115
	s_waitcnt lgkmcnt(1)
	v_mfma_f32_32x32x16_bf16 v[2:17], v[18:21], v[94:97], v[2:17]
	v_add_u32_e32 v18, 12, v149
	v_bitop3_b32 v18, v18, v151, 15 bitop3:0x78
	v_lshl_add_u32 v116, v18, 4, v26
	ds_read_b128 v[18:21], v116
	s_waitcnt lgkmcnt(1)
	v_mfma_f32_32x32x16_bf16 v[2:17], v[22:25], v[90:93], v[2:17]
	v_add_u32_e32 v22, 14, v149
	v_bitop3_b32 v22, v22, v151, 15 bitop3:0x78
	v_lshl_add_u32 v117, v22, 4, v26
	ds_read_b128 v[22:25], v117
	s_waitcnt lgkmcnt(0)
	s_waitcnt lgkmcnt(1)
	v_mfma_f32_32x32x16_bf16 v[2:17], v[18:21], v[86:89], v[2:17]
	v_mov_b32_e32 v19, v179
	s_waitcnt lgkmcnt(0)
	v_mfma_f32_32x32x16_bf16 v[2:17], v[22:25], v[82:85], v[2:17]
	v_mov_b32_e32 v24, v151
	s_nop 0
	v_ashrrev_i32_e32 v25, 4, v24
	v_add_u32_e32 v26, s27, v25
	v_max_i32_e32 v18, 0, v26
	v_lshlrev_b64 v[18:19], s24, v[18:19]
	v_lshl_add_u64 v[18:19], v[18:19], 0, s[12:13]
	v_mad_u64_u32 v[20:21], s[30:31], v18, s33, v[70:71]
	v_mov_b32_e32 v18, v21
	v_mad_u64_u32 v[18:19], s[30:31], v19, s33, v[18:19]
	v_mov_b32_e32 v21, v18
	v_lshl_add_u64 v[18:19], v[20:21], 0, s[16:17]
	v_xor_b32_e32 v20, v25, v24
	v_lshlrev_b32_e32 v20, 4, v20
	v_and_b32_e32 v20, 0xf0, v20
	v_mov_b32_e32 v21, v179
	v_lshl_add_u64 v[18:19], v[18:19], 0, v[20:21]
	v_lshl_add_u64 v[18:19], v[18:19], 0, s[82:83]
	v_add_u32_e32 v27, 4, v25
	global_load_lds_dwordx4 v[18:19], off
	v_add_u32_e32 v18, s27, v27
	v_max_i32_e32 v18, 0, v18
	v_mov_b32_e32 v19, v179
	v_lshlrev_b64 v[18:19], s24, v[18:19]
	v_lshl_add_u64 v[18:19], v[18:19], 0, s[12:13]
	v_mad_u64_u32 v[22:23], s[30:31], v18, s33, v[70:71]
	v_mov_b32_e32 v18, v23
	v_mad_u64_u32 v[18:19], s[30:31], v19, s33, v[18:19]
	v_mov_b32_e32 v23, v18
	v_lshl_add_u64 v[18:19], v[22:23], 0, s[16:17]
	v_xor_b32_e32 v22, v27, v24
	v_lshlrev_b32_e32 v22, 4, v22
	v_and_b32_e32 v22, 0xf0, v22
	v_mov_b32_e32 v23, v179
	v_lshl_add_u64 v[18:19], v[18:19], 0, v[22:23]
	v_lshl_add_u64 v[18:19], v[18:19], 0, s[82:83]
	s_mov_b32 m0, s4
	v_add_u32_e32 v27, 8, v25
	global_load_lds_dwordx4 v[18:19], off
	v_add_u32_e32 v18, s27, v27
	v_max_i32_e32 v18, 0, v18
	v_mov_b32_e32 v19, v179
	v_lshlrev_b64 v[18:19], s24, v[18:19]
	v_lshl_add_u64 v[18:19], v[18:19], 0, s[12:13]
	v_mad_u64_u32 v[22:23], s[30:31], v18, s33, v[70:71]
	v_mov_b32_e32 v18, v23
	v_mad_u64_u32 v[18:19], s[30:31], v19, s33, v[18:19]
	v_mov_b32_e32 v23, v18
	v_lshl_add_u64 v[18:19], v[22:23], 0, s[16:17]
	v_xor_b32_e32 v22, v27, v24
	v_lshlrev_b32_e32 v22, 4, v22
	v_and_b32_e32 v22, 0xf0, v22
	v_mov_b32_e32 v23, v179
	v_lshl_add_u64 v[18:19], v[18:19], 0, v[22:23]
	v_lshl_add_u64 v[18:19], v[18:19], 0, s[82:83]
	s_mov_b32 m0, s3
	v_add_u32_e32 v27, 12, v25
	global_load_lds_dwordx4 v[18:19], off
	v_add_u32_e32 v18, s27, v27
	v_max_i32_e32 v18, 0, v18
	v_mov_b32_e32 v19, v179
	v_lshlrev_b64 v[18:19], s24, v[18:19]
	v_lshl_add_u64 v[18:19], v[18:19], 0, s[12:13]
	v_mad_u64_u32 v[22:23], s[30:31], v18, s33, v[70:71]
	v_mov_b32_e32 v18, v23
	v_mad_u64_u32 v[18:19], s[30:31], v19, s33, v[18:19]
	v_mov_b32_e32 v23, v18
	v_lshl_add_u64 v[18:19], v[22:23], 0, s[16:17]
	v_xor_b32_e32 v22, v27, v24
	v_lshlrev_b32_e32 v22, 4, v22
	v_and_b32_e32 v22, 0xf0, v22
	v_mov_b32_e32 v23, v179
	v_lshl_add_u64 v[18:19], v[18:19], 0, v[22:23]
	s_mov_b32 m0, s20
	v_lshl_add_u64 v[18:19], v[18:19], 0, s[82:83]
	global_load_lds_dwordx4 v[18:19], off
	v_max_i32_e32 v18, -16, v26
	v_add_u32_e32 v18, 16, v18
	v_mov_b32_e32 v19, v179
	v_lshlrev_b64 v[18:19], s24, v[18:19]
	v_lshl_add_u64 v[18:19], v[18:19], 0, s[12:13]
	v_mad_u64_u32 v[22:23], s[30:31], v18, s33, v[70:71]
	v_mov_b32_e32 v18, v23
	v_mad_u64_u32 v[18:19], s[30:31], v19, s33, v[18:19]
	v_mov_b32_e32 v23, v18
	v_lshl_add_u64 v[18:19], v[22:23], 0, s[16:17]
	v_lshl_add_u64 v[18:19], v[18:19], 0, v[20:21]
	v_lshl_add_u64 v[18:19], v[18:19], 0, s[82:83]
	s_mov_b32 m0, s5
	v_add_u32_e32 v22, 20, v25
	global_load_lds_dwordx4 v[18:19], off
	v_add_u32_e32 v18, s27, v22
	v_max_i32_e32 v18, 0, v18
	v_mov_b32_e32 v19, v179
	v_lshlrev_b64 v[18:19], s24, v[18:19]
	v_lshl_add_u64 v[18:19], v[18:19], 0, s[12:13]
	v_mad_u64_u32 v[20:21], s[30:31], v18, s33, v[70:71]
	v_mov_b32_e32 v18, v21
	v_mad_u64_u32 v[18:19], s[30:31], v19, s33, v[18:19]
	v_mov_b32_e32 v21, v18
	v_lshl_add_u64 v[18:19], v[20:21], 0, s[16:17]
	v_xor_b32_e32 v20, v22, v24
	v_lshlrev_b32_e32 v20, 4, v20
	v_and_b32_e32 v20, 0xf0, v20
	v_mov_b32_e32 v21, v179
	v_lshl_add_u64 v[18:19], v[18:19], 0, v[20:21]
	v_lshl_add_u64 v[18:19], v[18:19], 0, s[82:83]
	s_mov_b32 m0, s21
	v_add_u32_e32 v22, 24, v25
	global_load_lds_dwordx4 v[18:19], off
	v_add_u32_e32 v18, s27, v22
	v_max_i32_e32 v18, 0, v18
	v_mov_b32_e32 v19, v179
	v_lshlrev_b64 v[18:19], s24, v[18:19]
	v_lshl_add_u64 v[18:19], v[18:19], 0, s[12:13]
	v_mad_u64_u32 v[20:21], s[30:31], v18, s33, v[70:71]
	v_mov_b32_e32 v18, v21
	v_mad_u64_u32 v[18:19], s[30:31], v19, s33, v[18:19]
	v_mov_b32_e32 v21, v18
	v_lshl_add_u64 v[18:19], v[20:21], 0, s[16:17]
	v_xor_b32_e32 v20, v22, v24
	v_lshlrev_b32_e32 v20, 4, v20
	v_and_b32_e32 v20, 0xf0, v20
	v_mov_b32_e32 v21, v179
	v_lshl_add_u64 v[18:19], v[18:19], 0, v[20:21]
	v_lshl_add_u64 v[18:19], v[18:19], 0, s[82:83]
	s_mov_b32 m0, s22
	v_add_u32_e32 v22, 28, v25
	global_load_lds_dwordx4 v[18:19], off
	v_add_u32_e32 v18, s27, v22
	v_max_i32_e32 v18, 0, v18
	v_mov_b32_e32 v19, v179
	v_lshlrev_b64 v[18:19], s24, v[18:19]
	v_lshl_add_u64 v[18:19], v[18:19], 0, s[12:13]
	v_mad_u64_u32 v[20:21], s[30:31], v18, s33, v[70:71]
	v_mov_b32_e32 v18, v21
	v_mad_u64_u32 v[18:19], s[30:31], v19, s33, v[18:19]
	v_mov_b32_e32 v21, v18
	v_lshl_add_u64 v[18:19], v[20:21], 0, s[16:17]
	v_xor_b32_e32 v20, v22, v24
	v_lshlrev_b32_e32 v20, 4, v20
	v_and_b32_e32 v20, 0xf0, v20
	v_mov_b32_e32 v21, v179
	v_lshl_add_u64 v[18:19], v[18:19], 0, v[20:21]
	s_mov_b32 m0, s23
	v_lshl_add_u64 v[18:19], v[18:19], 0, s[82:83]
	global_load_lds_dwordx4 v[18:19], off
	s_waitcnt vmcnt(0)
; #define LAS __attribute__((address_space(3)))
; __device__ __forceinline__ void dil_tile(const bf16* __restrict__ P, bf16* MIX, float* LSE, int T, LAS char* vimg, int lane) {
;     ...
;         int ln = lane; asm volatile("" : "+v"(ln));
; #pragma unroll
;         for (int it = 0; it < 8; ++it) { const int rr = (ln >> 4) + 4 * it, c16 = ln & 15; const int key = j0 + 32 * kt + rr, kc = key < 0 ? 0 : key;
;             __builtin_amdgcn_global_load_lds((const unsigned*)(P + (row0 + ((size_t)kc << dsh)) * LDP + C_KB + head * 128 + 8 * (c16 ^ (rr & 15))), (LAS unsigned*)(vimg + it * 1024), 16, 0, 0); }
;         asm volatile("s_waitcnt vmcnt(0)" ::: "memory");
;         bf16x8 kf[8];
; #pragma unroll
;         for (int s = 0; s < 8; ++s) kf[s] = *(const LAS bf16x8*)(vimg + r32 * 256 + (((2 * s + hi) ^ (r32 & 15)) << 4));
;         asm volatile("s_waitcnt lgkmcnt(0)" ::: "memory");
;         f32x16 a = {};
; #pragma unroll
;         for (int s = 0; s < 8; ++s) a = __builtin_amdgcn_mfma_f32_32x32x16_bf16(kf[s], qf[s], a, 0, 0, 0);
;         S[kt] = a; }
	ds_read_b128 v[18:21], v73
	ds_read_b128 v[34:37], v72
	s_waitcnt lgkmcnt(0)
	v_mfma_f32_32x32x16_bf16 v[18:33], v[18:21], v[66:69], 0
	s_mov_b32 m0, s2
	v_mfma_f32_32x32x16_bf16 v[18:33], v[34:37], v[106:109], v[18:33]
	ds_read_b128 v[34:37], v112
	ds_read_b128 v[38:41], v113
	s_waitcnt lgkmcnt(0)
	v_mfma_f32_32x32x16_bf16 v[18:33], v[34:37], v[102:105], v[18:33]
	v_mfma_f32_32x32x16_bf16 v[18:33], v[38:41], v[98:101], v[18:33]
	ds_read_b128 v[34:37], v114
	ds_read_b128 v[38:41], v115
	s_waitcnt lgkmcnt(0)
	v_mfma_f32_32x32x16_bf16 v[18:33], v[34:37], v[94:97], v[18:33]
	v_mfma_f32_32x32x16_bf16 v[18:33], v[38:41], v[90:93], v[18:33]
	ds_read_b128 v[34:37], v116
	ds_read_b128 v[38:41], v117
	s_waitcnt lgkmcnt(0)
	s_waitcnt lgkmcnt(0)
	v_mfma_f32_32x32x16_bf16 v[18:33], v[34:37], v[86:89], v[18:33]
	v_mov_b32_e32 v35, v179
	v_mfma_f32_32x32x16_bf16 v[18:33], v[38:41], v[82:85], v[18:33]
	v_mov_b32_e32 v40, v151
	s_nop 0
	v_ashrrev_i32_e32 v41, 4, v40
	v_add_u32_e32 v42, s26, v41
	v_max_i32_e32 v34, 0, v42
	v_lshlrev_b64 v[34:35], s24, v[34:35]
	v_lshl_add_u64 v[34:35], v[34:35], 0, s[12:13]
	v_mad_u64_u32 v[36:37], s[30:31], v34, s33, v[70:71]
	v_mov_b32_e32 v34, v37
	v_mad_u64_u32 v[34:35], s[30:31], v35, s33, v[34:35]
	v_mov_b32_e32 v37, v34
	v_lshl_add_u64 v[34:35], v[36:37], 0, s[16:17]
	v_xor_b32_e32 v36, v41, v40
	v_lshlrev_b32_e32 v36, 4, v36
	v_and_b32_e32 v36, 0xf0, v36
	v_mov_b32_e32 v37, v179
	v_lshl_add_u64 v[34:35], v[34:35], 0, v[36:37]
	v_lshl_add_u64 v[34:35], v[34:35], 0, s[82:83]
	v_add_u32_e32 v43, 4, v41
	global_load_lds_dwordx4 v[34:35], off
	v_add_u32_e32 v34, s26, v43
	v_max_i32_e32 v34, 0, v34
	v_mov_b32_e32 v35, v179
	v_lshlrev_b64 v[34:35], s24, v[34:35]
	v_lshl_add_u64 v[34:35], v[34:35], 0, s[12:13]
	v_mad_u64_u32 v[38:39], s[30:31], v34, s33, v[70:71]
	v_mov_b32_e32 v34, v39
	v_mad_u64_u32 v[34:35], s[30:31], v35, s33, v[34:35]
	v_mov_b32_e32 v39, v34
	v_lshl_add_u64 v[34:35], v[38:39], 0, s[16:17]
	v_xor_b32_e32 v38, v43, v40
	v_lshlrev_b32_e32 v38, 4, v38
	v_and_b32_e32 v38, 0xf0, v38
	v_mov_b32_e32 v39, v179
	v_lshl_add_u64 v[34:35], v[34:35], 0, v[38:39]
	v_lshl_add_u64 v[34:35], v[34:35], 0, s[82:83]
	s_mov_b32 m0, s4
	v_add_u32_e32 v43, 8, v41
	global_load_lds_dwordx4 v[34:35], off
	v_add_u32_e32 v34, s26, v43
	v_max_i32_e32 v34, 0, v34
	v_mov_b32_e32 v35, v179
	v_lshlrev_b64 v[34:35], s24, v[34:35]
	v_lshl_add_u64 v[34:35], v[34:35], 0, s[12:13]
	v_mad_u64_u32 v[38:39], s[30:31], v34, s33, v[70:71]
	v_mov_b32_e32 v34, v39
	v_mad_u64_u32 v[34:35], s[30:31], v35, s33, v[34:35]
	v_mov_b32_e32 v39, v34
	v_lshl_add_u64 v[34:35], v[38:39], 0, s[16:17]
	v_xor_b32_e32 v38, v43, v40
	v_lshlrev_b32_e32 v38, 4, v38
	v_and_b32_e32 v38, 0xf0, v38
	v_mov_b32_e32 v39, v179
	v_lshl_add_u64 v[34:35], v[34:35], 0, v[38:39]
	v_lshl_add_u64 v[34:35], v[34:35], 0, s[82:83]
	s_mov_b32 m0, s3
	v_add_u32_e32 v43, 12, v41
	global_load_lds_dwordx4 v[34:35], off
	v_add_u32_e32 v34, s26, v43
	v_max_i32_e32 v34, 0, v34
	v_mov_b32_e32 v35, v179
	v_lshlrev_b64 v[34:35], s24, v[34:35]
	v_lshl_add_u64 v[34:35], v[34:35], 0, s[12:13]
	v_mad_u64_u32 v[38:39], s[30:31], v34, s33, v[70:71]
	v_mov_b32_e32 v34, v39
	v_mad_u64_u32 v[34:35], s[30:31], v35, s33, v[34:35]
	v_mov_b32_e32 v39, v34
	v_lshl_add_u64 v[34:35], v[38:39], 0, s[16:17]
	v_xor_b32_e32 v38, v43, v40
	v_lshlrev_b32_e32 v38, 4, v38
	v_and_b32_e32 v38, 0xf0, v38
	v_mov_b32_e32 v39, v179
	v_lshl_add_u64 v[34:35], v[34:35], 0, v[38:39]
	s_mov_b32 m0, s20
	v_lshl_add_u64 v[34:35], v[34:35], 0, s[82:83]
	global_load_lds_dwordx4 v[34:35], off
	v_max_i32_e32 v34, -16, v42
	v_add_u32_e32 v34, 16, v34
	v_mov_b32_e32 v35, v179
	v_lshlrev_b64 v[34:35], s24, v[34:35]
	v_lshl_add_u64 v[34:35], v[34:35], 0, s[12:13]
	v_mad_u64_u32 v[38:39], s[30:31], v34, s33, v[70:71]
	v_mov_b32_e32 v34, v39
	v_mad_u64_u32 v[34:35], s[30:31], v35, s33, v[34:35]
	v_mov_b32_e32 v39, v34
	v_lshl_add_u64 v[34:35], v[38:39], 0, s[16:17]
	v_lshl_add_u64 v[34:35], v[34:35], 0, v[36:37]
	v_lshl_add_u64 v[34:35], v[34:35], 0, s[82:83]
	s_mov_b32 m0, s5
	v_add_u32_e32 v38, 20, v41
	global_load_lds_dwordx4 v[34:35], off
	v_add_u32_e32 v34, s26, v38
	v_max_i32_e32 v34, 0, v34
	v_mov_b32_e32 v35, v179
	v_lshlrev_b64 v[34:35], s24, v[34:35]
	v_lshl_add_u64 v[34:35], v[34:35], 0, s[12:13]
	v_mad_u64_u32 v[36:37], s[30:31], v34, s33, v[70:71]
	v_mov_b32_e32 v34, v37
	v_mad_u64_u32 v[34:35], s[30:31], v35, s33, v[34:35]
	v_mov_b32_e32 v37, v34
	v_lshl_add_u64 v[34:35], v[36:37], 0, s[16:17]
	v_xor_b32_e32 v36, v38, v40
	v_lshlrev_b32_e32 v36, 4, v36
	v_and_b32_e32 v36, 0xf0, v36
	v_mov_b32_e32 v37, v179
	v_lshl_add_u64 v[34:35], v[34:35], 0, v[36:37]
	v_lshl_add_u64 v[34:35], v[34:35], 0, s[82:83]
	s_mov_b32 m0, s21
	v_add_u32_e32 v38, 24, v41
	global_load_lds_dwordx4 v[34:35], off
	v_add_u32_e32 v34, s26, v38
	v_max_i32_e32 v34, 0, v34
	v_mov_b32_e32 v35, v179
	v_lshlrev_b64 v[34:35], s24, v[34:35]
	v_lshl_add_u64 v[34:35], v[34:35], 0, s[12:13]
	v_mad_u64_u32 v[36:37], s[30:31], v34, s33, v[70:71]
	v_mov_b32_e32 v34, v37
	v_mad_u64_u32 v[34:35], s[30:31], v35, s33, v[34:35]
	v_mov_b32_e32 v37, v34
	v_lshl_add_u64 v[34:35], v[36:37], 0, s[16:17]
	v_xor_b32_e32 v36, v38, v40
	v_lshlrev_b32_e32 v36, 4, v36
	v_and_b32_e32 v36, 0xf0, v36
	v_mov_b32_e32 v37, v179
	v_lshl_add_u64 v[34:35], v[34:35], 0, v[36:37]
	v_lshl_add_u64 v[34:35], v[34:35], 0, s[82:83]
	s_mov_b32 m0, s22
	v_add_u32_e32 v38, 28, v41
	global_load_lds_dwordx4 v[34:35], off
	v_add_u32_e32 v34, s26, v38
	v_max_i32_e32 v34, 0, v34
	v_mov_b32_e32 v35, v179
	v_lshlrev_b64 v[34:35], s24, v[34:35]
	v_lshl_add_u64 v[34:35], v[34:35], 0, s[12:13]
	v_mad_u64_u32 v[36:37], s[30:31], v34, s33, v[70:71]
	v_mov_b32_e32 v34, v37
	v_mad_u64_u32 v[34:35], s[30:31], v35, s33, v[34:35]
	v_mov_b32_e32 v37, v34
	v_lshl_add_u64 v[34:35], v[36:37], 0, s[16:17]
	v_xor_b32_e32 v36, v38, v40
	v_lshlrev_b32_e32 v36, 4, v36
	v_and_b32_e32 v36, 0xf0, v36
	v_mov_b32_e32 v37, v179
	v_lshl_add_u64 v[34:35], v[34:35], 0, v[36:37]
	s_mov_b32 m0, s23
	v_lshl_add_u64 v[34:35], v[34:35], 0, s[82:83]
	global_load_lds_dwordx4 v[34:35], off
	s_waitcnt vmcnt(0)
; #define LAS __attribute__((address_space(3)))
; __device__ __forceinline__ void dil_tile(const bf16* __restrict__ P, bf16* MIX, float* LSE, int T, LAS char* vimg, int lane) {
;     ...
;         int ln = lane; asm volatile("" : "+v"(ln));
; #pragma unroll
;         for (int it = 0; it < 8; ++it) { const int rr = (ln >> 4) + 4 * it, c16 = ln & 15; const int key = j0 + 32 * kt + rr, kc = key < 0 ? 0 : key;
;             __builtin_amdgcn_global_load_lds((const unsigned*)(P + (row0 + ((size_t)kc << dsh)) * LDP + C_KB + head * 128 + 8 * (c16 ^ (rr & 15))), (LAS unsigned*)(vimg + it * 1024), 16, 0, 0); }
;         asm volatile("s_waitcnt vmcnt(0)" ::: "memory");
;         bf16x8 kf[8];
; #pragma unroll
;         for (int s = 0; s < 8; ++s) kf[s] = *(const LAS bf16x8*)(vimg + r32 * 256 + (((2 * s + hi) ^ (r32 & 15)) << 4));
;         asm volatile("s_waitcnt lgkmcnt(0)" ::: "memory");
;         f32x16 a = {};
; #pragma unroll
;         for (int s = 0; s < 8; ++s) a = __builtin_amdgcn_mfma_f32_32x32x16_bf16(kf[s], qf[s], a, 0, 0, 0);
;         S[kt] = a; }
	ds_read_b128 v[34:37], v73
	ds_read_b128 v[50:53], v72
	s_waitcnt lgkmcnt(0)
	v_mfma_f32_32x32x16_bf16 v[34:49], v[34:37], v[66:69], 0
	s_mov_b32 m0, s2
	v_mfma_f32_32x32x16_bf16 v[34:49], v[50:53], v[106:109], v[34:49]
	ds_read_b128 v[50:53], v112
	ds_read_b128 v[54:57], v113
	s_waitcnt lgkmcnt(0)
	v_mfma_f32_32x32x16_bf16 v[34:49], v[50:53], v[102:105], v[34:49]
	v_mfma_f32_32x32x16_bf16 v[34:49], v[54:57], v[98:101], v[34:49]
	ds_read_b128 v[50:53], v114
	ds_read_b128 v[54:57], v115
	s_waitcnt lgkmcnt(0)
	v_mfma_f32_32x32x16_bf16 v[34:49], v[50:53], v[94:97], v[34:49]
	v_mfma_f32_32x32x16_bf16 v[34:49], v[54:57], v[90:93], v[34:49]
	ds_read_b128 v[50:53], v116
	ds_read_b128 v[54:57], v117
	s_waitcnt lgkmcnt(0)
	s_waitcnt lgkmcnt(0)
	v_mfma_f32_32x32x16_bf16 v[34:49], v[50:53], v[86:89], v[34:49]
	v_mov_b32_e32 v51, v179
	v_mfma_f32_32x32x16_bf16 v[34:49], v[54:57], v[82:85], v[34:49]
	v_mov_b32_e32 v56, v151
	s_nop 0
	v_ashrrev_i32_e32 v57, 4, v56
	v_add_u32_e32 v58, s15, v57
	v_max_i32_e32 v50, 0, v58
	v_lshlrev_b64 v[50:51], s24, v[50:51]
	v_lshl_add_u64 v[50:51], v[50:51], 0, s[12:13]
	v_mad_u64_u32 v[52:53], s[30:31], v50, s33, v[70:71]
	v_mov_b32_e32 v50, v53
	v_mad_u64_u32 v[50:51], s[30:31], v51, s33, v[50:51]
	v_mov_b32_e32 v53, v50
	v_lshl_add_u64 v[50:51], v[52:53], 0, s[16:17]
	v_xor_b32_e32 v52, v57, v56
	v_lshlrev_b32_e32 v52, 4, v52
	v_and_b32_e32 v52, 0xf0, v52
	v_mov_b32_e32 v53, v179
	v_lshl_add_u64 v[50:51], v[50:51], 0, v[52:53]
	v_lshl_add_u64 v[50:51], v[50:51], 0, s[82:83]
	v_add_u32_e32 v59, 4, v57
	global_load_lds_dwordx4 v[50:51], off
	v_add_u32_e32 v50, s15, v59
	v_max_i32_e32 v50, 0, v50
	v_mov_b32_e32 v51, v179
	v_lshlrev_b64 v[50:51], s24, v[50:51]
	v_lshl_add_u64 v[50:51], v[50:51], 0, s[12:13]
	v_mad_u64_u32 v[54:55], s[30:31], v50, s33, v[70:71]
	v_mov_b32_e32 v50, v55
	v_mad_u64_u32 v[50:51], s[30:31], v51, s33, v[50:51]
	v_mov_b32_e32 v55, v50
	v_lshl_add_u64 v[50:51], v[54:55], 0, s[16:17]
	v_xor_b32_e32 v54, v59, v56
	v_lshlrev_b32_e32 v54, 4, v54
	v_and_b32_e32 v54, 0xf0, v54
	v_mov_b32_e32 v55, v179
	v_lshl_add_u64 v[50:51], v[50:51], 0, v[54:55]
	v_lshl_add_u64 v[50:51], v[50:51], 0, s[82:83]
	s_mov_b32 m0, s4
	v_add_u32_e32 v59, 8, v57
	global_load_lds_dwordx4 v[50:51], off
	v_add_u32_e32 v50, s15, v59
	v_max_i32_e32 v50, 0, v50
	v_mov_b32_e32 v51, v179
	v_lshlrev_b64 v[50:51], s24, v[50:51]
	v_lshl_add_u64 v[50:51], v[50:51], 0, s[12:13]
	v_mad_u64_u32 v[54:55], s[30:31], v50, s33, v[70:71]
	v_mov_b32_e32 v50, v55
	v_mad_u64_u32 v[50:51], s[30:31], v51, s33, v[50:51]
	v_mov_b32_e32 v55, v50
	v_lshl_add_u64 v[50:51], v[54:55], 0, s[16:17]
	v_xor_b32_e32 v54, v59, v56
	v_lshlrev_b32_e32 v54, 4, v54
	v_and_b32_e32 v54, 0xf0, v54
	v_mov_b32_e32 v55, v179
	v_lshl_add_u64 v[50:51], v[50:51], 0, v[54:55]
	v_lshl_add_u64 v[50:51], v[50:51], 0, s[82:83]
	s_mov_b32 m0, s3
	v_add_u32_e32 v59, 12, v57
	global_load_lds_dwordx4 v[50:51], off
	v_add_u32_e32 v50, s15, v59
	v_max_i32_e32 v50, 0, v50
	v_mov_b32_e32 v51, v179
	v_lshlrev_b64 v[50:51], s24, v[50:51]
	v_lshl_add_u64 v[50:51], v[50:51], 0, s[12:13]
	v_mad_u64_u32 v[54:55], s[30:31], v50, s33, v[70:71]
	v_mov_b32_e32 v50, v55
	v_mad_u64_u32 v[50:51], s[30:31], v51, s33, v[50:51]
	v_mov_b32_e32 v55, v50
	v_lshl_add_u64 v[50:51], v[54:55], 0, s[16:17]
	v_xor_b32_e32 v54, v59, v56
	v_lshlrev_b32_e32 v54, 4, v54
	v_and_b32_e32 v54, 0xf0, v54
	v_mov_b32_e32 v55, v179
	v_lshl_add_u64 v[50:51], v[50:51], 0, v[54:55]
	s_mov_b32 m0, s20
	v_lshl_add_u64 v[50:51], v[50:51], 0, s[82:83]
	global_load_lds_dwordx4 v[50:51], off
	v_max_i32_e32 v50, -16, v58
	v_add_u32_e32 v50, 16, v50
	v_mov_b32_e32 v51, v179
	v_lshlrev_b64 v[50:51], s24, v[50:51]
	v_lshl_add_u64 v[50:51], v[50:51], 0, s[12:13]
	v_mad_u64_u32 v[54:55], s[30:31], v50, s33, v[70:71]
	v_mov_b32_e32 v50, v55
	v_mad_u64_u32 v[50:51], s[30:31], v51, s33, v[50:51]
	v_mov_b32_e32 v55, v50
	v_lshl_add_u64 v[50:51], v[54:55], 0, s[16:17]
	v_lshl_add_u64 v[50:51], v[50:51], 0, v[52:53]
	v_lshl_add_u64 v[50:51], v[50:51], 0, s[82:83]
	s_mov_b32 m0, s5
	v_add_u32_e32 v54, 20, v57
	global_load_lds_dwordx4 v[50:51], off
	v_add_u32_e32 v50, s15, v54
	v_max_i32_e32 v50, 0, v50
	v_mov_b32_e32 v51, v179
	v_lshlrev_b64 v[50:51], s24, v[50:51]
	v_lshl_add_u64 v[50:51], v[50:51], 0, s[12:13]
	v_mad_u64_u32 v[52:53], s[30:31], v50, s33, v[70:71]
	v_mov_b32_e32 v50, v53
	v_mad_u64_u32 v[50:51], s[30:31], v51, s33, v[50:51]
	v_mov_b32_e32 v53, v50
	v_lshl_add_u64 v[50:51], v[52:53], 0, s[16:17]
	v_xor_b32_e32 v52, v54, v56
	v_lshlrev_b32_e32 v52, 4, v52
	v_and_b32_e32 v52, 0xf0, v52
	v_mov_b32_e32 v53, v179
	v_lshl_add_u64 v[50:51], v[50:51], 0, v[52:53]
	v_lshl_add_u64 v[50:51], v[50:51], 0, s[82:83]
	s_mov_b32 m0, s21
	v_add_u32_e32 v54, 24, v57
	global_load_lds_dwordx4 v[50:51], off
	v_add_u32_e32 v50, s15, v54
	v_max_i32_e32 v50, 0, v50
	v_mov_b32_e32 v51, v179
	v_lshlrev_b64 v[50:51], s24, v[50:51]
	v_lshl_add_u64 v[50:51], v[50:51], 0, s[12:13]
	v_mad_u64_u32 v[52:53], s[30:31], v50, s33, v[70:71]
	v_mov_b32_e32 v50, v53
	v_mad_u64_u32 v[50:51], s[30:31], v51, s33, v[50:51]
	v_mov_b32_e32 v53, v50
	v_lshl_add_u64 v[50:51], v[52:53], 0, s[16:17]
	v_xor_b32_e32 v52, v54, v56
	v_lshlrev_b32_e32 v52, 4, v52
	v_and_b32_e32 v52, 0xf0, v52
	v_mov_b32_e32 v53, v179
	v_lshl_add_u64 v[50:51], v[50:51], 0, v[52:53]
	v_lshl_add_u64 v[50:51], v[50:51], 0, s[82:83]
	s_mov_b32 m0, s22
	v_add_u32_e32 v54, 28, v57
	global_load_lds_dwordx4 v[50:51], off
	v_add_u32_e32 v50, s15, v54
	v_max_i32_e32 v50, 0, v50
	v_mov_b32_e32 v51, v179
	v_lshlrev_b64 v[50:51], s24, v[50:51]
	v_lshl_add_u64 v[50:51], v[50:51], 0, s[12:13]
	v_mad_u64_u32 v[52:53], s[30:31], v50, s33, v[70:71]
	v_mov_b32_e32 v50, v53
	v_mad_u64_u32 v[50:51], s[30:31], v51, s33, v[50:51]
	v_mov_b32_e32 v53, v50
	v_lshl_add_u64 v[50:51], v[52:53], 0, s[16:17]
	v_xor_b32_e32 v52, v54, v56
	v_lshlrev_b32_e32 v52, 4, v52
	v_and_b32_e32 v52, 0xf0, v52
	v_mov_b32_e32 v53, v179
	v_lshl_add_u64 v[50:51], v[50:51], 0, v[52:53]
	s_mov_b32 m0, s23
	v_lshl_add_u64 v[50:51], v[50:51], 0, s[82:83]
	global_load_lds_dwordx4 v[50:51], off
	s_waitcnt vmcnt(0)
; #define LAS __attribute__((address_space(3)))
; __device__ __forceinline__ void dil_tile(const bf16* __restrict__ P, bf16* MIX, float* LSE, int T, LAS char* vimg, int lane) {
;     ...
;         int ln = lane; asm volatile("" : "+v"(ln));
; #pragma unroll
;         for (int it = 0; it < 8; ++it) { const int rr = (ln >> 4) + 4 * it, c16 = ln & 15; const int key = j0 + 32 * kt + rr, kc = key < 0 ? 0 : key;
;             __builtin_amdgcn_global_load_lds((const unsigned*)(P + (row0 + ((size_t)kc << dsh)) * LDP + C_KB + head * 128 + 8 * (c16 ^ (rr & 15))), (LAS unsigned*)(vimg + it * 1024), 16, 0, 0); }
;         asm volatile("s_waitcnt vmcnt(0)" ::: "memory");
;         bf16x8 kf[8];
; #pragma unroll
;         for (int s = 0; s < 8; ++s) kf[s] = *(const LAS bf16x8*)(vimg + r32 * 256 + (((2 * s + hi) ^ (r32 & 15)) << 4));
;         asm volatile("s_waitcnt lgkmcnt(0)" ::: "memory");
;         f32x16 a = {};
; #pragma unroll
;         for (int s = 0; s < 8; ++s) a = __builtin_amdgcn_mfma_f32_32x32x16_bf16(kf[s], qf[s], a, 0, 0, 0);
;         S[kt] = a; }
	ds_read_b128 v[50:53], v73
	ds_read_b128 v[74:77], v72
	s_waitcnt lgkmcnt(0)
	v_mfma_f32_32x32x16_bf16 v[50:65], v[50:53], v[66:69], 0
	s_mov_b32 m0, s2
	v_mfma_f32_32x32x16_bf16 v[50:65], v[74:77], v[106:109], v[50:65]
	ds_read_b128 v[74:77], v112
	ds_read_b128 v[78:81], v113
	s_waitcnt lgkmcnt(0)
	v_mfma_f32_32x32x16_bf16 v[50:65], v[74:77], v[102:105], v[50:65]
	v_mfma_f32_32x32x16_bf16 v[50:65], v[78:81], v[98:101], v[50:65]
	ds_read_b128 v[74:77], v114
	ds_read_b128 v[78:81], v115
	s_waitcnt lgkmcnt(0)
	v_mfma_f32_32x32x16_bf16 v[50:65], v[74:77], v[94:97], v[50:65]
	v_mfma_f32_32x32x16_bf16 v[50:65], v[78:81], v[90:93], v[50:65]
	ds_read_b128 v[74:77], v116
	ds_read_b128 v[78:81], v117
	s_waitcnt lgkmcnt(0)
	s_waitcnt lgkmcnt(0)
	v_mfma_f32_32x32x16_bf16 v[50:65], v[74:77], v[86:89], v[50:65]
	v_mov_b32_e32 v75, v179
	v_mfma_f32_32x32x16_bf16 v[50:65], v[78:81], v[82:85], v[50:65]
	v_mov_b32_e32 v80, v151
	s_nop 0
	v_ashrrev_i32_e32 v81, 4, v80
	v_add_u32_e32 v118, s25, v81
	v_max_i32_e32 v74, 0, v118
	v_lshlrev_b64 v[74:75], s24, v[74:75]
	v_lshl_add_u64 v[74:75], v[74:75], 0, s[12:13]
	v_mad_u64_u32 v[76:77], s[30:31], v74, s33, v[70:71]
	v_mov_b32_e32 v74, v77
	v_mad_u64_u32 v[74:75], s[30:31], v75, s33, v[74:75]
	v_mov_b32_e32 v77, v74
	v_lshl_add_u64 v[74:75], v[76:77], 0, s[16:17]
	v_xor_b32_e32 v76, v81, v80
	v_lshlrev_b32_e32 v76, 4, v76
	v_and_b32_e32 v76, 0xf0, v76
	v_mov_b32_e32 v77, v179
	v_lshl_add_u64 v[74:75], v[74:75], 0, v[76:77]
	v_lshl_add_u64 v[74:75], v[74:75], 0, s[82:83]
	v_add_u32_e32 v119, 4, v81
	global_load_lds_dwordx4 v[74:75], off
	v_add_u32_e32 v74, s25, v119
	v_max_i32_e32 v74, 0, v74
	v_mov_b32_e32 v75, v179
	v_lshlrev_b64 v[74:75], s24, v[74:75]
	v_lshl_add_u64 v[74:75], v[74:75], 0, s[12:13]
	v_mad_u64_u32 v[78:79], s[30:31], v74, s33, v[70:71]
	v_mov_b32_e32 v74, v79
	v_mad_u64_u32 v[74:75], s[30:31], v75, s33, v[74:75]
	v_mov_b32_e32 v79, v74
	v_lshl_add_u64 v[74:75], v[78:79], 0, s[16:17]
	v_xor_b32_e32 v78, v119, v80
	v_lshlrev_b32_e32 v78, 4, v78
	v_and_b32_e32 v78, 0xf0, v78
	v_mov_b32_e32 v79, v179
	v_lshl_add_u64 v[74:75], v[74:75], 0, v[78:79]
	v_lshl_add_u64 v[74:75], v[74:75], 0, s[82:83]
	s_mov_b32 m0, s4
	v_add_u32_e32 v119, 8, v81
	global_load_lds_dwordx4 v[74:75], off
	v_add_u32_e32 v74, s25, v119
	v_max_i32_e32 v74, 0, v74
	v_mov_b32_e32 v75, v179
	v_lshlrev_b64 v[74:75], s24, v[74:75]
	v_lshl_add_u64 v[74:75], v[74:75], 0, s[12:13]
	v_mad_u64_u32 v[78:79], s[30:31], v74, s33, v[70:71]
	v_mov_b32_e32 v74, v79
	v_mad_u64_u32 v[74:75], s[30:31], v75, s33, v[74:75]
	v_mov_b32_e32 v79, v74
	v_lshl_add_u64 v[74:75], v[78:79], 0, s[16:17]
	v_xor_b32_e32 v78, v119, v80
	v_lshlrev_b32_e32 v78, 4, v78
	v_and_b32_e32 v78, 0xf0, v78
	v_mov_b32_e32 v79, v179
	v_lshl_add_u64 v[74:75], v[74:75], 0, v[78:79]
	v_lshl_add_u64 v[74:75], v[74:75], 0, s[82:83]
	s_mov_b32 m0, s3
	v_add_u32_e32 v119, 12, v81
	global_load_lds_dwordx4 v[74:75], off
	v_add_u32_e32 v74, s25, v119
	v_max_i32_e32 v74, 0, v74
	v_mov_b32_e32 v75, v179
	v_lshlrev_b64 v[74:75], s24, v[74:75]
	v_lshl_add_u64 v[74:75], v[74:75], 0, s[12:13]
	v_mad_u64_u32 v[78:79], s[30:31], v74, s33, v[70:71]
	v_mov_b32_e32 v74, v79
	v_mad_u64_u32 v[74:75], s[30:31], v75, s33, v[74:75]
	v_mov_b32_e32 v79, v74
	v_lshl_add_u64 v[74:75], v[78:79], 0, s[16:17]
	v_xor_b32_e32 v78, v119, v80
	v_lshlrev_b32_e32 v78, 4, v78
	v_and_b32_e32 v78, 0xf0, v78
	v_mov_b32_e32 v79, v179
	v_lshl_add_u64 v[74:75], v[74:75], 0, v[78:79]
	s_mov_b32 m0, s20
	v_lshl_add_u64 v[74:75], v[74:75], 0, s[82:83]
	global_load_lds_dwordx4 v[74:75], off
	v_max_i32_e32 v74, -16, v118
	v_add_u32_e32 v74, 16, v74
	v_mov_b32_e32 v75, v179
	v_lshlrev_b64 v[74:75], s24, v[74:75]
	v_lshl_add_u64 v[74:75], v[74:75], 0, s[12:13]
	v_mad_u64_u32 v[78:79], s[30:31], v74, s33, v[70:71]
	v_mov_b32_e32 v74, v79
	v_mad_u64_u32 v[74:75], s[30:31], v75, s33, v[74:75]
	v_mov_b32_e32 v79, v74
	v_lshl_add_u64 v[74:75], v[78:79], 0, s[16:17]
	v_lshl_add_u64 v[74:75], v[74:75], 0, v[76:77]
	v_lshl_add_u64 v[74:75], v[74:75], 0, s[82:83]
	s_mov_b32 m0, s5
	v_add_u32_e32 v78, 20, v81
	global_load_lds_dwordx4 v[74:75], off
	v_add_u32_e32 v74, s25, v78
	v_max_i32_e32 v74, 0, v74
	v_mov_b32_e32 v75, v179
	v_lshlrev_b64 v[74:75], s24, v[74:75]
	v_lshl_add_u64 v[74:75], v[74:75], 0, s[12:13]
	v_mad_u64_u32 v[76:77], s[4:5], v74, s33, v[70:71]
	v_mov_b32_e32 v74, v77
	v_mad_u64_u32 v[74:75], s[4:5], v75, s33, v[74:75]
	v_mov_b32_e32 v77, v74
	v_lshl_add_u64 v[74:75], v[76:77], 0, s[16:17]
	v_xor_b32_e32 v76, v78, v80
	v_lshlrev_b32_e32 v76, 4, v76
	v_and_b32_e32 v76, 0xf0, v76
	v_mov_b32_e32 v77, v179
	v_lshl_add_u64 v[74:75], v[74:75], 0, v[76:77]
	v_lshl_add_u64 v[74:75], v[74:75], 0, s[82:83]
	s_mov_b32 m0, s21
	v_add_u32_e32 v78, 24, v81
	global_load_lds_dwordx4 v[74:75], off
	v_add_u32_e32 v74, s25, v78
	v_max_i32_e32 v74, 0, v74
	v_mov_b32_e32 v75, v179
	v_lshlrev_b64 v[74:75], s24, v[74:75]
	v_lshl_add_u64 v[74:75], v[74:75], 0, s[12:13]
	v_mad_u64_u32 v[76:77], s[4:5], v74, s33, v[70:71]
	v_mov_b32_e32 v74, v77
	v_mad_u64_u32 v[74:75], s[4:5], v75, s33, v[74:75]
	v_mov_b32_e32 v77, v74
	v_lshl_add_u64 v[74:75], v[76:77], 0, s[16:17]
	v_xor_b32_e32 v76, v78, v80
	v_lshlrev_b32_e32 v76, 4, v76
	v_and_b32_e32 v76, 0xf0, v76
	v_mov_b32_e32 v77, v179
	v_lshl_add_u64 v[74:75], v[74:75], 0, v[76:77]
	v_lshl_add_u64 v[74:75], v[74:75], 0, s[82:83]
	s_mov_b32 m0, s22
	v_add_u32_e32 v76, 28, v81
	global_load_lds_dwordx4 v[74:75], off
	v_add_u32_e32 v74, s25, v76
	v_max_i32_e32 v74, 0, v74
	v_mov_b32_e32 v75, v179
	v_lshlrev_b64 v[74:75], s24, v[74:75]
	v_lshl_add_u64 v[74:75], v[74:75], 0, s[12:13]
	v_mad_u64_u32 v[70:71], s[4:5], v74, s33, v[70:71]
	v_mov_b32_e32 v74, v71
	v_mad_u64_u32 v[74:75], s[4:5], v75, s33, v[74:75]
	v_mov_b32_e32 v71, v74
	v_xor_b32_e32 v74, v76, v80
	v_lshlrev_b32_e32 v74, 4, v74
	v_lshl_add_u64 v[70:71], v[70:71], 0, s[16:17]
	v_and_b32_e32 v74, 0xf0, v74
	v_mov_b32_e32 v75, v179
	v_lshl_add_u64 v[70:71], v[70:71], 0, v[74:75]
	s_mov_b32 m0, s23
	v_lshl_add_u64 v[70:71], v[70:71], 0, s[82:83]
	global_load_lds_dwordx4 v[70:71], off
	s_waitcnt vmcnt(0)
; __device__ __forceinline__ int crow(int r, int hi) { return (r & 3) + 8 * (r >> 2) + 4 * hi; }
; __device__ __forceinline__ int crow(int r, int hi) { return (r & 3) + 8 * (r >> 2) + 4 * hi; }
; __device__ __forceinline__ void dil_tile(const bf16* __restrict__ P, bf16* MIX, float* LSE, int T, LAS char* vimg, int lane) {
;     ...
;         f32x16 a = {};
; #pragma unroll
;         for (int s = 0; s < 8; ++s) a = __builtin_amdgcn_mfma_f32_32x32x16_bf16(kf[s], qf[s], a, 0, 0, 0);
;         S[kt] = a; }
;     const int iq = i0 + r32; float mx = -INFINITY;
; #pragma unroll
;     for (int kt = 0; kt < 5; ++kt)
; #pragma unroll
;         for (int g = 0; g < 16; ++g) { const int key = j0 + 32 * kt + crow(g, hi); const bool ok = (key >= 0) && (key <= iq) && (key >= iq - 128); const float v = ok ? S[kt][g] : -INFINITY; S[kt][g] = v; mx = fmaxf(mx, v); }
	ds_read_b128 v[74:77], v73
	ds_read_b128 v[118:121], v72
	s_waitcnt lgkmcnt(0)
	v_mfma_f32_32x32x16_bf16 v[66:81], v[74:77], v[66:69], 0
	v_mfma_f32_32x32x16_bf16 v[66:81], v[118:121], v[106:109], v[66:81]
	ds_read_b128 v[106:109], v112
	ds_read_b128 v[118:121], v113
	s_waitcnt lgkmcnt(0)
	v_mfma_f32_32x32x16_bf16 v[66:81], v[106:109], v[102:105], v[66:81]
	v_mfma_f32_32x32x16_bf16 v[66:81], v[118:121], v[98:101], v[66:81]
	ds_read_b128 v[98:101], v114
	ds_read_b128 v[102:105], v115
	s_waitcnt lgkmcnt(0)
	v_mfma_f32_32x32x16_bf16 v[66:81], v[98:101], v[94:97], v[66:81]
	v_mfma_f32_32x32x16_bf16 v[66:81], v[102:105], v[90:93], v[66:81]
	ds_read_b128 v[90:93], v116
	ds_read_b128 v[94:97], v117
	s_waitcnt lgkmcnt(0)
	s_waitcnt lgkmcnt(0)
	v_mfma_f32_32x32x16_bf16 v[66:81], v[90:93], v[86:89], v[66:81]
	v_mfma_f32_32x32x16_bf16 v[66:81], v[94:97], v[82:85], v[66:81]
	v_lshlrev_b32_e32 v82, 2, v149
	v_add_u32_e32 v83, s28, v82
	v_add_u32_e32 v84, 0xffffff80, v178
	v_cmp_le_u32_e32 vcc, v83, v178
	v_cmp_ge_i32_e64 s[4:5], v83, v84
	s_and_b64 vcc, vcc, s[4:5]
	v_or_b32_e32 v85, 1, v83
	v_cndmask_b32_e32 v2, v200, v2, vcc
	v_cmp_lt_u32_e32 vcc, v83, v178
	v_cmp_ge_i32_e64 s[4:5], v85, v84
	s_and_b64 vcc, vcc, s[4:5]
	v_cndmask_b32_e32 v3, v200, v3, vcc
	s_mov_b32 s4, 0xff800000
	v_or_b32_e32 v86, 2, v83
	v_max3_f32 v85, v2, s4, v3
	v_cmp_le_u32_e32 vcc, v86, v178
	v_cmp_ge_i32_e64 s[4:5], v86, v84
	s_and_b64 vcc, vcc, s[4:5]
	v_or_b32_e32 v86, 3, v83
	v_cndmask_b32_e32 v4, v200, v4, vcc
	v_cmp_le_u32_e32 vcc, v86, v178
	v_cmp_ge_i32_e64 s[4:5], v86, v84
	s_and_b64 vcc, vcc, s[4:5]
	v_add_u32_e32 v86, 8, v83
	v_cndmask_b32_e32 v5, v200, v5, vcc
	v_cmp_le_u32_e32 vcc, v86, v178
	v_cmp_ge_i32_e64 s[4:5], v86, v84
	s_and_b64 vcc, vcc, s[4:5]
	v_add_u32_e32 v86, 9, v83
	v_cndmask_b32_e32 v6, v200, v6, vcc
	v_cmp_le_u32_e32 vcc, v86, v178
	v_cmp_ge_i32_e64 s[4:5], v86, v84
	s_and_b64 vcc, vcc, s[4:5]
	v_add_u32_e32 v86, 10, v83
	v_cndmask_b32_e32 v7, v200, v7, vcc
	v_cmp_le_u32_e32 vcc, v86, v178
	v_cmp_ge_i32_e64 s[4:5], v86, v84
	s_and_b64 vcc, vcc, s[4:5]
	v_add_u32_e32 v86, 11, v83
	v_cndmask_b32_e32 v8, v200, v8, vcc
	v_cmp_le_u32_e32 vcc, v86, v178
	v_cmp_ge_i32_e64 s[4:5], v86, v84
	s_and_b64 vcc, vcc, s[4:5]
	v_add_u32_e32 v86, 16, v83
	v_cndmask_b32_e32 v9, v200, v9, vcc
	v_cmp_le_u32_e32 vcc, v86, v178
	v_cmp_ge_i32_e64 s[4:5], v86, v84
	s_and_b64 vcc, vcc, s[4:5]
	v_add_u32_e32 v86, 17, v83
	v_max3_f32 v85, v85, v4, v5
	v_cndmask_b32_e32 v10, v200, v10, vcc
	v_cmp_le_u32_e32 vcc, v86, v178
	v_cmp_ge_i32_e64 s[4:5], v86, v84
	v_max3_f32 v85, v85, v6, v7
	s_and_b64 vcc, vcc, s[4:5]
	v_max3_f32 v85, v85, v8, v9
	v_cndmask_b32_e32 v86, v200, v11, vcc
	v_max3_f32 v11, v85, v10, v86
	v_add_u32_e32 v85, 18, v83
	v_cmp_le_u32_e32 vcc, v85, v178
	v_cmp_ge_i32_e64 s[4:5], v85, v84
	s_and_b64 vcc, vcc, s[4:5]
	v_add_u32_e32 v85, 19, v83
	v_cndmask_b32_e32 v12, v200, v12, vcc
	v_cmp_le_u32_e32 vcc, v85, v178
	v_cmp_ge_i32_e64 s[4:5], v85, v84
	s_and_b64 vcc, vcc, s[4:5]
	v_add_u32_e32 v85, 24, v83
	v_cndmask_b32_e32 v13, v200, v13, vcc
	v_cmp_le_u32_e32 vcc, v85, v178
	v_cmp_ge_i32_e64 s[4:5], v85, v84
	s_and_b64 vcc, vcc, s[4:5]
	v_add_u32_e32 v85, 25, v83
	v_cndmask_b32_e32 v14, v200, v14, vcc
	v_cmp_le_u32_e32 vcc, v85, v178
	v_cmp_ge_i32_e64 s[4:5], v85, v84
	s_and_b64 vcc, vcc, s[4:5]
	v_add_u32_e32 v85, 26, v83
	v_cndmask_b32_e32 v15, v200, v15, vcc
	v_cmp_le_u32_e32 vcc, v85, v178
	v_cmp_ge_i32_e64 s[4:5], v85, v84
	s_and_b64 vcc, vcc, s[4:5]
	v_add_u32_e32 v85, 27, v83
	v_cndmask_b32_e32 v16, v200, v16, vcc
	v_cmp_le_u32_e32 vcc, v85, v178
	v_cmp_ge_i32_e64 s[4:5], v85, v84
	s_and_b64 vcc, vcc, s[4:5]
	v_add_u32_e32 v85, 32, v83
	v_cndmask_b32_e32 v17, v200, v17, vcc
	v_cmp_le_u32_e32 vcc, v85, v178
	v_cmp_ge_i32_e64 s[4:5], v85, v84
	s_and_b64 vcc, vcc, s[4:5]
	v_add_u32_e32 v87, 33, v83
	v_cndmask_b32_e32 v18, v200, v18, vcc
	v_cmp_lt_u32_e32 vcc, v85, v178
	v_cmp_ge_i32_e64 s[4:5], v87, v84
	s_and_b64 vcc, vcc, s[4:5]
	v_add_u32_e32 v85, 34, v83
	v_cndmask_b32_e32 v19, v200, v19, vcc
	v_cmp_le_u32_e32 vcc, v85, v178
	v_cmp_ge_i32_e64 s[4:5], v85, v84
	s_and_b64 vcc, vcc, s[4:5]
	v_add_u32_e32 v85, 35, v83
	v_cndmask_b32_e32 v20, v200, v20, vcc
	v_cmp_le_u32_e32 vcc, v85, v178
	v_cmp_ge_i32_e64 s[4:5], v85, v84
	s_and_b64 vcc, vcc, s[4:5]
	v_add_u32_e32 v85, 40, v83
	v_cndmask_b32_e32 v21, v200, v21, vcc
	v_cmp_le_u32_e32 vcc, v85, v178
	v_cmp_ge_i32_e64 s[4:5], v85, v84
	s_and_b64 vcc, vcc, s[4:5]
	v_add_u32_e32 v85, 41, v83
	v_cndmask_b32_e32 v22, v200, v22, vcc
	v_cmp_le_u32_e32 vcc, v85, v178
	v_cmp_ge_i32_e64 s[4:5], v85, v84
	s_and_b64 vcc, vcc, s[4:5]
	v_add_u32_e32 v85, 42, v83
	v_cndmask_b32_e32 v23, v200, v23, vcc
	v_cmp_le_u32_e32 vcc, v85, v178
	v_cmp_ge_i32_e64 s[4:5], v85, v84
	s_and_b64 vcc, vcc, s[4:5]
	v_add_u32_e32 v85, 43, v83
	v_cndmask_b32_e32 v24, v200, v24, vcc
	v_cmp_le_u32_e32 vcc, v85, v178
	v_cmp_ge_i32_e64 s[4:5], v85, v84
	s_and_b64 vcc, vcc, s[4:5]
	v_add_u32_e32 v85, 48, v83
	v_cndmask_b32_e32 v25, v200, v25, vcc
	v_cmp_le_u32_e32 vcc, v85, v178
	v_cmp_ge_i32_e64 s[4:5], v85, v84
	s_and_b64 vcc, vcc, s[4:5]
	v_add_u32_e32 v85, 49, v83
	v_cndmask_b32_e32 v26, v200, v26, vcc
	v_cmp_le_u32_e32 vcc, v85, v178
	v_cmp_ge_i32_e64 s[4:5], v85, v84
	s_and_b64 vcc, vcc, s[4:5]
	v_add_u32_e32 v85, 50, v83
	v_cndmask_b32_e32 v27, v200, v27, vcc
	v_cmp_le_u32_e32 vcc, v85, v178
	v_cmp_ge_i32_e64 s[4:5], v85, v84
	s_and_b64 vcc, vcc, s[4:5]
	v_add_u32_e32 v85, 51, v83
	v_cndmask_b32_e32 v28, v200, v28, vcc
	v_cmp_le_u32_e32 vcc, v85, v178
	v_cmp_ge_i32_e64 s[4:5], v85, v84
	s_and_b64 vcc, vcc, s[4:5]
	v_add_u32_e32 v85, 56, v83
; __device__ __forceinline__ int crow(int r, int hi) { return (r & 3) + 8 * (r >> 2) + 4 * hi; }
; __device__ __forceinline__ int crow(int r, int hi) { return (r & 3) + 8 * (r >> 2) + 4 * hi; }
; __device__ __forceinline__ void dil_tile(const bf16* __restrict__ P, bf16* MIX, float* LSE, int T, LAS char* vimg, int lane) {
;     ...
;     const int iq = i0 + r32; float mx = -INFINITY;
; #pragma unroll
;     for (int kt = 0; kt < 5; ++kt)
; #pragma unroll
;         for (int g = 0; g < 16; ++g) { const int key = j0 + 32 * kt + crow(g, hi); const bool ok = (key >= 0) && (key <= iq) && (key >= iq - 128); const float v = ok ? S[kt][g] : -INFINITY; S[kt][g] = v; mx = fmaxf(mx, v); }
	v_cndmask_b32_e32 v29, v200, v29, vcc
	v_cmp_le_u32_e32 vcc, v85, v178
	v_cmp_ge_i32_e64 s[4:5], v85, v84
	s_and_b64 vcc, vcc, s[4:5]
	v_add_u32_e32 v85, 57, v83
	v_cndmask_b32_e32 v30, v200, v30, vcc
	v_cmp_le_u32_e32 vcc, v85, v178
	v_cmp_ge_i32_e64 s[4:5], v85, v84
	s_and_b64 vcc, vcc, s[4:5]
	v_add_u32_e32 v85, 58, v83
	v_cndmask_b32_e32 v31, v200, v31, vcc
	v_cmp_le_u32_e32 vcc, v85, v178
	v_cmp_ge_i32_e64 s[4:5], v85, v84
	s_and_b64 vcc, vcc, s[4:5]
	v_add_u32_e32 v85, 59, v83
	v_cndmask_b32_e32 v32, v200, v32, vcc
	v_cmp_le_u32_e32 vcc, v85, v178
	v_cmp_ge_i32_e64 s[4:5], v85, v84
	s_and_b64 vcc, vcc, s[4:5]
	v_add_u32_e32 v85, 64, v83
	v_cndmask_b32_e32 v33, v200, v33, vcc
	v_cmp_le_u32_e32 vcc, v85, v178
	v_cmp_ge_i32_e64 s[4:5], v85, v84
	s_and_b64 vcc, vcc, s[4:5]
	v_add_u32_e32 v87, 0x41, v83
	v_cndmask_b32_e32 v34, v200, v34, vcc
	v_cmp_lt_u32_e32 vcc, v85, v178
	v_cmp_ge_i32_e64 s[4:5], v87, v84
	s_and_b64 vcc, vcc, s[4:5]
	v_add_u32_e32 v85, 0x42, v83
	v_cndmask_b32_e32 v35, v200, v35, vcc
	v_cmp_le_u32_e32 vcc, v85, v178
	v_cmp_ge_i32_e64 s[4:5], v85, v84
	s_and_b64 vcc, vcc, s[4:5]
	v_add_u32_e32 v85, 0x43, v83
	v_cndmask_b32_e32 v36, v200, v36, vcc
	v_cmp_le_u32_e32 vcc, v85, v178
	v_cmp_ge_i32_e64 s[4:5], v85, v84
	s_and_b64 vcc, vcc, s[4:5]
	v_add_u32_e32 v85, 0x48, v83
	v_cndmask_b32_e32 v37, v200, v37, vcc
	v_cmp_le_u32_e32 vcc, v85, v178
	v_cmp_ge_i32_e64 s[4:5], v85, v84
	s_and_b64 vcc, vcc, s[4:5]
	v_add_u32_e32 v85, 0x49, v83
	v_cndmask_b32_e32 v38, v200, v38, vcc
	v_cmp_le_u32_e32 vcc, v85, v178
	v_cmp_ge_i32_e64 s[4:5], v85, v84
	s_and_b64 vcc, vcc, s[4:5]
	v_add_u32_e32 v85, 0x4a, v83
	v_cndmask_b32_e32 v39, v200, v39, vcc
	v_cmp_le_u32_e32 vcc, v85, v178
	v_cmp_ge_i32_e64 s[4:5], v85, v84
	s_and_b64 vcc, vcc, s[4:5]
	v_add_u32_e32 v85, 0x4b, v83
	v_cndmask_b32_e32 v40, v200, v40, vcc
	v_cmp_le_u32_e32 vcc, v85, v178
	v_cmp_ge_i32_e64 s[4:5], v85, v84
	s_and_b64 vcc, vcc, s[4:5]
	v_add_u32_e32 v85, 0x50, v83
	v_cndmask_b32_e32 v41, v200, v41, vcc
	v_cmp_le_u32_e32 vcc, v85, v178
	v_cmp_ge_i32_e64 s[4:5], v85, v84
	s_and_b64 vcc, vcc, s[4:5]
	v_add_u32_e32 v85, 0x51, v83
	v_cndmask_b32_e32 v42, v200, v42, vcc
	v_cmp_le_u32_e32 vcc, v85, v178
	v_cmp_ge_i32_e64 s[4:5], v85, v84
	s_and_b64 vcc, vcc, s[4:5]
	v_add_u32_e32 v85, 0x52, v83
	v_cndmask_b32_e32 v43, v200, v43, vcc
	v_cmp_le_u32_e32 vcc, v85, v178
	v_cmp_ge_i32_e64 s[4:5], v85, v84
	s_and_b64 vcc, vcc, s[4:5]
	v_add_u32_e32 v85, 0x53, v83
	v_cndmask_b32_e32 v44, v200, v44, vcc
	v_cmp_le_u32_e32 vcc, v85, v178
	v_cmp_ge_i32_e64 s[4:5], v85, v84
	s_and_b64 vcc, vcc, s[4:5]
	v_add_u32_e32 v85, 0x58, v83
	v_cndmask_b32_e32 v45, v200, v45, vcc
	v_cmp_le_u32_e32 vcc, v85, v178
	v_cmp_ge_i32_e64 s[4:5], v85, v84
	s_and_b64 vcc, vcc, s[4:5]
	v_add_u32_e32 v85, 0x59, v83
	v_cndmask_b32_e32 v46, v200, v46, vcc
	v_cmp_le_u32_e32 vcc, v85, v178
	v_cmp_ge_i32_e64 s[4:5], v85, v84
	s_and_b64 vcc, vcc, s[4:5]
	v_add_u32_e32 v85, 0x5a, v83
	v_cndmask_b32_e32 v47, v200, v47, vcc
	v_cmp_le_u32_e32 vcc, v85, v178
	v_cmp_ge_i32_e64 s[4:5], v85, v84
	s_and_b64 vcc, vcc, s[4:5]
	v_add_u32_e32 v85, 0x5b, v83
	v_cndmask_b32_e32 v48, v200, v48, vcc
	v_cmp_le_u32_e32 vcc, v85, v178
	v_cmp_ge_i32_e64 s[4:5], v85, v84
	s_and_b64 vcc, vcc, s[4:5]
	v_add_u32_e32 v85, 0x60, v83
	v_cndmask_b32_e32 v49, v200, v49, vcc
	v_cmp_le_u32_e32 vcc, v85, v178
	v_cmp_ge_i32_e64 s[4:5], v85, v84
	s_and_b64 vcc, vcc, s[4:5]
	v_add_u32_e32 v87, 0x61, v83
	v_cndmask_b32_e32 v50, v200, v50, vcc
	v_cmp_lt_u32_e32 vcc, v85, v178
	v_cmp_ge_i32_e64 s[4:5], v87, v84
	s_and_b64 vcc, vcc, s[4:5]
	v_add_u32_e32 v85, 0x62, v83
	v_cndmask_b32_e32 v51, v200, v51, vcc
	v_cmp_le_u32_e32 vcc, v85, v178
	v_cmp_ge_i32_e64 s[4:5], v85, v84
	s_and_b64 vcc, vcc, s[4:5]
	v_add_u32_e32 v85, 0x63, v83
	v_cndmask_b32_e32 v52, v200, v52, vcc
	v_cmp_le_u32_e32 vcc, v85, v178
	v_cmp_ge_i32_e64 s[4:5], v85, v84
	s_and_b64 vcc, vcc, s[4:5]
	v_add_u32_e32 v85, 0x68, v83
	v_cndmask_b32_e32 v53, v200, v53, vcc
	v_cmp_le_u32_e32 vcc, v85, v178
	v_cmp_ge_i32_e64 s[4:5], v85, v84
	s_and_b64 vcc, vcc, s[4:5]
	v_add_u32_e32 v85, 0x69, v83
	v_cndmask_b32_e32 v54, v200, v54, vcc
	v_cmp_le_u32_e32 vcc, v85, v178
	v_cmp_ge_i32_e64 s[4:5], v85, v84
	s_and_b64 vcc, vcc, s[4:5]
	v_add_u32_e32 v85, 0x6a, v83
	v_cndmask_b32_e32 v55, v200, v55, vcc
	v_cmp_le_u32_e32 vcc, v85, v178
	v_cmp_ge_i32_e64 s[4:5], v85, v84
	s_and_b64 vcc, vcc, s[4:5]
	v_add_u32_e32 v85, 0x6b, v83
	v_cndmask_b32_e32 v56, v200, v56, vcc
	v_cmp_le_u32_e32 vcc, v85, v178
	v_cmp_ge_i32_e64 s[4:5], v85, v84
	s_and_b64 vcc, vcc, s[4:5]
	v_add_u32_e32 v85, 0x70, v83
	v_cndmask_b32_e32 v57, v200, v57, vcc
	v_cmp_le_u32_e32 vcc, v85, v178
	v_cmp_ge_i32_e64 s[4:5], v85, v84
	s_and_b64 vcc, vcc, s[4:5]
	v_add_u32_e32 v85, 0x71, v83
	v_cndmask_b32_e32 v58, v200, v58, vcc
	v_cmp_le_u32_e32 vcc, v85, v178
	v_cmp_ge_i32_e64 s[4:5], v85, v84
	s_and_b64 vcc, vcc, s[4:5]
	v_add_u32_e32 v85, 0x72, v83
	v_cndmask_b32_e32 v59, v200, v59, vcc
	v_cmp_le_u32_e32 vcc, v85, v178
	v_cmp_ge_i32_e64 s[4:5], v85, v84
	s_and_b64 vcc, vcc, s[4:5]
	v_add_u32_e32 v85, 0x73, v83
	v_cndmask_b32_e32 v60, v200, v60, vcc
	v_cmp_le_u32_e32 vcc, v85, v178
	v_cmp_ge_i32_e64 s[4:5], v85, v84
	s_and_b64 vcc, vcc, s[4:5]
	v_add_u32_e32 v85, 0x78, v83
	v_cndmask_b32_e32 v61, v200, v61, vcc
	v_cmp_le_u32_e32 vcc, v85, v178
	v_cmp_ge_i32_e64 s[4:5], v85, v84
	s_and_b64 vcc, vcc, s[4:5]
	v_add_u32_e32 v85, 0x79, v83
	v_cndmask_b32_e32 v62, v200, v62, vcc
	v_cmp_le_u32_e32 vcc, v85, v178
	v_cmp_ge_i32_e64 s[4:5], v85, v84
	s_and_b64 vcc, vcc, s[4:5]
	v_add_u32_e32 v85, 0x7a, v83
	v_cndmask_b32_e32 v63, v200, v63, vcc
; __device__ __forceinline__ int crow(int r, int hi) { return (r & 3) + 8 * (r >> 2) + 4 * hi; }
; __device__ __forceinline__ int crow(int r, int hi) { return (r & 3) + 8 * (r >> 2) + 4 * hi; }
; __device__ __forceinline__ void dil_tile(const bf16* __restrict__ P, bf16* MIX, float* LSE, int T, LAS char* vimg, int lane) {
;     ...
;     for (int kt = 0; kt < 5; ++kt)
; #pragma unroll
;         for (int g = 0; g < 16; ++g) { const int key = j0 + 32 * kt + crow(g, hi); const bool ok = (key >= 0) && (key <= iq) && (key >= iq - 128); const float v = ok ? S[kt][g] : -INFINITY; S[kt][g] = v; mx = fmaxf(mx, v); }
;     mx = fmaxf(mx, __shfl_xor(mx, 32));
	v_cmp_le_u32_e32 vcc, v85, v178
	v_cmp_ge_i32_e64 s[4:5], v85, v84
	s_and_b64 vcc, vcc, s[4:5]
	v_add_u32_e32 v85, 0x7b, v83
	v_cndmask_b32_e32 v64, v200, v64, vcc
	v_cmp_le_u32_e32 vcc, v85, v178
	v_cmp_ge_i32_e64 s[4:5], v85, v84
	s_and_b64 vcc, vcc, s[4:5]
	v_add_u32_e32 v82, s25, v82
	v_cndmask_b32_e32 v65, v200, v65, vcc
	v_cmp_le_u32_e32 vcc, v82, v178
	v_cmp_ge_i32_e64 s[4:5], v82, v84
	v_max3_f32 v11, v11, v12, v13
	s_and_b64 vcc, vcc, s[4:5]
	v_or_b32_e32 v85, 1, v82
	v_max3_f32 v11, v11, v14, v15
	v_cndmask_b32_e32 v66, v200, v66, vcc
	v_cmp_lt_u32_e32 vcc, v82, v178
	v_cmp_ge_i32_e64 s[4:5], v85, v84
	v_max3_f32 v11, v11, v16, v17
	s_and_b64 vcc, vcc, s[4:5]
	v_or_b32_e32 v85, 2, v82
	v_max3_f32 v11, v11, v18, v19
	v_cndmask_b32_e32 v67, v200, v67, vcc
	v_cmp_le_u32_e32 vcc, v85, v178
	v_cmp_ge_i32_e64 s[4:5], v85, v84
	v_max3_f32 v11, v11, v20, v21
	s_and_b64 vcc, vcc, s[4:5]
	v_or_b32_e32 v85, 3, v82
	v_max3_f32 v11, v11, v22, v23
	v_cndmask_b32_e32 v68, v200, v68, vcc
	v_cmp_le_u32_e32 vcc, v85, v178
	v_cmp_ge_i32_e64 s[4:5], v85, v84
	v_max3_f32 v11, v11, v24, v25
	s_and_b64 vcc, vcc, s[4:5]
	v_add_u32_e32 v85, 0x88, v83
	v_max3_f32 v11, v11, v26, v27
	v_cndmask_b32_e32 v69, v200, v69, vcc
	v_cmp_le_u32_e32 vcc, v85, v178
	v_cmp_ge_i32_e64 s[4:5], v85, v84
	v_max3_f32 v11, v11, v28, v29
	s_and_b64 vcc, vcc, s[4:5]
	v_max3_f32 v11, v11, v30, v31
	v_cndmask_b32_e32 v87, v200, v70, vcc
	v_add_u32_e32 v70, 9, v82
	v_max3_f32 v11, v11, v32, v33
	v_cmp_le_u32_e32 vcc, v70, v178
	v_cmp_ge_i32_e64 s[4:5], v70, v84
	v_max3_f32 v11, v11, v34, v35
	s_and_b64 vcc, vcc, s[4:5]
	v_add_u32_e32 v70, 10, v82
	v_max3_f32 v11, v11, v36, v37
	v_cndmask_b32_e32 v88, v200, v71, vcc
	v_cmp_le_u32_e32 vcc, v70, v178
	v_cmp_ge_i32_e64 s[4:5], v70, v84
	v_max3_f32 v11, v11, v38, v39
	s_and_b64 vcc, vcc, s[4:5]
	v_add_u32_e32 v70, 11, v82
	v_max3_f32 v11, v11, v40, v41
	v_cndmask_b32_e32 v89, v200, v72, vcc
	v_cmp_le_u32_e32 vcc, v70, v178
	v_cmp_ge_i32_e64 s[4:5], v70, v84
	v_max3_f32 v11, v11, v42, v43
	s_and_b64 vcc, vcc, s[4:5]
	v_add_u32_e32 v70, 0x90, v83
	v_max3_f32 v11, v11, v44, v45
	v_cndmask_b32_e32 v98, v200, v73, vcc
	v_cmp_le_u32_e32 vcc, v70, v178
	v_cmp_ge_i32_e64 s[4:5], v70, v84
	v_max3_f32 v11, v11, v46, v47
	s_and_b64 vcc, vcc, s[4:5]
	v_add_u32_e32 v70, 17, v82
	v_max3_f32 v11, v11, v48, v49
	v_cndmask_b32_e32 v74, v200, v74, vcc
	v_cmp_le_u32_e32 vcc, v70, v178
	v_cmp_ge_i32_e64 s[4:5], v70, v84
	v_max3_f32 v11, v11, v50, v51
	s_and_b64 vcc, vcc, s[4:5]
	v_add_u32_e32 v70, 18, v82
	v_max3_f32 v11, v11, v52, v53
	v_cndmask_b32_e32 v75, v200, v75, vcc
	v_cmp_le_u32_e32 vcc, v70, v178
	v_cmp_ge_i32_e64 s[4:5], v70, v84
	v_max3_f32 v11, v11, v54, v55
	s_and_b64 vcc, vcc, s[4:5]
	v_add_u32_e32 v70, 19, v82
	v_max3_f32 v11, v11, v56, v57
	v_cndmask_b32_e32 v76, v200, v76, vcc
	v_cmp_le_u32_e32 vcc, v70, v178
	v_cmp_ge_i32_e64 s[4:5], v70, v84
	v_max3_f32 v11, v11, v58, v59
	s_and_b64 vcc, vcc, s[4:5]
	v_add_u32_e32 v70, 0x98, v83
	v_max3_f32 v11, v11, v60, v61
	v_cndmask_b32_e32 v77, v200, v77, vcc
	v_cmp_le_u32_e32 vcc, v70, v178
	v_cmp_ge_i32_e64 s[4:5], v70, v84
	v_max3_f32 v11, v11, v62, v63
	s_and_b64 vcc, vcc, s[4:5]
	v_add_u32_e32 v70, 25, v82
	v_max3_f32 v11, v11, v64, v65
	v_cndmask_b32_e32 v78, v200, v78, vcc
	v_cmp_le_u32_e32 vcc, v70, v178
	v_cmp_ge_i32_e64 s[4:5], v70, v84
	v_max3_f32 v11, v11, v66, v67
	s_and_b64 vcc, vcc, s[4:5]
	v_add_u32_e32 v70, 26, v82
	v_max3_f32 v11, v11, v68, v69
	v_cndmask_b32_e32 v79, v200, v79, vcc
	v_cmp_le_u32_e32 vcc, v70, v178
	v_cmp_ge_i32_e64 s[4:5], v70, v84
	v_max3_f32 v11, v11, v87, v88
	s_and_b64 vcc, vcc, s[4:5]
	v_add_u32_e32 v70, 27, v82
	v_max3_f32 v11, v11, v89, v98
	v_cndmask_b32_e32 v80, v200, v80, vcc
	v_cmp_le_u32_e32 vcc, v70, v178
	v_cmp_ge_i32_e64 s[4:5], v70, v84
	v_and_b32_e32 v71, 64, v197
	v_max3_f32 v11, v11, v74, v75
	s_and_b64 vcc, vcc, s[4:5]
	v_xor_b32_e32 v70, 32, v197
	v_add_u32_e32 v71, 64, v71
	v_max3_f32 v11, v11, v76, v77
	v_cndmask_b32_e32 v81, v200, v81, vcc
	v_cmp_lt_i32_e32 vcc, v70, v71
	v_max3_f32 v11, v11, v78, v79
	v_max3_f32 v11, v11, v80, v81
	v_cndmask_b32_e32 v70, v197, v70, vcc
	v_lshlrev_b32_e32 v99, 2, v70
	ds_bpermute_b32 v70, v99, v11
	v_cmp_gt_u32_e32 vcc, 32, v151
	s_waitcnt lgkmcnt(0)
; __device__ __forceinline__ void dil_tile(const bf16* __restrict__ P, bf16* MIX, float* LSE, int T, LAS char* vimg, int lane) {
;     ...
;     mx = fmaxf(mx, __shfl_xor(mx, 32));
;     float l = 0.f;
; #pragma unroll
;     for (int kt = 0; kt < 5; ++kt)
; #pragma unroll
;         for (int g = 0; g < 16; ++g) { const float p = __builtin_amdgcn_exp2f(S[kt][g] - mx); S[kt][g] = p; l += p; }
;     l += __shfl_xor(l, 32);
	v_max_f32_e32 v70, v70, v70
	v_max_f32_e32 v11, v11, v70
	v_sub_f32_e32 v2, v2, v11
	v_exp_f32_e32 v2, v2
	v_sub_f32_e32 v3, v3, v11
	v_exp_f32_e32 v3, v3
	v_sub_f32_e32 v4, v4, v11
	v_exp_f32_e32 v4, v4
	v_sub_f32_e32 v5, v5, v11
	v_exp_f32_e32 v5, v5
	v_sub_f32_e32 v6, v6, v11
	v_add_f32_e32 v70, 0, v2
	v_exp_f32_e32 v6, v6
	v_sub_f32_e32 v7, v7, v11
	v_add_f32_e32 v70, v3, v70
	v_exp_f32_e32 v7, v7
	v_sub_f32_e32 v8, v8, v11
	v_add_f32_e32 v70, v4, v70
	v_exp_f32_e32 v8, v8
	v_sub_f32_e32 v9, v9, v11
	v_add_f32_e32 v70, v5, v70
	v_exp_f32_e32 v9, v9
	v_add_f32_e32 v70, v6, v70
	v_add_f32_e32 v70, v7, v70
	v_add_f32_e32 v70, v8, v70
	v_sub_f32_e32 v10, v10, v11
	v_add_f32_e32 v82, v9, v70
	v_exp_f32_e32 v70, v10
	v_sub_f32_e32 v10, v86, v11
	v_exp_f32_e32 v71, v10
	v_sub_f32_e32 v10, v12, v11
	v_exp_f32_e32 v72, v10
	v_sub_f32_e32 v10, v13, v11
	v_exp_f32_e32 v73, v10
	v_sub_f32_e32 v12, v14, v11
	v_add_f32_e32 v10, v70, v82
	v_exp_f32_e32 v144, v12
	v_sub_f32_e32 v12, v15, v11
	v_add_f32_e32 v10, v71, v10
	v_exp_f32_e32 v145, v12
	v_sub_f32_e32 v12, v16, v11
	v_add_f32_e32 v10, v72, v10
	v_exp_f32_e32 v146, v12
	v_sub_f32_e32 v12, v17, v11
	v_add_f32_e32 v10, v73, v10
	v_exp_f32_e32 v147, v12
	v_sub_f32_e32 v12, v18, v11
	v_add_f32_e32 v10, v144, v10
	v_exp_f32_e32 v136, v12
	v_sub_f32_e32 v12, v19, v11
	v_add_f32_e32 v10, v145, v10
	v_exp_f32_e32 v137, v12
	v_sub_f32_e32 v12, v20, v11
	v_add_f32_e32 v10, v146, v10
	v_exp_f32_e32 v138, v12
	v_sub_f32_e32 v12, v21, v11
	v_add_f32_e32 v10, v147, v10
	v_exp_f32_e32 v139, v12
	v_sub_f32_e32 v12, v22, v11
	v_add_f32_e32 v10, v136, v10
	v_exp_f32_e32 v140, v12
	v_sub_f32_e32 v12, v23, v11
	v_add_f32_e32 v10, v137, v10
	v_exp_f32_e32 v141, v12
	v_sub_f32_e32 v12, v24, v11
	v_add_f32_e32 v10, v138, v10
	v_exp_f32_e32 v142, v12
	v_sub_f32_e32 v12, v25, v11
	v_add_f32_e32 v10, v139, v10
	v_exp_f32_e32 v143, v12
	v_sub_f32_e32 v12, v26, v11
	v_add_f32_e32 v10, v140, v10
	v_exp_f32_e32 v128, v12
	v_sub_f32_e32 v12, v27, v11
	v_add_f32_e32 v10, v141, v10
	v_exp_f32_e32 v129, v12
	v_sub_f32_e32 v12, v28, v11
	v_add_f32_e32 v10, v142, v10
	v_exp_f32_e32 v130, v12
	v_sub_f32_e32 v12, v29, v11
	v_add_f32_e32 v10, v143, v10
	v_exp_f32_e32 v131, v12
	v_sub_f32_e32 v12, v30, v11
	v_add_f32_e32 v10, v128, v10
	v_exp_f32_e32 v132, v12
	v_sub_f32_e32 v12, v31, v11
	v_add_f32_e32 v10, v129, v10
	v_exp_f32_e32 v133, v12
	v_sub_f32_e32 v12, v32, v11
	v_add_f32_e32 v10, v130, v10
	v_exp_f32_e32 v134, v12
	v_sub_f32_e32 v12, v33, v11
	v_add_f32_e32 v10, v131, v10
	v_exp_f32_e32 v135, v12
	v_sub_f32_e32 v12, v34, v11
	v_add_f32_e32 v10, v132, v10
	v_exp_f32_e32 v120, v12
	v_sub_f32_e32 v12, v35, v11
	v_add_f32_e32 v10, v133, v10
	v_exp_f32_e32 v121, v12
	v_sub_f32_e32 v12, v36, v11
	v_add_f32_e32 v10, v134, v10
	v_exp_f32_e32 v122, v12
	v_sub_f32_e32 v12, v37, v11
	v_add_f32_e32 v10, v135, v10
	v_exp_f32_e32 v123, v12
	v_sub_f32_e32 v12, v38, v11
	v_add_f32_e32 v10, v120, v10
	v_exp_f32_e32 v124, v12
	v_sub_f32_e32 v12, v39, v11
	v_add_f32_e32 v10, v121, v10
	v_exp_f32_e32 v125, v12
	v_sub_f32_e32 v12, v40, v11
	v_add_f32_e32 v10, v122, v10
	v_exp_f32_e32 v126, v12
	v_sub_f32_e32 v12, v41, v11
	v_add_f32_e32 v10, v123, v10
	v_exp_f32_e32 v127, v12
	v_sub_f32_e32 v12, v42, v11
	v_add_f32_e32 v10, v124, v10
	v_exp_f32_e32 v112, v12
	v_sub_f32_e32 v12, v43, v11
	v_add_f32_e32 v10, v125, v10
	v_exp_f32_e32 v113, v12
	v_sub_f32_e32 v12, v44, v11
	v_add_f32_e32 v10, v126, v10
	v_exp_f32_e32 v114, v12
	v_sub_f32_e32 v12, v45, v11
	v_add_f32_e32 v10, v127, v10
	v_exp_f32_e32 v115, v12
	v_sub_f32_e32 v12, v46, v11
	v_add_f32_e32 v10, v112, v10
	v_exp_f32_e32 v116, v12
	v_sub_f32_e32 v12, v47, v11
	v_add_f32_e32 v10, v113, v10
	v_exp_f32_e32 v117, v12
	v_sub_f32_e32 v12, v48, v11
	v_add_f32_e32 v10, v114, v10
	v_exp_f32_e32 v118, v12
	v_sub_f32_e32 v12, v49, v11
	v_add_f32_e32 v10, v115, v10
	v_exp_f32_e32 v119, v12
	v_sub_f32_e32 v12, v50, v11
	v_add_f32_e32 v10, v116, v10
	v_exp_f32_e32 v102, v12
	v_sub_f32_e32 v12, v51, v11
	v_add_f32_e32 v10, v117, v10
	v_exp_f32_e32 v103, v12
	v_sub_f32_e32 v12, v52, v11
	v_add_f32_e32 v10, v118, v10
	v_exp_f32_e32 v104, v12
	v_sub_f32_e32 v12, v53, v11
	v_add_f32_e32 v10, v119, v10
	v_exp_f32_e32 v105, v12
	v_sub_f32_e32 v12, v54, v11
	v_add_f32_e32 v10, v102, v10
	v_exp_f32_e32 v106, v12
	v_sub_f32_e32 v12, v55, v11
	v_add_f32_e32 v10, v103, v10
	v_exp_f32_e32 v107, v12
	v_sub_f32_e32 v12, v56, v11
	v_add_f32_e32 v10, v104, v10
	v_exp_f32_e32 v108, v12
	v_sub_f32_e32 v12, v57, v11
	v_add_f32_e32 v10, v105, v10
	v_exp_f32_e32 v109, v12
	v_sub_f32_e32 v12, v58, v11
	v_add_f32_e32 v10, v106, v10
	v_exp_f32_e32 v90, v12
	v_sub_f32_e32 v12, v59, v11
	v_add_f32_e32 v10, v107, v10
	v_exp_f32_e32 v91, v12
	v_sub_f32_e32 v12, v60, v11
	v_add_f32_e32 v10, v108, v10
	v_exp_f32_e32 v92, v12
	v_sub_f32_e32 v12, v61, v11
	v_add_f32_e32 v10, v109, v10
	v_exp_f32_e32 v93, v12
	v_sub_f32_e32 v12, v62, v11
	v_add_f32_e32 v10, v90, v10
	v_exp_f32_e32 v94, v12
	v_sub_f32_e32 v12, v63, v11
	v_add_f32_e32 v10, v91, v10
	v_exp_f32_e32 v95, v12
	v_sub_f32_e32 v12, v64, v11
	v_add_f32_e32 v10, v92, v10
	v_exp_f32_e32 v96, v12
	v_sub_f32_e32 v12, v65, v11
	v_add_f32_e32 v10, v93, v10
	v_exp_f32_e32 v97, v12
	v_sub_f32_e32 v12, v66, v11
	v_add_f32_e32 v10, v94, v10
	v_exp_f32_e32 v82, v12
	v_sub_f32_e32 v12, v67, v11
	v_add_f32_e32 v10, v95, v10
	v_exp_f32_e32 v83, v12
	v_sub_f32_e32 v12, v68, v11
	v_add_f32_e32 v10, v96, v10
	v_exp_f32_e32 v84, v12
	v_sub_f32_e32 v12, v69, v11
	v_add_f32_e32 v10, v97, v10
	v_exp_f32_e32 v85, v12
	v_sub_f32_e32 v12, v87, v11
	v_add_f32_e32 v10, v82, v10
	v_exp_f32_e32 v86, v12
	v_sub_f32_e32 v12, v88, v11
	v_add_f32_e32 v10, v83, v10
	v_exp_f32_e32 v87, v12
	v_sub_f32_e32 v12, v89, v11
	v_add_f32_e32 v10, v84, v10
	v_exp_f32_e32 v88, v12
	v_sub_f32_e32 v12, v98, v11
	v_add_f32_e32 v10, v85, v10
	v_exp_f32_e32 v89, v12
	v_sub_f32_e32 v12, v74, v11
	v_add_f32_e32 v10, v86, v10
	v_exp_f32_e32 v74, v12
	v_sub_f32_e32 v12, v75, v11
	v_add_f32_e32 v10, v87, v10
	v_exp_f32_e32 v75, v12
	v_sub_f32_e32 v12, v76, v11
	v_add_f32_e32 v10, v88, v10
	v_exp_f32_e32 v76, v12
	v_sub_f32_e32 v12, v77, v11
	v_add_f32_e32 v10, v89, v10
	v_exp_f32_e32 v77, v12
	v_sub_f32_e32 v12, v78, v11
	v_add_f32_e32 v10, v74, v10
	v_exp_f32_e32 v78, v12
	v_sub_f32_e32 v12, v79, v11
	v_add_f32_e32 v10, v75, v10
	v_exp_f32_e32 v79, v12
	v_sub_f32_e32 v12, v80, v11
	v_add_f32_e32 v10, v76, v10
	v_exp_f32_e32 v80, v12
	v_sub_f32_e32 v12, v81, v11
	v_add_f32_e32 v10, v77, v10
	v_exp_f32_e32 v81, v12
	v_add_f32_e32 v10, v78, v10
	v_add_f32_e32 v10, v79, v10
	v_add_f32_e32 v10, v80, v10
	v_add_f32_e32 v10, v81, v10
	ds_bpermute_b32 v12, v99, v10
	s_waitcnt lgkmcnt(0)
	v_add_f32_e32 v10, v10, v12
	s_and_saveexec_b64 s[4:5], vcc
	s_cbranch_execz .LBB0_399
; __device__ __forceinline__ void dil_tile(const bf16* __restrict__ P, bf16* MIX, float* LSE, int T, LAS char* vimg, int lane) {
;     ...
;     l += __shfl_xor(l, 32);
;     if (hi == 0) LSE[(row0 + ((size_t)iq << dsh)) * 16 + head] = mx + __builtin_amdgcn_logf(l);
	v_log_f32_e32 v14, v10
	v_lshlrev_b64 v[12:13], 6, v[110:111]
	s_ashr_i32 s19, s18, 31
	v_lshl_add_u64 v[12:13], s[10:11], 0, v[12:13]
	v_add_f32_e32 v11, v11, v14
	v_lshl_add_u64 v[12:13], s[18:19], 2, v[12:13]
	global_store_dword v[12:13], v11, off
	s_branch .LBB0_399

; #define PG8_STAGE(bufoff, gbase, voff) do { _Pragma("unroll") for (int _i = 0; _i < 2; ++_i) \
;         __builtin_amdgcn_global_load_lds((const unsigned*)((const char*)(gbase) + (voff)[_i]), (PG8_LAS unsigned*)(lds + (bufoff) + ldsw + _i * 8192), 16, 0, 0); } while (0)
; #define PG8_LDA(dst, b, h) do { _Pragma("unroll") for (int m = 0; m < 4; ++m) _Pragma("unroll") for (int k = 0; k < 2; ++k) dst[m][k] = *(const PG8_LAS bf16x8*)(lds + PG8_SA(b, h) + aoff + m * 2048 + k * 1024); } while (0)
; #define PG8_LDB(dst, b, h) do { _Pragma("unroll") for (int n = 0; n < 2; ++n) _Pragma("unroll") for (int k = 0; k < 2; ++k) dst[n][k] = *(const PG8_LAS bf16x8*)(lds + PG8_SB(b, h) + boff + n * 2048 + k * 1024); } while (0)
; #define PG8_MMA(ai, bj, At, Bt) do { __builtin_amdgcn_s_setprio(1); _Pragma("unroll") for (int m = 0; m < 4; ++m) _Pragma("unroll") for (int n = 0; n < 2; ++n) _Pragma("unroll") for (int k = 0; k < 2; ++k) \
;         acc[ai][bj][m][n] = __builtin_amdgcn_mfma_f32_16x16x32_bf16(Bt[n][k], At[m][k], acc[ai][bj][m][n], 0, 0, 0); __builtin_amdgcn_s_setprio(0); } while (0)
; #define PG8_WAIT_V(n) asm volatile("s_waitcnt vmcnt(" #n ")" ::: "memory")
; template <class Epi, class Sched, bool ALIGN_EPI, int LMASK = -1, int LMASKB = LMASK>
; __device__ __forceinline__ void gemm_phase(PG8_LAS unsigned char* lds, const Gemm g, const Sched& S, const Epi& E) {
;     ...
;         const char* nA = has_next ? (const char*)g.A + (size_t)(nxt.pm & LMASK) * tstepA : cA; const char* nB = has_next ? (const char*)g.Bt + (size_t)nxt.pm * g.b_pm_stride + (size_t)(nxt.pn & LMASKB) * tstepB : cB;
;         for (int t = 0; t < nt; t += 2) {
;             const bool last = (t == nt - 2);
;             const char* a1 = cA + (size_t)(t + 1) * kstepA;
;             const char* a2 = last ? nA : cA + (size_t)(t + 2) * kstepA; const char* b2 = last ? nB : cB + (size_t)(t + 2) * kstepB;
;             const char* a3 = a2 + kstepA; const char* b3 = b2 + kstepB;
;             PG8_LDB(B0, 0, 0); PG8_LDB(B1, 0, 1); PG8_SCHED; PG8_LDA(At, 0, 0); PG8_STAGE(PG8_SA(1, 1), a1 + hstepA, voffA);
;             PG8_WAIT_V(8); PG8_WAIT_L(0); PG8_BAR; PG8_MMA(0, 0, At, B0); PG8_MMA(0, 1, At, B1); PG8_BAR; PG8_SCHED;
;             PG8_LDA(At, 0, 1); PG8_STAGE(PG8_SB(0, 0), b2, voffB); PG8_STAGE(PG8_SB(0, 1), b2 + hstepB, voffB); PG8_STAGE(PG8_SA(0, 0), a2, voffA);
.LBB0_580:
	s_add_u32 s30, s28, 0xfff00800
	s_addc_u32 s31, s29, -1
	s_add_i32 s51, 0, 0x10000
	s_cmp_eq_u32 s50, 60
	s_cselect_b32 s35, s19, s31
	s_cselect_b32 s34, s25, s30
	v_add_u32_e32 v146, s51, v149
	s_cselect_b32 s31, s17, s49
	s_cselect_b32 s30, s47, s48
	s_add_i32 s54, 0, 0x14000
	ds_read_b128 v[130:133], v146
	ds_read_b128 v[142:145], v146 offset:1024
	ds_read_b128 v[152:155], v146 offset:2048
	ds_read_b128 v[156:159], v146 offset:3072
	v_add_u32_e32 v146, s54, v149
	ds_read_b128 v[160:163], v146
	ds_read_b128 v[164:167], v146 offset:1024
	ds_read_b128 v[168:171], v146 offset:2048
	ds_read_b128 v[172:175], v146 offset:3072
	v_lshl_add_u64 v[146:147], s[28:29], 0, v[138:139]
	s_add_i32 m0, s27, 0xc000
	ds_read_b128 v[188:191], v151
	ds_read_b128 v[206:209], v151 offset:1024
	ds_read_b128 v[218:221], v151 offset:2048
	ds_read_b128 v[222:225], v151 offset:3072
	ds_read_b128 v[226:229], v151 offset:4096
	ds_read_b128 v[230:233], v151 offset:5120
	ds_read_b128 v[234:237], v151 offset:6144
	ds_read_b128 v[238:241], v151 offset:7168
	global_load_lds_dwordx4 v[146:147], off
	s_add_i32 m0, s27, 0xe000
	v_lshl_add_u64 v[146:147], s[28:29], 0, v[140:141]
	global_load_lds_dwordx4 v[146:147], off
	s_waitcnt vmcnt(8)
	s_waitcnt lgkmcnt(0)
	s_setprio 1
	s_barrier
	v_mfma_f32_16x16x32_bf16 v[126:129], v[130:133], v[188:191], v[126:129]
	v_mfma_f32_16x16x32_bf16 v[122:125], v[152:155], v[188:191], v[122:125]
	v_mfma_f32_16x16x32_bf16 v[110:113], v[130:133], v[218:221], v[110:113]
	v_mfma_f32_16x16x32_bf16 v[106:109], v[152:155], v[218:221], v[106:109]
	v_mfma_f32_16x16x32_bf16 v[94:97], v[130:133], v[226:229], v[94:97]
	v_mfma_f32_16x16x32_bf16 v[90:93], v[152:155], v[226:229], v[90:93]
	v_mfma_f32_16x16x32_bf16 v[78:81], v[130:133], v[234:237], v[78:81]
	v_mfma_f32_16x16x32_bf16 v[74:77], v[152:155], v[234:237], v[74:77]
	v_mfma_f32_16x16x32_bf16 v[126:129], v[142:145], v[206:209], v[126:129]
	v_mfma_f32_16x16x32_bf16 v[122:125], v[156:159], v[206:209], v[122:125]
	v_mfma_f32_16x16x32_bf16 v[110:113], v[142:145], v[222:225], v[110:113]
	v_mfma_f32_16x16x32_bf16 v[106:109], v[156:159], v[222:225], v[106:109]
	v_mfma_f32_16x16x32_bf16 v[94:97], v[142:145], v[230:233], v[94:97]
	v_mfma_f32_16x16x32_bf16 v[90:93], v[156:159], v[230:233], v[90:93]
	v_mfma_f32_16x16x32_bf16 v[78:81], v[142:145], v[238:241], v[78:81]
	v_mfma_f32_16x16x32_bf16 v[74:77], v[156:159], v[238:241], v[74:77]
	v_mfma_f32_16x16x32_bf16 v[118:121], v[160:163], v[188:191], v[118:121]
	v_mfma_f32_16x16x32_bf16 v[114:117], v[168:171], v[188:191], v[114:117]
	v_mfma_f32_16x16x32_bf16 v[102:105], v[160:163], v[218:221], v[102:105]
	v_mfma_f32_16x16x32_bf16 v[98:101], v[168:171], v[218:221], v[98:101]
	v_mfma_f32_16x16x32_bf16 v[86:89], v[160:163], v[226:229], v[86:89]
	v_mfma_f32_16x16x32_bf16 v[82:85], v[168:171], v[226:229], v[82:85]
	v_mfma_f32_16x16x32_bf16 v[70:73], v[160:163], v[234:237], v[70:73]
	v_mfma_f32_16x16x32_bf16 v[66:69], v[168:171], v[234:237], v[66:69]
	v_mfma_f32_16x16x32_bf16 v[118:121], v[164:167], v[206:209], v[118:121]
	v_mfma_f32_16x16x32_bf16 v[114:117], v[172:175], v[206:209], v[114:117]
	v_mfma_f32_16x16x32_bf16 v[102:105], v[164:167], v[222:225], v[102:105]
	v_mfma_f32_16x16x32_bf16 v[98:101], v[172:175], v[222:225], v[98:101]
	v_mfma_f32_16x16x32_bf16 v[86:89], v[164:167], v[230:233], v[86:89]
	v_mfma_f32_16x16x32_bf16 v[82:85], v[172:175], v[230:233], v[82:85]
	v_mfma_f32_16x16x32_bf16 v[70:73], v[164:167], v[238:241], v[70:73]
	v_mfma_f32_16x16x32_bf16 v[66:69], v[172:175], v[238:241], v[66:69]
	s_barrier
	s_setprio 0
	s_add_i32 s51, s51, s38
	v_lshl_add_u64 v[146:147], s[30:31], 0, v[134:135]
	s_mov_b32 m0, s51
	ds_read_b128 v[188:191], v151 offset:16384
	ds_read_b128 v[206:209], v151 offset:17408
	ds_read_b128 v[218:221], v151 offset:18432
	ds_read_b128 v[222:225], v151 offset:19456
	ds_read_b128 v[226:229], v151 offset:20480
	ds_read_b128 v[230:233], v151 offset:21504
	ds_read_b128 v[234:237], v151 offset:22528
	ds_read_b128 v[238:241], v151 offset:23552
	global_load_lds_dwordx4 v[146:147], off
	s_add_i32 m0, s51, 0x2000
	s_add_u32 s52, s30, 0x100000
	v_lshl_add_u64 v[176:177], s[30:31], 0, v[136:137]
	s_addc_u32 s53, s31, 0
	s_add_i32 s51, s54, s38
	global_load_lds_dwordx4 v[176:177], off
	v_lshl_add_u64 v[194:195], s[52:53], 0, v[134:135]
	s_mov_b32 m0, s51
	v_lshl_add_u64 v[210:211], s[34:35], 0, v[136:137]
	global_load_lds_dwordx4 v[194:195], off
	s_add_i32 m0, s51, 0x2000
	v_lshl_add_u64 v[194:195], s[52:53], 0, v[136:137]
	global_load_lds_dwordx4 v[194:195], off
	s_mov_b32 m0, s27
	v_lshl_add_u64 v[194:195], s[34:35], 0, v[134:135]
	global_load_lds_dwordx4 v[194:195], off
	s_mov_b32 m0, s39
	s_nop 0
	global_load_lds_dwordx4 v[210:211], off
	s_waitcnt vmcnt(8)
	s_waitcnt lgkmcnt(0)
	s_setprio 1
	s_barrier
; #define PG8_STAGE(bufoff, gbase, voff) do { _Pragma("unroll") for (int _i = 0; _i < 2; ++_i) \
;         __builtin_amdgcn_global_load_lds((const unsigned*)((const char*)(gbase) + (voff)[_i]), (PG8_LAS unsigned*)(lds + (bufoff) + ldsw + _i * 8192), 16, 0, 0); } while (0)
; #define PG8_LDA(dst, b, h) do { _Pragma("unroll") for (int m = 0; m < 4; ++m) _Pragma("unroll") for (int k = 0; k < 2; ++k) dst[m][k] = *(const PG8_LAS bf16x8*)(lds + PG8_SA(b, h) + aoff + m * 2048 + k * 1024); } while (0)
; #define PG8_LDB(dst, b, h) do { _Pragma("unroll") for (int n = 0; n < 2; ++n) _Pragma("unroll") for (int k = 0; k < 2; ++k) dst[n][k] = *(const PG8_LAS bf16x8*)(lds + PG8_SB(b, h) + boff + n * 2048 + k * 1024); } while (0)
; #define PG8_MMA(ai, bj, At, Bt) do { __builtin_amdgcn_s_setprio(1); _Pragma("unroll") for (int m = 0; m < 4; ++m) _Pragma("unroll") for (int n = 0; n < 2; ++n) _Pragma("unroll") for (int k = 0; k < 2; ++k) \
;         acc[ai][bj][m][n] = __builtin_amdgcn_mfma_f32_16x16x32_bf16(Bt[n][k], At[m][k], acc[ai][bj][m][n], 0, 0, 0); __builtin_amdgcn_s_setprio(0); } while (0)
; #define PG8_WAIT_V(n) asm volatile("s_waitcnt vmcnt(" #n ")" ::: "memory")
; #define PG8_WAIT_L(n) asm volatile("s_waitcnt lgkmcnt(" #n ")" ::: "memory")
; #define PG8_BAR __builtin_amdgcn_s_barrier()
; #define PG8_SCHED __builtin_amdgcn_sched_barrier(0)
; template <class Epi, class Sched, bool ALIGN_EPI, int LMASK = -1, int LMASKB = LMASK>
; __device__ __forceinline__ void gemm_phase(PG8_LAS unsigned char* lds, const Gemm g, const Sched& S, const Epi& E) {
;     ...
;             PG8_WAIT_V(8); PG8_WAIT_L(0); PG8_BAR; PG8_MMA(0, 0, At, B0); PG8_MMA(0, 1, At, B1); PG8_BAR; PG8_SCHED;
;             PG8_LDA(At, 0, 1); PG8_STAGE(PG8_SB(0, 0), b2, voffB); PG8_STAGE(PG8_SB(0, 1), b2 + hstepB, voffB); PG8_STAGE(PG8_SA(0, 0), a2, voffA);
;             PG8_WAIT_V(8); PG8_WAIT_L(0); PG8_BAR; PG8_MMA(1, 0, At, B0); PG8_MMA(1, 1, At, B1); PG8_BAR; PG8_SCHED;
;             PG8_LDB(B0, 1, 0); PG8_LDB(B1, 1, 1); PG8_SCHED; PG8_LDA(At, 1, 0); PG8_STAGE(PG8_SA(0, 1), a2 + hstepA, voffA);
;             PG8_WAIT_V(8); PG8_WAIT_L(0); PG8_BAR; PG8_MMA(0, 0, At, B0); PG8_MMA(0, 1, At, B1); PG8_BAR; PG8_SCHED;
	v_mfma_f32_16x16x32_bf16 v[62:65], v[130:133], v[188:191], v[62:65]
	v_mfma_f32_16x16x32_bf16 v[58:61], v[152:155], v[188:191], v[58:61]
	v_mfma_f32_16x16x32_bf16 v[46:49], v[130:133], v[218:221], v[46:49]
	v_mfma_f32_16x16x32_bf16 v[42:45], v[152:155], v[218:221], v[42:45]
	v_mfma_f32_16x16x32_bf16 v[30:33], v[130:133], v[226:229], v[30:33]
	v_mfma_f32_16x16x32_bf16 v[26:29], v[152:155], v[226:229], v[26:29]
	v_mfma_f32_16x16x32_bf16 v[14:17], v[130:133], v[234:237], v[14:17]
	v_mfma_f32_16x16x32_bf16 v[10:13], v[152:155], v[234:237], v[10:13]
	v_mfma_f32_16x16x32_bf16 v[62:65], v[142:145], v[206:209], v[62:65]
	v_mfma_f32_16x16x32_bf16 v[58:61], v[156:159], v[206:209], v[58:61]
	v_mfma_f32_16x16x32_bf16 v[46:49], v[142:145], v[222:225], v[46:49]
	v_mfma_f32_16x16x32_bf16 v[42:45], v[156:159], v[222:225], v[42:45]
	v_mfma_f32_16x16x32_bf16 v[30:33], v[142:145], v[230:233], v[30:33]
	v_mfma_f32_16x16x32_bf16 v[26:29], v[156:159], v[230:233], v[26:29]
	v_mfma_f32_16x16x32_bf16 v[14:17], v[142:145], v[238:241], v[14:17]
	v_mfma_f32_16x16x32_bf16 v[10:13], v[156:159], v[238:241], v[10:13]
	v_mfma_f32_16x16x32_bf16 v[54:57], v[160:163], v[188:191], v[54:57]
	v_mfma_f32_16x16x32_bf16 v[50:53], v[168:171], v[188:191], v[50:53]
	v_mfma_f32_16x16x32_bf16 v[38:41], v[160:163], v[218:221], v[38:41]
	v_mfma_f32_16x16x32_bf16 v[34:37], v[168:171], v[218:221], v[34:37]
	v_mfma_f32_16x16x32_bf16 v[22:25], v[160:163], v[226:229], v[22:25]
	v_mfma_f32_16x16x32_bf16 v[18:21], v[168:171], v[226:229], v[18:21]
	v_mfma_f32_16x16x32_bf16 v[6:9], v[160:163], v[234:237], v[6:9]
	v_mfma_f32_16x16x32_bf16 v[2:5], v[168:171], v[234:237], v[2:5]
	v_mfma_f32_16x16x32_bf16 v[54:57], v[164:167], v[206:209], v[54:57]
	v_mfma_f32_16x16x32_bf16 v[50:53], v[172:175], v[206:209], v[50:53]
	v_mfma_f32_16x16x32_bf16 v[38:41], v[164:167], v[222:225], v[38:41]
	v_mfma_f32_16x16x32_bf16 v[34:37], v[172:175], v[222:225], v[34:37]
	v_mfma_f32_16x16x32_bf16 v[22:25], v[164:167], v[230:233], v[22:25]
	v_mfma_f32_16x16x32_bf16 v[18:21], v[172:175], v[230:233], v[18:21]
	v_mfma_f32_16x16x32_bf16 v[6:9], v[164:167], v[238:241], v[6:9]
	v_mfma_f32_16x16x32_bf16 v[2:5], v[172:175], v[238:241], v[2:5]
	s_barrier
	s_setprio 0
	s_add_i32 s51, 0, 0x18000
	s_add_i32 s52, 0, 0x1c000
	v_add_u32_e32 v156, s51, v149
	v_add_u32_e32 v172, s52, v149
	ds_read_b128 v[130:133], v156
	ds_read_b128 v[142:145], v156 offset:1024
	ds_read_b128 v[152:155], v156 offset:2048
	ds_read_b128 v[156:159], v156 offset:3072
	ds_read_b128 v[160:163], v172
	ds_read_b128 v[164:167], v172 offset:1024
	ds_read_b128 v[168:171], v172 offset:2048
	ds_read_b128 v[172:175], v172 offset:3072
	s_add_u32 s34, s34, 0x100000
	s_addc_u32 s35, s35, 0
	s_mov_b32 m0, s40
	v_lshl_add_u64 v[212:213], s[34:35], 0, v[134:135]
	ds_read_b128 v[188:191], v151 offset:32768
	ds_read_b128 v[206:209], v151 offset:33792
	ds_read_b128 v[218:221], v151 offset:34816
	ds_read_b128 v[222:225], v151 offset:35840
	ds_read_b128 v[226:229], v151 offset:36864
	ds_read_b128 v[230:233], v151 offset:37888
	ds_read_b128 v[234:237], v151 offset:38912
	ds_read_b128 v[238:241], v151 offset:39936
	global_load_lds_dwordx4 v[212:213], off
	s_mov_b32 m0, s41
	v_lshl_add_u64 v[212:213], s[34:35], 0, v[136:137]
	global_load_lds_dwordx4 v[212:213], off
	s_waitcnt vmcnt(8)
	s_waitcnt lgkmcnt(0)
	s_setprio 1
	s_barrier
	v_mfma_f32_16x16x32_bf16 v[126:129], v[130:133], v[188:191], v[126:129]
	v_mfma_f32_16x16x32_bf16 v[122:125], v[152:155], v[188:191], v[122:125]
	v_mfma_f32_16x16x32_bf16 v[110:113], v[130:133], v[218:221], v[110:113]
	v_mfma_f32_16x16x32_bf16 v[106:109], v[152:155], v[218:221], v[106:109]
	v_mfma_f32_16x16x32_bf16 v[94:97], v[130:133], v[226:229], v[94:97]
	v_mfma_f32_16x16x32_bf16 v[90:93], v[152:155], v[226:229], v[90:93]
	v_mfma_f32_16x16x32_bf16 v[78:81], v[130:133], v[234:237], v[78:81]
	v_mfma_f32_16x16x32_bf16 v[74:77], v[152:155], v[234:237], v[74:77]
	v_mfma_f32_16x16x32_bf16 v[126:129], v[142:145], v[206:209], v[126:129]
	v_mfma_f32_16x16x32_bf16 v[122:125], v[156:159], v[206:209], v[122:125]
	v_mfma_f32_16x16x32_bf16 v[110:113], v[142:145], v[222:225], v[110:113]
	v_mfma_f32_16x16x32_bf16 v[106:109], v[156:159], v[222:225], v[106:109]
	v_mfma_f32_16x16x32_bf16 v[94:97], v[142:145], v[230:233], v[94:97]
	v_mfma_f32_16x16x32_bf16 v[90:93], v[156:159], v[230:233], v[90:93]
	v_mfma_f32_16x16x32_bf16 v[78:81], v[142:145], v[238:241], v[78:81]
	v_mfma_f32_16x16x32_bf16 v[74:77], v[156:159], v[238:241], v[74:77]
	v_mfma_f32_16x16x32_bf16 v[118:121], v[160:163], v[188:191], v[118:121]
	v_mfma_f32_16x16x32_bf16 v[114:117], v[168:171], v[188:191], v[114:117]
	v_mfma_f32_16x16x32_bf16 v[102:105], v[160:163], v[218:221], v[102:105]
	v_mfma_f32_16x16x32_bf16 v[98:101], v[168:171], v[218:221], v[98:101]
	v_mfma_f32_16x16x32_bf16 v[86:89], v[160:163], v[226:229], v[86:89]
	v_mfma_f32_16x16x32_bf16 v[82:85], v[168:171], v[226:229], v[82:85]
	v_mfma_f32_16x16x32_bf16 v[70:73], v[160:163], v[234:237], v[70:73]
	v_mfma_f32_16x16x32_bf16 v[66:69], v[168:171], v[234:237], v[66:69]
	v_mfma_f32_16x16x32_bf16 v[118:121], v[164:167], v[206:209], v[118:121]
	v_mfma_f32_16x16x32_bf16 v[114:117], v[172:175], v[206:209], v[114:117]
	v_mfma_f32_16x16x32_bf16 v[102:105], v[164:167], v[222:225], v[102:105]
	v_mfma_f32_16x16x32_bf16 v[98:101], v[172:175], v[222:225], v[98:101]
	v_mfma_f32_16x16x32_bf16 v[86:89], v[164:167], v[230:233], v[86:89]
	v_mfma_f32_16x16x32_bf16 v[82:85], v[172:175], v[230:233], v[82:85]
	v_mfma_f32_16x16x32_bf16 v[70:73], v[164:167], v[238:241], v[70:73]
	v_mfma_f32_16x16x32_bf16 v[66:69], v[172:175], v[238:241], v[66:69]
	s_barrier
; #define PG8_STAGE(bufoff, gbase, voff) do { _Pragma("unroll") for (int _i = 0; _i < 2; ++_i) \
;         __builtin_amdgcn_global_load_lds((const unsigned*)((const char*)(gbase) + (voff)[_i]), (PG8_LAS unsigned*)(lds + (bufoff) + ldsw + _i * 8192), 16, 0, 0); } while (0)
; #define PG8_LDA(dst, b, h) do { _Pragma("unroll") for (int m = 0; m < 4; ++m) _Pragma("unroll") for (int k = 0; k < 2; ++k) dst[m][k] = *(const PG8_LAS bf16x8*)(lds + PG8_SA(b, h) + aoff + m * 2048 + k * 1024); } while (0)
; #define PG8_MMA(ai, bj, At, Bt) do { __builtin_amdgcn_s_setprio(1); _Pragma("unroll") for (int m = 0; m < 4; ++m) _Pragma("unroll") for (int n = 0; n < 2; ++n) _Pragma("unroll") for (int k = 0; k < 2; ++k) \
;         acc[ai][bj][m][n] = __builtin_amdgcn_mfma_f32_16x16x32_bf16(Bt[n][k], At[m][k], acc[ai][bj][m][n], 0, 0, 0); __builtin_amdgcn_s_setprio(0); } while (0)
; #define PG8_WAIT_V(n) asm volatile("s_waitcnt vmcnt(" #n ")" ::: "memory")
; #define PG8_WAIT_L(n) asm volatile("s_waitcnt lgkmcnt(" #n ")" ::: "memory")
; #define PG8_BAR __builtin_amdgcn_s_barrier()
; #define PG8_SCHED __builtin_amdgcn_sched_barrier(0)
; template <class Epi, class Sched, bool ALIGN_EPI, int LMASK = -1, int LMASKB = LMASK>
; __device__ __forceinline__ void gemm_phase(PG8_LAS unsigned char* lds, const Gemm g, const Sched& S, const Epi& E) {
;     ...
;             PG8_LDA(At, 1, 1); PG8_STAGE(PG8_SB(1, 0), b3, voffB); PG8_STAGE(PG8_SB(1, 1), b3 + hstepB, voffB); PG8_STAGE(PG8_SA(1, 0), a3, voffA);
;             PG8_WAIT_V(8); PG8_WAIT_L(0); PG8_BAR; PG8_MMA(1, 0, At, B0); PG8_MMA(1, 1, At, B1); PG8_BAR; PG8_SCHED;
;         }
	s_setprio 0
	s_add_i32 s34, s51, s38
	v_lshl_add_u64 v[146:147], v[146:147], 0, s[80:81]
	s_mov_b32 m0, s34
	ds_read_b128 v[188:191], v151 offset:49152
	ds_read_b128 v[206:209], v151 offset:50176
	ds_read_b128 v[218:221], v151 offset:51200
	ds_read_b128 v[222:225], v151 offset:52224
	ds_read_b128 v[226:229], v151 offset:53248
	ds_read_b128 v[230:233], v151 offset:54272
	ds_read_b128 v[234:237], v151 offset:55296
	ds_read_b128 v[238:241], v151 offset:56320
	global_load_lds_dwordx4 v[146:147], off
	s_add_i32 m0, s34, 0x2000
	s_add_u32 s30, s30, 0x100800
	v_lshl_add_u64 v[146:147], v[176:177], 0, s[80:81]
	s_addc_u32 s31, s31, 0
	s_add_i32 s34, s52, s38
	global_load_lds_dwordx4 v[146:147], off
	s_mov_b32 m0, s34
	v_lshl_add_u64 v[146:147], s[30:31], 0, v[134:135]
	global_load_lds_dwordx4 v[146:147], off
	s_add_i32 m0, s34, 0x2000
	v_lshl_add_u64 v[146:147], s[30:31], 0, v[136:137]
	global_load_lds_dwordx4 v[146:147], off
	s_mov_b32 m0, s42
	v_lshl_add_u64 v[146:147], v[194:195], 0, s[80:81]
	global_load_lds_dwordx4 v[146:147], off
	s_mov_b32 m0, s43
	v_lshl_add_u64 v[146:147], v[210:211], 0, s[80:81]
	global_load_lds_dwordx4 v[146:147], off
	s_waitcnt vmcnt(8)
	s_waitcnt lgkmcnt(0)
	s_setprio 1
	s_barrier
	v_mfma_f32_16x16x32_bf16 v[62:65], v[130:133], v[188:191], v[62:65]
	v_mfma_f32_16x16x32_bf16 v[58:61], v[152:155], v[188:191], v[58:61]
	v_mfma_f32_16x16x32_bf16 v[46:49], v[130:133], v[218:221], v[46:49]
	v_mfma_f32_16x16x32_bf16 v[42:45], v[152:155], v[218:221], v[42:45]
	v_mfma_f32_16x16x32_bf16 v[30:33], v[130:133], v[226:229], v[30:33]
	v_mfma_f32_16x16x32_bf16 v[26:29], v[152:155], v[226:229], v[26:29]
	v_mfma_f32_16x16x32_bf16 v[14:17], v[130:133], v[234:237], v[14:17]
	v_mfma_f32_16x16x32_bf16 v[10:13], v[152:155], v[234:237], v[10:13]
	v_mfma_f32_16x16x32_bf16 v[62:65], v[142:145], v[206:209], v[62:65]
	v_mfma_f32_16x16x32_bf16 v[58:61], v[156:159], v[206:209], v[58:61]
	v_mfma_f32_16x16x32_bf16 v[46:49], v[142:145], v[222:225], v[46:49]
	v_mfma_f32_16x16x32_bf16 v[42:45], v[156:159], v[222:225], v[42:45]
	v_mfma_f32_16x16x32_bf16 v[30:33], v[142:145], v[230:233], v[30:33]
	v_mfma_f32_16x16x32_bf16 v[26:29], v[156:159], v[230:233], v[26:29]
	v_mfma_f32_16x16x32_bf16 v[14:17], v[142:145], v[238:241], v[14:17]
	v_mfma_f32_16x16x32_bf16 v[10:13], v[156:159], v[238:241], v[10:13]
	v_mfma_f32_16x16x32_bf16 v[54:57], v[160:163], v[188:191], v[54:57]
	v_mfma_f32_16x16x32_bf16 v[50:53], v[168:171], v[188:191], v[50:53]
	v_mfma_f32_16x16x32_bf16 v[38:41], v[160:163], v[218:221], v[38:41]
	v_mfma_f32_16x16x32_bf16 v[34:37], v[168:171], v[218:221], v[34:37]
	v_mfma_f32_16x16x32_bf16 v[22:25], v[160:163], v[226:229], v[22:25]
	v_mfma_f32_16x16x32_bf16 v[18:21], v[168:171], v[226:229], v[18:21]
	v_mfma_f32_16x16x32_bf16 v[6:9], v[160:163], v[234:237], v[6:9]
	v_mfma_f32_16x16x32_bf16 v[2:5], v[168:171], v[234:237], v[2:5]
	v_mfma_f32_16x16x32_bf16 v[54:57], v[164:167], v[206:209], v[54:57]
	v_mfma_f32_16x16x32_bf16 v[50:53], v[172:175], v[206:209], v[50:53]
	v_mfma_f32_16x16x32_bf16 v[38:41], v[164:167], v[222:225], v[38:41]
	v_mfma_f32_16x16x32_bf16 v[34:37], v[172:175], v[222:225], v[34:37]
	v_mfma_f32_16x16x32_bf16 v[22:25], v[164:167], v[230:233], v[22:25]
	v_mfma_f32_16x16x32_bf16 v[18:21], v[172:175], v[230:233], v[18:21]
	v_mfma_f32_16x16x32_bf16 v[6:9], v[164:167], v[238:241], v[6:9]
	v_mfma_f32_16x16x32_bf16 v[2:5], v[172:175], v[238:241], v[2:5]
	s_barrier
	s_setprio 0
	s_add_i32 s50, s50, 2
	s_add_u32 s28, s28, 0x1000
	s_addc_u32 s29, s29, 0
	s_add_u32 s48, s48, 0x1000
	s_addc_u32 s49, s49, 0
	s_cmp_gt_u32 s50, 61
	s_cbranch_scc0 .LBB0_580
	s_and_b64 vcc, exec, s[14:15]
	s_cbranch_vccz .LBB0_583
	s_barrier

; #define PG8_STAGE(bufoff, gbase, voff) do { _Pragma("unroll") for (int _i = 0; _i < 2; ++_i) \
;         __builtin_amdgcn_global_load_lds((const unsigned*)((const char*)(gbase) + (voff)[_i]), (PG8_LAS unsigned*)(lds + (bufoff) + ldsw + _i * 8192), 16, 0, 0); } while (0)
; #define PG8_LDA(dst, b, h) do { _Pragma("unroll") for (int m = 0; m < 4; ++m) _Pragma("unroll") for (int k = 0; k < 2; ++k) dst[m][k] = *(const PG8_LAS bf16x8*)(lds + PG8_SA(b, h) + aoff + m * 2048 + k * 1024); } while (0)
; #define PG8_LDB(dst, b, h) do { _Pragma("unroll") for (int n = 0; n < 2; ++n) _Pragma("unroll") for (int k = 0; k < 2; ++k) dst[n][k] = *(const PG8_LAS bf16x8*)(lds + PG8_SB(b, h) + boff + n * 2048 + k * 1024); } while (0)
; #define PG8_MMA(ai, bj, At, Bt) do { __builtin_amdgcn_s_setprio(1); _Pragma("unroll") for (int m = 0; m < 4; ++m) _Pragma("unroll") for (int n = 0; n < 2; ++n) _Pragma("unroll") for (int k = 0; k < 2; ++k) \
;         acc[ai][bj][m][n] = __builtin_amdgcn_mfma_f32_16x16x32_bf16(Bt[n][k], At[m][k], acc[ai][bj][m][n], 0, 0, 0); __builtin_amdgcn_s_setprio(0); } while (0)
; #define PG8_WAIT_V(n) asm volatile("s_waitcnt vmcnt(" #n ")" ::: "memory")
; template <class Epi, class Sched, bool ALIGN_EPI, int LMASK = -1, int LMASKB = LMASK>
; __device__ __forceinline__ void gemm_phase(PG8_LAS unsigned char* lds, const Gemm g, const Sched& S, const Epi& E) {
;     ...
;         const char* nA = has_next ? (const char*)g.A + (size_t)(nxt.pm & LMASK) * tstepA : cA; const char* nB = has_next ? (const char*)g.Bt + (size_t)nxt.pm * g.b_pm_stride + (size_t)(nxt.pn & LMASKB) * tstepB : cB;
;         for (int t = 0; t < nt; t += 2) {
;             const bool last = (t == nt - 2);
;             const char* a1 = cA + (size_t)(t + 1) * kstepA;
;             const char* a2 = last ? nA : cA + (size_t)(t + 2) * kstepA; const char* b2 = last ? nB : cB + (size_t)(t + 2) * kstepB;
;             const char* a3 = a2 + kstepA; const char* b3 = b2 + kstepB;
;             PG8_LDB(B0, 0, 0); PG8_LDB(B1, 0, 1); PG8_SCHED; PG8_LDA(At, 0, 0); PG8_STAGE(PG8_SA(1, 1), a1 + hstepA, voffA);
;             PG8_WAIT_V(8); PG8_WAIT_L(0); PG8_BAR; PG8_MMA(0, 0, At, B0); PG8_MMA(0, 1, At, B1); PG8_BAR; PG8_SCHED;
;             PG8_LDA(At, 0, 1); PG8_STAGE(PG8_SB(0, 0), b2, voffB); PG8_STAGE(PG8_SB(0, 1), b2 + hstepB, voffB); PG8_STAGE(PG8_SA(0, 0), a2, voffA);
.LBB0_678:
	s_add_u32 s26, s24, 0xfff00800
	s_addc_u32 s27, s25, -1
	s_add_i32 s50, 0, 0x10000
	s_cmp_eq_u32 s49, 60
	s_cselect_b32 s29, s1, s27
	s_cselect_b32 s28, s2, s26
	s_cselect_b32 s27, s15, s48
	s_cselect_b32 s26, s17, s47
	s_add_i32 s52, 0, 0x14000
	v_add_u32_e32 v154, s50, v143
	v_add_u32_e32 v170, s52, v143
	ds_read_b128 v[138:141], v154
	ds_read_b128 v[146:149], v154 offset:1024
	ds_read_b128 v[150:153], v154 offset:2048
	ds_read_b128 v[154:157], v154 offset:3072
	ds_read_b128 v[158:161], v170
	ds_read_b128 v[162:165], v170 offset:1024
	ds_read_b128 v[166:169], v170 offset:2048
	ds_read_b128 v[170:173], v170 offset:3072
	v_lshl_add_u64 v[194:195], s[24:25], 0, v[134:135]
	s_add_i32 m0, s23, 0xc000
	ds_read_b128 v[174:177], v145
	ds_read_b128 v[188:191], v145 offset:1024
	ds_read_b128 v[206:209], v145 offset:2048
	ds_read_b128 v[218:221], v145 offset:3072
	ds_read_b128 v[222:225], v145 offset:4096
	ds_read_b128 v[226:229], v145 offset:5120
	ds_read_b128 v[230:233], v145 offset:6144
	ds_read_b128 v[234:237], v145 offset:7168
	global_load_lds_dwordx4 v[194:195], off
	s_add_i32 m0, s23, 0xe000
	v_lshl_add_u64 v[194:195], s[24:25], 0, v[136:137]
	global_load_lds_dwordx4 v[194:195], off
	s_waitcnt vmcnt(8)
	s_waitcnt lgkmcnt(0)
	s_setprio 1
	s_barrier
	v_mfma_f32_16x16x32_bf16 v[126:129], v[138:141], v[174:177], v[126:129]
	v_mfma_f32_16x16x32_bf16 v[122:125], v[150:153], v[174:177], v[122:125]
	v_mfma_f32_16x16x32_bf16 v[110:113], v[138:141], v[206:209], v[110:113]
	v_mfma_f32_16x16x32_bf16 v[106:109], v[150:153], v[206:209], v[106:109]
	v_mfma_f32_16x16x32_bf16 v[94:97], v[138:141], v[222:225], v[94:97]
	v_mfma_f32_16x16x32_bf16 v[90:93], v[150:153], v[222:225], v[90:93]
	v_mfma_f32_16x16x32_bf16 v[78:81], v[138:141], v[230:233], v[78:81]
	v_mfma_f32_16x16x32_bf16 v[74:77], v[150:153], v[230:233], v[74:77]
	v_mfma_f32_16x16x32_bf16 v[126:129], v[146:149], v[188:191], v[126:129]
	v_mfma_f32_16x16x32_bf16 v[122:125], v[154:157], v[188:191], v[122:125]
	v_mfma_f32_16x16x32_bf16 v[110:113], v[146:149], v[218:221], v[110:113]
	v_mfma_f32_16x16x32_bf16 v[106:109], v[154:157], v[218:221], v[106:109]
	v_mfma_f32_16x16x32_bf16 v[94:97], v[146:149], v[226:229], v[94:97]
	v_mfma_f32_16x16x32_bf16 v[90:93], v[154:157], v[226:229], v[90:93]
	v_mfma_f32_16x16x32_bf16 v[78:81], v[146:149], v[234:237], v[78:81]
	v_mfma_f32_16x16x32_bf16 v[74:77], v[154:157], v[234:237], v[74:77]
	v_mfma_f32_16x16x32_bf16 v[118:121], v[158:161], v[174:177], v[118:121]
	v_mfma_f32_16x16x32_bf16 v[114:117], v[166:169], v[174:177], v[114:117]
	v_mfma_f32_16x16x32_bf16 v[102:105], v[158:161], v[206:209], v[102:105]
	v_mfma_f32_16x16x32_bf16 v[98:101], v[166:169], v[206:209], v[98:101]
	v_mfma_f32_16x16x32_bf16 v[86:89], v[158:161], v[222:225], v[86:89]
	v_mfma_f32_16x16x32_bf16 v[82:85], v[166:169], v[222:225], v[82:85]
	v_mfma_f32_16x16x32_bf16 v[70:73], v[158:161], v[230:233], v[70:73]
	v_mfma_f32_16x16x32_bf16 v[66:69], v[166:169], v[230:233], v[66:69]
	v_mfma_f32_16x16x32_bf16 v[118:121], v[162:165], v[188:191], v[118:121]
	v_mfma_f32_16x16x32_bf16 v[114:117], v[170:173], v[188:191], v[114:117]
	v_mfma_f32_16x16x32_bf16 v[102:105], v[162:165], v[218:221], v[102:105]
	v_mfma_f32_16x16x32_bf16 v[98:101], v[170:173], v[218:221], v[98:101]
	v_mfma_f32_16x16x32_bf16 v[86:89], v[162:165], v[226:229], v[86:89]
	v_mfma_f32_16x16x32_bf16 v[82:85], v[170:173], v[226:229], v[82:85]
	v_mfma_f32_16x16x32_bf16 v[70:73], v[162:165], v[234:237], v[70:73]
	v_mfma_f32_16x16x32_bf16 v[66:69], v[170:173], v[234:237], v[66:69]
	s_barrier
	s_setprio 0
	s_add_i32 s50, s50, s38
	v_lshl_add_u64 v[194:195], s[26:27], 0, v[130:131]
	s_mov_b32 m0, s50
	ds_read_b128 v[174:177], v145 offset:16384
	ds_read_b128 v[188:191], v145 offset:17408
	ds_read_b128 v[206:209], v145 offset:18432
	ds_read_b128 v[218:221], v145 offset:19456
	ds_read_b128 v[222:225], v145 offset:20480
	ds_read_b128 v[226:229], v145 offset:21504
	ds_read_b128 v[230:233], v145 offset:22528
	ds_read_b128 v[234:237], v145 offset:23552
	global_load_lds_dwordx4 v[194:195], off
	s_add_i32 m0, s50, 0x2000
	s_add_u32 s50, s26, 0x100000
	v_lshl_add_u64 v[210:211], s[26:27], 0, v[132:133]
	s_addc_u32 s51, s27, 0
	s_add_i32 s52, s52, s38
	global_load_lds_dwordx4 v[210:211], off
	v_lshl_add_u64 v[212:213], s[50:51], 0, v[130:131]
	s_mov_b32 m0, s52
	v_lshl_add_u64 v[238:239], s[28:29], 0, v[132:133]
	global_load_lds_dwordx4 v[212:213], off
	s_add_i32 m0, s52, 0x2000
	v_lshl_add_u64 v[212:213], s[50:51], 0, v[132:133]
	global_load_lds_dwordx4 v[212:213], off
	s_mov_b32 m0, s23
	v_lshl_add_u64 v[212:213], s[28:29], 0, v[130:131]
	global_load_lds_dwordx4 v[212:213], off
	s_mov_b32 m0, s39
	s_nop 0
	global_load_lds_dwordx4 v[238:239], off
	s_waitcnt vmcnt(8)
	s_waitcnt lgkmcnt(0)
	s_setprio 1
	s_barrier
; #define PG8_STAGE(bufoff, gbase, voff) do { _Pragma("unroll") for (int _i = 0; _i < 2; ++_i) \
;         __builtin_amdgcn_global_load_lds((const unsigned*)((const char*)(gbase) + (voff)[_i]), (PG8_LAS unsigned*)(lds + (bufoff) + ldsw + _i * 8192), 16, 0, 0); } while (0)
; #define PG8_LDA(dst, b, h) do { _Pragma("unroll") for (int m = 0; m < 4; ++m) _Pragma("unroll") for (int k = 0; k < 2; ++k) dst[m][k] = *(const PG8_LAS bf16x8*)(lds + PG8_SA(b, h) + aoff + m * 2048 + k * 1024); } while (0)
; #define PG8_LDB(dst, b, h) do { _Pragma("unroll") for (int n = 0; n < 2; ++n) _Pragma("unroll") for (int k = 0; k < 2; ++k) dst[n][k] = *(const PG8_LAS bf16x8*)(lds + PG8_SB(b, h) + boff + n * 2048 + k * 1024); } while (0)
; #define PG8_MMA(ai, bj, At, Bt) do { __builtin_amdgcn_s_setprio(1); _Pragma("unroll") for (int m = 0; m < 4; ++m) _Pragma("unroll") for (int n = 0; n < 2; ++n) _Pragma("unroll") for (int k = 0; k < 2; ++k) \
;         acc[ai][bj][m][n] = __builtin_amdgcn_mfma_f32_16x16x32_bf16(Bt[n][k], At[m][k], acc[ai][bj][m][n], 0, 0, 0); __builtin_amdgcn_s_setprio(0); } while (0)
; #define PG8_WAIT_V(n) asm volatile("s_waitcnt vmcnt(" #n ")" ::: "memory")
; #define PG8_WAIT_L(n) asm volatile("s_waitcnt lgkmcnt(" #n ")" ::: "memory")
; #define PG8_BAR __builtin_amdgcn_s_barrier()
; #define PG8_SCHED __builtin_amdgcn_sched_barrier(0)
; template <class Epi, class Sched, bool ALIGN_EPI, int LMASK = -1, int LMASKB = LMASK>
; __device__ __forceinline__ void gemm_phase(PG8_LAS unsigned char* lds, const Gemm g, const Sched& S, const Epi& E) {
;     ...
;             PG8_WAIT_V(8); PG8_WAIT_L(0); PG8_BAR; PG8_MMA(0, 0, At, B0); PG8_MMA(0, 1, At, B1); PG8_BAR; PG8_SCHED;
;             PG8_LDA(At, 0, 1); PG8_STAGE(PG8_SB(0, 0), b2, voffB); PG8_STAGE(PG8_SB(0, 1), b2 + hstepB, voffB); PG8_STAGE(PG8_SA(0, 0), a2, voffA);
;             PG8_WAIT_V(8); PG8_WAIT_L(0); PG8_BAR; PG8_MMA(1, 0, At, B0); PG8_MMA(1, 1, At, B1); PG8_BAR; PG8_SCHED;
;             PG8_LDB(B0, 1, 0); PG8_LDB(B1, 1, 1); PG8_SCHED; PG8_LDA(At, 1, 0); PG8_STAGE(PG8_SA(0, 1), a2 + hstepA, voffA);
;             PG8_WAIT_V(8); PG8_WAIT_L(0); PG8_BAR; PG8_MMA(0, 0, At, B0); PG8_MMA(0, 1, At, B1); PG8_BAR; PG8_SCHED;
	v_mfma_f32_16x16x32_bf16 v[62:65], v[138:141], v[174:177], v[62:65]
	v_mfma_f32_16x16x32_bf16 v[58:61], v[150:153], v[174:177], v[58:61]
	v_mfma_f32_16x16x32_bf16 v[46:49], v[138:141], v[206:209], v[46:49]
	v_mfma_f32_16x16x32_bf16 v[42:45], v[150:153], v[206:209], v[42:45]
	v_mfma_f32_16x16x32_bf16 v[30:33], v[138:141], v[222:225], v[30:33]
	v_mfma_f32_16x16x32_bf16 v[26:29], v[150:153], v[222:225], v[26:29]
	v_mfma_f32_16x16x32_bf16 v[14:17], v[138:141], v[230:233], v[14:17]
	v_mfma_f32_16x16x32_bf16 v[10:13], v[150:153], v[230:233], v[10:13]
	v_mfma_f32_16x16x32_bf16 v[62:65], v[146:149], v[188:191], v[62:65]
	v_mfma_f32_16x16x32_bf16 v[58:61], v[154:157], v[188:191], v[58:61]
	v_mfma_f32_16x16x32_bf16 v[46:49], v[146:149], v[218:221], v[46:49]
	v_mfma_f32_16x16x32_bf16 v[42:45], v[154:157], v[218:221], v[42:45]
	v_mfma_f32_16x16x32_bf16 v[30:33], v[146:149], v[226:229], v[30:33]
	v_mfma_f32_16x16x32_bf16 v[26:29], v[154:157], v[226:229], v[26:29]
	v_mfma_f32_16x16x32_bf16 v[14:17], v[146:149], v[234:237], v[14:17]
	v_mfma_f32_16x16x32_bf16 v[10:13], v[154:157], v[234:237], v[10:13]
	v_mfma_f32_16x16x32_bf16 v[54:57], v[158:161], v[174:177], v[54:57]
	v_mfma_f32_16x16x32_bf16 v[50:53], v[166:169], v[174:177], v[50:53]
	v_mfma_f32_16x16x32_bf16 v[38:41], v[158:161], v[206:209], v[38:41]
	v_mfma_f32_16x16x32_bf16 v[34:37], v[166:169], v[206:209], v[34:37]
	v_mfma_f32_16x16x32_bf16 v[22:25], v[158:161], v[222:225], v[22:25]
	v_mfma_f32_16x16x32_bf16 v[18:21], v[166:169], v[222:225], v[18:21]
	v_mfma_f32_16x16x32_bf16 v[6:9], v[158:161], v[230:233], v[6:9]
	v_mfma_f32_16x16x32_bf16 v[2:5], v[166:169], v[230:233], v[2:5]
	v_mfma_f32_16x16x32_bf16 v[54:57], v[162:165], v[188:191], v[54:57]
	v_mfma_f32_16x16x32_bf16 v[50:53], v[170:173], v[188:191], v[50:53]
	v_mfma_f32_16x16x32_bf16 v[38:41], v[162:165], v[218:221], v[38:41]
	v_mfma_f32_16x16x32_bf16 v[34:37], v[170:173], v[218:221], v[34:37]
	v_mfma_f32_16x16x32_bf16 v[22:25], v[162:165], v[226:229], v[22:25]
	v_mfma_f32_16x16x32_bf16 v[18:21], v[170:173], v[226:229], v[18:21]
	v_mfma_f32_16x16x32_bf16 v[6:9], v[162:165], v[234:237], v[6:9]
	v_mfma_f32_16x16x32_bf16 v[2:5], v[170:173], v[234:237], v[2:5]
	s_barrier
	s_setprio 0
	s_add_i32 s50, 0, 0x18000
	s_add_i32 s51, 0, 0x1c000
	v_add_u32_e32 v154, s50, v143
	v_add_u32_e32 v170, s51, v143
	ds_read_b128 v[138:141], v154
	ds_read_b128 v[146:149], v154 offset:1024
	ds_read_b128 v[150:153], v154 offset:2048
	ds_read_b128 v[154:157], v154 offset:3072
	ds_read_b128 v[158:161], v170
	ds_read_b128 v[162:165], v170 offset:1024
	ds_read_b128 v[166:169], v170 offset:2048
	ds_read_b128 v[170:173], v170 offset:3072
	s_add_u32 s28, s28, 0x100000
	s_addc_u32 s29, s29, 0
	s_mov_b32 m0, s40
	v_lshl_add_u64 v[240:241], s[28:29], 0, v[130:131]
	ds_read_b128 v[174:177], v145 offset:32768
	ds_read_b128 v[188:191], v145 offset:33792
	ds_read_b128 v[206:209], v145 offset:34816
	ds_read_b128 v[218:221], v145 offset:35840
	ds_read_b128 v[222:225], v145 offset:36864
	ds_read_b128 v[226:229], v145 offset:37888
	ds_read_b128 v[230:233], v145 offset:38912
	ds_read_b128 v[234:237], v145 offset:39936
	global_load_lds_dwordx4 v[240:241], off
	s_mov_b32 m0, s41
	v_lshl_add_u64 v[240:241], s[28:29], 0, v[132:133]
	global_load_lds_dwordx4 v[240:241], off
	s_waitcnt vmcnt(8)
	s_waitcnt lgkmcnt(0)
	s_setprio 1
	s_barrier
	v_mfma_f32_16x16x32_bf16 v[126:129], v[138:141], v[174:177], v[126:129]
	v_mfma_f32_16x16x32_bf16 v[122:125], v[150:153], v[174:177], v[122:125]
	v_mfma_f32_16x16x32_bf16 v[110:113], v[138:141], v[206:209], v[110:113]
	v_mfma_f32_16x16x32_bf16 v[106:109], v[150:153], v[206:209], v[106:109]
	v_mfma_f32_16x16x32_bf16 v[94:97], v[138:141], v[222:225], v[94:97]
	v_mfma_f32_16x16x32_bf16 v[90:93], v[150:153], v[222:225], v[90:93]
	v_mfma_f32_16x16x32_bf16 v[78:81], v[138:141], v[230:233], v[78:81]
	v_mfma_f32_16x16x32_bf16 v[74:77], v[150:153], v[230:233], v[74:77]
	v_mfma_f32_16x16x32_bf16 v[126:129], v[146:149], v[188:191], v[126:129]
	v_mfma_f32_16x16x32_bf16 v[122:125], v[154:157], v[188:191], v[122:125]
	v_mfma_f32_16x16x32_bf16 v[110:113], v[146:149], v[218:221], v[110:113]
	v_mfma_f32_16x16x32_bf16 v[106:109], v[154:157], v[218:221], v[106:109]
	v_mfma_f32_16x16x32_bf16 v[94:97], v[146:149], v[226:229], v[94:97]
	v_mfma_f32_16x16x32_bf16 v[90:93], v[154:157], v[226:229], v[90:93]
	v_mfma_f32_16x16x32_bf16 v[78:81], v[146:149], v[234:237], v[78:81]
	v_mfma_f32_16x16x32_bf16 v[74:77], v[154:157], v[234:237], v[74:77]
	v_mfma_f32_16x16x32_bf16 v[118:121], v[158:161], v[174:177], v[118:121]
	v_mfma_f32_16x16x32_bf16 v[114:117], v[166:169], v[174:177], v[114:117]
	v_mfma_f32_16x16x32_bf16 v[102:105], v[158:161], v[206:209], v[102:105]
	v_mfma_f32_16x16x32_bf16 v[98:101], v[166:169], v[206:209], v[98:101]
	v_mfma_f32_16x16x32_bf16 v[86:89], v[158:161], v[222:225], v[86:89]
	v_mfma_f32_16x16x32_bf16 v[82:85], v[166:169], v[222:225], v[82:85]
	v_mfma_f32_16x16x32_bf16 v[70:73], v[158:161], v[230:233], v[70:73]
	v_mfma_f32_16x16x32_bf16 v[66:69], v[166:169], v[230:233], v[66:69]
	v_mfma_f32_16x16x32_bf16 v[118:121], v[162:165], v[188:191], v[118:121]
	v_mfma_f32_16x16x32_bf16 v[114:117], v[170:173], v[188:191], v[114:117]
	v_mfma_f32_16x16x32_bf16 v[102:105], v[162:165], v[218:221], v[102:105]
	v_mfma_f32_16x16x32_bf16 v[98:101], v[170:173], v[218:221], v[98:101]
	v_mfma_f32_16x16x32_bf16 v[86:89], v[162:165], v[226:229], v[86:89]
	v_mfma_f32_16x16x32_bf16 v[82:85], v[170:173], v[226:229], v[82:85]
	v_mfma_f32_16x16x32_bf16 v[70:73], v[162:165], v[234:237], v[70:73]
	v_mfma_f32_16x16x32_bf16 v[66:69], v[170:173], v[234:237], v[66:69]
	s_barrier
; #define PG8_STAGE(bufoff, gbase, voff) do { _Pragma("unroll") for (int _i = 0; _i < 2; ++_i) \
;         __builtin_amdgcn_global_load_lds((const unsigned*)((const char*)(gbase) + (voff)[_i]), (PG8_LAS unsigned*)(lds + (bufoff) + ldsw + _i * 8192), 16, 0, 0); } while (0)
; #define PG8_LDA(dst, b, h) do { _Pragma("unroll") for (int m = 0; m < 4; ++m) _Pragma("unroll") for (int k = 0; k < 2; ++k) dst[m][k] = *(const PG8_LAS bf16x8*)(lds + PG8_SA(b, h) + aoff + m * 2048 + k * 1024); } while (0)
; #define PG8_MMA(ai, bj, At, Bt) do { __builtin_amdgcn_s_setprio(1); _Pragma("unroll") for (int m = 0; m < 4; ++m) _Pragma("unroll") for (int n = 0; n < 2; ++n) _Pragma("unroll") for (int k = 0; k < 2; ++k) \
;         acc[ai][bj][m][n] = __builtin_amdgcn_mfma_f32_16x16x32_bf16(Bt[n][k], At[m][k], acc[ai][bj][m][n], 0, 0, 0); __builtin_amdgcn_s_setprio(0); } while (0)
; #define PG8_WAIT_V(n) asm volatile("s_waitcnt vmcnt(" #n ")" ::: "memory")
; #define PG8_WAIT_L(n) asm volatile("s_waitcnt lgkmcnt(" #n ")" ::: "memory")
; #define PG8_BAR __builtin_amdgcn_s_barrier()
; #define PG8_SCHED __builtin_amdgcn_sched_barrier(0)
; template <class Epi, class Sched, bool ALIGN_EPI, int LMASK = -1, int LMASKB = LMASK>
; __device__ __forceinline__ void gemm_phase(PG8_LAS unsigned char* lds, const Gemm g, const Sched& S, const Epi& E) {
;     ...
;             PG8_LDA(At, 1, 1); PG8_STAGE(PG8_SB(1, 0), b3, voffB); PG8_STAGE(PG8_SB(1, 1), b3 + hstepB, voffB); PG8_STAGE(PG8_SA(1, 0), a3, voffA);
;             PG8_WAIT_V(8); PG8_WAIT_L(0); PG8_BAR; PG8_MMA(1, 0, At, B0); PG8_MMA(1, 1, At, B1); PG8_BAR; PG8_SCHED;
;         }
	s_setprio 0
	s_add_i32 s28, s50, s38
	v_lshl_add_u64 v[194:195], v[194:195], 0, s[80:81]
	s_mov_b32 m0, s28
	ds_read_b128 v[174:177], v145 offset:49152
	ds_read_b128 v[188:191], v145 offset:50176
	ds_read_b128 v[206:209], v145 offset:51200
	ds_read_b128 v[218:221], v145 offset:52224
	ds_read_b128 v[222:225], v145 offset:53248
	ds_read_b128 v[226:229], v145 offset:54272
	ds_read_b128 v[230:233], v145 offset:55296
	ds_read_b128 v[234:237], v145 offset:56320
	global_load_lds_dwordx4 v[194:195], off
	s_add_i32 m0, s28, 0x2000
	s_add_u32 s26, s26, 0x100800
	v_lshl_add_u64 v[194:195], v[210:211], 0, s[80:81]
	s_addc_u32 s27, s27, 0
	s_add_i32 s28, s51, s38
	global_load_lds_dwordx4 v[194:195], off
	s_mov_b32 m0, s28
	v_lshl_add_u64 v[194:195], s[26:27], 0, v[130:131]
	global_load_lds_dwordx4 v[194:195], off
	s_add_i32 m0, s28, 0x2000
	v_lshl_add_u64 v[194:195], s[26:27], 0, v[132:133]
	global_load_lds_dwordx4 v[194:195], off
	s_mov_b32 m0, s42
	v_lshl_add_u64 v[194:195], v[212:213], 0, s[80:81]
	global_load_lds_dwordx4 v[194:195], off
	s_mov_b32 m0, s43
	v_lshl_add_u64 v[194:195], v[238:239], 0, s[80:81]
	global_load_lds_dwordx4 v[194:195], off
	s_waitcnt vmcnt(8)
	s_waitcnt lgkmcnt(0)
	s_setprio 1
	s_barrier
	v_mfma_f32_16x16x32_bf16 v[62:65], v[138:141], v[174:177], v[62:65]
	v_mfma_f32_16x16x32_bf16 v[58:61], v[150:153], v[174:177], v[58:61]
	v_mfma_f32_16x16x32_bf16 v[46:49], v[138:141], v[206:209], v[46:49]
	v_mfma_f32_16x16x32_bf16 v[42:45], v[150:153], v[206:209], v[42:45]
	v_mfma_f32_16x16x32_bf16 v[30:33], v[138:141], v[222:225], v[30:33]
	v_mfma_f32_16x16x32_bf16 v[26:29], v[150:153], v[222:225], v[26:29]
	v_mfma_f32_16x16x32_bf16 v[14:17], v[138:141], v[230:233], v[14:17]
	v_mfma_f32_16x16x32_bf16 v[10:13], v[150:153], v[230:233], v[10:13]
	v_mfma_f32_16x16x32_bf16 v[62:65], v[146:149], v[188:191], v[62:65]
	v_mfma_f32_16x16x32_bf16 v[58:61], v[154:157], v[188:191], v[58:61]
	v_mfma_f32_16x16x32_bf16 v[46:49], v[146:149], v[218:221], v[46:49]
	v_mfma_f32_16x16x32_bf16 v[42:45], v[154:157], v[218:221], v[42:45]
	v_mfma_f32_16x16x32_bf16 v[30:33], v[146:149], v[226:229], v[30:33]
	v_mfma_f32_16x16x32_bf16 v[26:29], v[154:157], v[226:229], v[26:29]
	v_mfma_f32_16x16x32_bf16 v[14:17], v[146:149], v[234:237], v[14:17]
	v_mfma_f32_16x16x32_bf16 v[10:13], v[154:157], v[234:237], v[10:13]
	v_mfma_f32_16x16x32_bf16 v[54:57], v[158:161], v[174:177], v[54:57]
	v_mfma_f32_16x16x32_bf16 v[50:53], v[166:169], v[174:177], v[50:53]
	v_mfma_f32_16x16x32_bf16 v[38:41], v[158:161], v[206:209], v[38:41]
	v_mfma_f32_16x16x32_bf16 v[34:37], v[166:169], v[206:209], v[34:37]
	v_mfma_f32_16x16x32_bf16 v[22:25], v[158:161], v[222:225], v[22:25]
	v_mfma_f32_16x16x32_bf16 v[18:21], v[166:169], v[222:225], v[18:21]
	v_mfma_f32_16x16x32_bf16 v[6:9], v[158:161], v[230:233], v[6:9]
	v_mfma_f32_16x16x32_bf16 v[2:5], v[166:169], v[230:233], v[2:5]
	v_mfma_f32_16x16x32_bf16 v[54:57], v[162:165], v[188:191], v[54:57]
	v_mfma_f32_16x16x32_bf16 v[50:53], v[170:173], v[188:191], v[50:53]
	v_mfma_f32_16x16x32_bf16 v[38:41], v[162:165], v[218:221], v[38:41]
	v_mfma_f32_16x16x32_bf16 v[34:37], v[170:173], v[218:221], v[34:37]
	v_mfma_f32_16x16x32_bf16 v[22:25], v[162:165], v[226:229], v[22:25]
	v_mfma_f32_16x16x32_bf16 v[18:21], v[170:173], v[226:229], v[18:21]
	v_mfma_f32_16x16x32_bf16 v[6:9], v[162:165], v[234:237], v[6:9]
	v_mfma_f32_16x16x32_bf16 v[2:5], v[170:173], v[234:237], v[2:5]
	s_barrier
	s_setprio 0
	s_add_i32 s49, s49, 2
	s_add_u32 s24, s24, 0x1000
	s_addc_u32 s25, s25, 0
	s_add_u32 s47, s47, 0x1000
	s_addc_u32 s48, s48, 0
	s_cmp_gt_u32 s49, 61
	s_cbranch_scc0 .LBB0_678
	s_and_b64 vcc, exec, s[12:13]
	s_cbranch_vccz .LBB0_681
	s_barrier

; #define PG8_STAGE(bufoff, gbase, voff) do { _Pragma("unroll") for (int _i = 0; _i < 2; ++_i) \
;         __builtin_amdgcn_global_load_lds((const unsigned*)((const char*)(gbase) + (voff)[_i]), (PG8_LAS unsigned*)(lds + (bufoff) + ldsw + _i * 8192), 16, 0, 0); } while (0)
; #define PG8_LDA(dst, b, h) do { _Pragma("unroll") for (int m = 0; m < 4; ++m) _Pragma("unroll") for (int k = 0; k < 2; ++k) dst[m][k] = *(const PG8_LAS bf16x8*)(lds + PG8_SA(b, h) + aoff + m * 2048 + k * 1024); } while (0)
; #define PG8_LDB(dst, b, h) do { _Pragma("unroll") for (int n = 0; n < 2; ++n) _Pragma("unroll") for (int k = 0; k < 2; ++k) dst[n][k] = *(const PG8_LAS bf16x8*)(lds + PG8_SB(b, h) + boff + n * 2048 + k * 1024); } while (0)
; #define PG8_MMA(ai, bj, At, Bt) do { __builtin_amdgcn_s_setprio(1); _Pragma("unroll") for (int m = 0; m < 4; ++m) _Pragma("unroll") for (int n = 0; n < 2; ++n) _Pragma("unroll") for (int k = 0; k < 2; ++k) \
;         acc[ai][bj][m][n] = __builtin_amdgcn_mfma_f32_16x16x32_bf16(Bt[n][k], At[m][k], acc[ai][bj][m][n], 0, 0, 0); __builtin_amdgcn_s_setprio(0); } while (0)
; #define PG8_WAIT_V(n) asm volatile("s_waitcnt vmcnt(" #n ")" ::: "memory")
; template <class Epi, class Sched, bool ALIGN_EPI, int LMASK = -1, int LMASKB = LMASK>
; __device__ __forceinline__ void gemm_phase(PG8_LAS unsigned char* lds, const Gemm g, const Sched& S, const Epi& E) {
;     ...
;         const char* nA = has_next ? (const char*)g.A + (size_t)(nxt.pm & LMASK) * tstepA : cA; const char* nB = has_next ? (const char*)g.Bt + (size_t)nxt.pm * g.b_pm_stride + (size_t)(nxt.pn & LMASKB) * tstepB : cB;
;         for (int t = 0; t < nt; t += 2) {
;             const bool last = (t == nt - 2);
;             const char* a1 = cA + (size_t)(t + 1) * kstepA;
;             const char* a2 = last ? nA : cA + (size_t)(t + 2) * kstepA; const char* b2 = last ? nB : cB + (size_t)(t + 2) * kstepB;
;             const char* a3 = a2 + kstepA; const char* b3 = b2 + kstepB;
;             PG8_LDB(B0, 0, 0); PG8_LDB(B1, 0, 1); PG8_SCHED; PG8_LDA(At, 0, 0); PG8_STAGE(PG8_SA(1, 1), a1 + hstepA, voffA);
;             PG8_WAIT_V(8); PG8_WAIT_L(0); PG8_BAR; PG8_MMA(0, 0, At, B0); PG8_MMA(0, 1, At, B1); PG8_BAR; PG8_SCHED;
;             PG8_LDA(At, 0, 1); PG8_STAGE(PG8_SB(0, 0), b2, voffB); PG8_STAGE(PG8_SB(0, 1), b2 + hstepB, voffB); PG8_STAGE(PG8_SA(0, 0), a2, voffA);
.LBB0_761:
	s_add_u32 s2, s28, 0xffc00800
	s_addc_u32 s3, s29, -1
	s_add_i32 s51, 0, 0x10000
	s_cmpk_eq_i32 s50, 0xfc
	s_cselect_b32 s31, s19, s3
	s_cselect_b32 s30, s46, s2
	v_add_u32_e32 v146, s51, v149
	s_cselect_b32 s3, s17, s49
	s_cselect_b32 s2, s47, s48
	s_add_i32 s54, 0, 0x14000
	ds_read_b128 v[130:133], v146
	ds_read_b128 v[142:145], v146 offset:1024
	ds_read_b128 v[152:155], v146 offset:2048
	ds_read_b128 v[156:159], v146 offset:3072
	v_add_u32_e32 v146, s54, v149
	ds_read_b128 v[160:163], v146
	ds_read_b128 v[164:167], v146 offset:1024
	ds_read_b128 v[168:171], v146 offset:2048
	ds_read_b128 v[172:175], v146 offset:3072
	v_lshl_add_u64 v[146:147], s[28:29], 0, v[138:139]
	s_add_i32 m0, s25, 0xc000
	ds_read_b128 v[188:191], v151
	ds_read_b128 v[206:209], v151 offset:1024
	ds_read_b128 v[218:221], v151 offset:2048
	ds_read_b128 v[222:225], v151 offset:3072
	ds_read_b128 v[226:229], v151 offset:4096
	ds_read_b128 v[230:233], v151 offset:5120
	ds_read_b128 v[234:237], v151 offset:6144
	ds_read_b128 v[238:241], v151 offset:7168
	global_load_lds_dwordx4 v[146:147], off
	s_add_i32 m0, s25, 0xe000
	v_lshl_add_u64 v[146:147], s[28:29], 0, v[140:141]
	global_load_lds_dwordx4 v[146:147], off
	s_waitcnt vmcnt(8)
	s_waitcnt lgkmcnt(0)
	s_setprio 1
	s_barrier
	v_mfma_f32_16x16x32_bf16 v[126:129], v[130:133], v[188:191], v[126:129]
	v_mfma_f32_16x16x32_bf16 v[122:125], v[152:155], v[188:191], v[122:125]
	v_mfma_f32_16x16x32_bf16 v[110:113], v[130:133], v[218:221], v[110:113]
	v_mfma_f32_16x16x32_bf16 v[106:109], v[152:155], v[218:221], v[106:109]
	v_mfma_f32_16x16x32_bf16 v[94:97], v[130:133], v[226:229], v[94:97]
	v_mfma_f32_16x16x32_bf16 v[90:93], v[152:155], v[226:229], v[90:93]
	v_mfma_f32_16x16x32_bf16 v[78:81], v[130:133], v[234:237], v[78:81]
	v_mfma_f32_16x16x32_bf16 v[74:77], v[152:155], v[234:237], v[74:77]
	v_mfma_f32_16x16x32_bf16 v[126:129], v[142:145], v[206:209], v[126:129]
	v_mfma_f32_16x16x32_bf16 v[122:125], v[156:159], v[206:209], v[122:125]
	v_mfma_f32_16x16x32_bf16 v[110:113], v[142:145], v[222:225], v[110:113]
	v_mfma_f32_16x16x32_bf16 v[106:109], v[156:159], v[222:225], v[106:109]
	v_mfma_f32_16x16x32_bf16 v[94:97], v[142:145], v[230:233], v[94:97]
	v_mfma_f32_16x16x32_bf16 v[90:93], v[156:159], v[230:233], v[90:93]
	v_mfma_f32_16x16x32_bf16 v[78:81], v[142:145], v[238:241], v[78:81]
	v_mfma_f32_16x16x32_bf16 v[74:77], v[156:159], v[238:241], v[74:77]
	v_mfma_f32_16x16x32_bf16 v[118:121], v[160:163], v[188:191], v[118:121]
	v_mfma_f32_16x16x32_bf16 v[114:117], v[168:171], v[188:191], v[114:117]
	v_mfma_f32_16x16x32_bf16 v[102:105], v[160:163], v[218:221], v[102:105]
	v_mfma_f32_16x16x32_bf16 v[98:101], v[168:171], v[218:221], v[98:101]
	v_mfma_f32_16x16x32_bf16 v[86:89], v[160:163], v[226:229], v[86:89]
	v_mfma_f32_16x16x32_bf16 v[82:85], v[168:171], v[226:229], v[82:85]
	v_mfma_f32_16x16x32_bf16 v[70:73], v[160:163], v[234:237], v[70:73]
	v_mfma_f32_16x16x32_bf16 v[66:69], v[168:171], v[234:237], v[66:69]
	v_mfma_f32_16x16x32_bf16 v[118:121], v[164:167], v[206:209], v[118:121]
	v_mfma_f32_16x16x32_bf16 v[114:117], v[172:175], v[206:209], v[114:117]
	v_mfma_f32_16x16x32_bf16 v[102:105], v[164:167], v[222:225], v[102:105]
	v_mfma_f32_16x16x32_bf16 v[98:101], v[172:175], v[222:225], v[98:101]
	v_mfma_f32_16x16x32_bf16 v[86:89], v[164:167], v[230:233], v[86:89]
	v_mfma_f32_16x16x32_bf16 v[82:85], v[172:175], v[230:233], v[82:85]
	v_mfma_f32_16x16x32_bf16 v[70:73], v[164:167], v[238:241], v[70:73]
	v_mfma_f32_16x16x32_bf16 v[66:69], v[172:175], v[238:241], v[66:69]
	s_barrier
	s_setprio 0
	s_add_i32 s51, s51, s38
	v_lshl_add_u64 v[146:147], s[2:3], 0, v[134:135]
	s_mov_b32 m0, s51
	ds_read_b128 v[188:191], v151 offset:16384
	ds_read_b128 v[206:209], v151 offset:17408
	ds_read_b128 v[218:221], v151 offset:18432
	ds_read_b128 v[222:225], v151 offset:19456
	ds_read_b128 v[226:229], v151 offset:20480
	ds_read_b128 v[230:233], v151 offset:21504
	ds_read_b128 v[234:237], v151 offset:22528
	ds_read_b128 v[238:241], v151 offset:23552
	global_load_lds_dwordx4 v[146:147], off
	s_add_i32 m0, s51, 0x2000
	s_add_u32 s52, s2, 0x400000
	v_lshl_add_u64 v[176:177], s[2:3], 0, v[136:137]
	s_addc_u32 s53, s3, 0
	s_add_i32 s51, s54, s38
	global_load_lds_dwordx4 v[176:177], off
	v_lshl_add_u64 v[194:195], s[52:53], 0, v[134:135]
	s_mov_b32 m0, s51
	v_lshl_add_u64 v[210:211], s[30:31], 0, v[136:137]
	global_load_lds_dwordx4 v[194:195], off
	s_add_i32 m0, s51, 0x2000
	v_lshl_add_u64 v[194:195], s[52:53], 0, v[136:137]
	global_load_lds_dwordx4 v[194:195], off
	s_mov_b32 m0, s25
	v_lshl_add_u64 v[194:195], s[30:31], 0, v[134:135]
	global_load_lds_dwordx4 v[194:195], off
	s_mov_b32 m0, s27
	s_nop 0
	global_load_lds_dwordx4 v[210:211], off
	s_waitcnt vmcnt(8)
	s_waitcnt lgkmcnt(0)
	s_setprio 1
	s_barrier
; #define PG8_STAGE(bufoff, gbase, voff) do { _Pragma("unroll") for (int _i = 0; _i < 2; ++_i) \
;         __builtin_amdgcn_global_load_lds((const unsigned*)((const char*)(gbase) + (voff)[_i]), (PG8_LAS unsigned*)(lds + (bufoff) + ldsw + _i * 8192), 16, 0, 0); } while (0)
; #define PG8_LDA(dst, b, h) do { _Pragma("unroll") for (int m = 0; m < 4; ++m) _Pragma("unroll") for (int k = 0; k < 2; ++k) dst[m][k] = *(const PG8_LAS bf16x8*)(lds + PG8_SA(b, h) + aoff + m * 2048 + k * 1024); } while (0)
; #define PG8_LDB(dst, b, h) do { _Pragma("unroll") for (int n = 0; n < 2; ++n) _Pragma("unroll") for (int k = 0; k < 2; ++k) dst[n][k] = *(const PG8_LAS bf16x8*)(lds + PG8_SB(b, h) + boff + n * 2048 + k * 1024); } while (0)
; #define PG8_MMA(ai, bj, At, Bt) do { __builtin_amdgcn_s_setprio(1); _Pragma("unroll") for (int m = 0; m < 4; ++m) _Pragma("unroll") for (int n = 0; n < 2; ++n) _Pragma("unroll") for (int k = 0; k < 2; ++k) \
;         acc[ai][bj][m][n] = __builtin_amdgcn_mfma_f32_16x16x32_bf16(Bt[n][k], At[m][k], acc[ai][bj][m][n], 0, 0, 0); __builtin_amdgcn_s_setprio(0); } while (0)
; #define PG8_WAIT_V(n) asm volatile("s_waitcnt vmcnt(" #n ")" ::: "memory")
; #define PG8_WAIT_L(n) asm volatile("s_waitcnt lgkmcnt(" #n ")" ::: "memory")
; #define PG8_BAR __builtin_amdgcn_s_barrier()
; #define PG8_SCHED __builtin_amdgcn_sched_barrier(0)
; template <class Epi, class Sched, bool ALIGN_EPI, int LMASK = -1, int LMASKB = LMASK>
; __device__ __forceinline__ void gemm_phase(PG8_LAS unsigned char* lds, const Gemm g, const Sched& S, const Epi& E) {
;     ...
;             PG8_WAIT_V(8); PG8_WAIT_L(0); PG8_BAR; PG8_MMA(1, 0, At, B0); PG8_MMA(1, 1, At, B1); PG8_BAR; PG8_SCHED;
;             PG8_LDB(B0, 1, 0); PG8_LDB(B1, 1, 1); PG8_SCHED; PG8_LDA(At, 1, 0); PG8_STAGE(PG8_SA(0, 1), a2 + hstepA, voffA);
;             PG8_WAIT_V(8); PG8_WAIT_L(0); PG8_BAR; PG8_MMA(0, 0, At, B0); PG8_MMA(0, 1, At, B1); PG8_BAR; PG8_SCHED;
	v_mfma_f32_16x16x32_bf16 v[62:65], v[130:133], v[188:191], v[62:65]
	v_mfma_f32_16x16x32_bf16 v[58:61], v[152:155], v[188:191], v[58:61]
	v_mfma_f32_16x16x32_bf16 v[46:49], v[130:133], v[218:221], v[46:49]
	v_mfma_f32_16x16x32_bf16 v[42:45], v[152:155], v[218:221], v[42:45]
	v_mfma_f32_16x16x32_bf16 v[30:33], v[130:133], v[226:229], v[30:33]
	v_mfma_f32_16x16x32_bf16 v[26:29], v[152:155], v[226:229], v[26:29]
	v_mfma_f32_16x16x32_bf16 v[14:17], v[130:133], v[234:237], v[14:17]
	v_mfma_f32_16x16x32_bf16 v[10:13], v[152:155], v[234:237], v[10:13]
	v_mfma_f32_16x16x32_bf16 v[62:65], v[142:145], v[206:209], v[62:65]
	v_mfma_f32_16x16x32_bf16 v[58:61], v[156:159], v[206:209], v[58:61]
	v_mfma_f32_16x16x32_bf16 v[46:49], v[142:145], v[222:225], v[46:49]
	v_mfma_f32_16x16x32_bf16 v[42:45], v[156:159], v[222:225], v[42:45]
	v_mfma_f32_16x16x32_bf16 v[30:33], v[142:145], v[230:233], v[30:33]
	v_mfma_f32_16x16x32_bf16 v[26:29], v[156:159], v[230:233], v[26:29]
	v_mfma_f32_16x16x32_bf16 v[14:17], v[142:145], v[238:241], v[14:17]
	v_mfma_f32_16x16x32_bf16 v[10:13], v[156:159], v[238:241], v[10:13]
	v_mfma_f32_16x16x32_bf16 v[54:57], v[160:163], v[188:191], v[54:57]
	v_mfma_f32_16x16x32_bf16 v[50:53], v[168:171], v[188:191], v[50:53]
	v_mfma_f32_16x16x32_bf16 v[38:41], v[160:163], v[218:221], v[38:41]
	v_mfma_f32_16x16x32_bf16 v[34:37], v[168:171], v[218:221], v[34:37]
	v_mfma_f32_16x16x32_bf16 v[22:25], v[160:163], v[226:229], v[22:25]
	v_mfma_f32_16x16x32_bf16 v[18:21], v[168:171], v[226:229], v[18:21]
	v_mfma_f32_16x16x32_bf16 v[6:9], v[160:163], v[234:237], v[6:9]
	v_mfma_f32_16x16x32_bf16 v[2:5], v[168:171], v[234:237], v[2:5]
	v_mfma_f32_16x16x32_bf16 v[54:57], v[164:167], v[206:209], v[54:57]
	v_mfma_f32_16x16x32_bf16 v[50:53], v[172:175], v[206:209], v[50:53]
	v_mfma_f32_16x16x32_bf16 v[38:41], v[164:167], v[222:225], v[38:41]
	v_mfma_f32_16x16x32_bf16 v[34:37], v[172:175], v[222:225], v[34:37]
	v_mfma_f32_16x16x32_bf16 v[22:25], v[164:167], v[230:233], v[22:25]
	v_mfma_f32_16x16x32_bf16 v[18:21], v[172:175], v[230:233], v[18:21]
	v_mfma_f32_16x16x32_bf16 v[6:9], v[164:167], v[238:241], v[6:9]
	v_mfma_f32_16x16x32_bf16 v[2:5], v[172:175], v[238:241], v[2:5]
	s_barrier
	s_setprio 0
	s_add_i32 s51, 0, 0x18000
	s_add_i32 s52, 0, 0x1c000
	v_add_u32_e32 v156, s51, v149
	v_add_u32_e32 v172, s52, v149
	ds_read_b128 v[130:133], v156
	ds_read_b128 v[142:145], v156 offset:1024
	ds_read_b128 v[152:155], v156 offset:2048
	ds_read_b128 v[156:159], v156 offset:3072
	ds_read_b128 v[160:163], v172
	ds_read_b128 v[164:167], v172 offset:1024
	ds_read_b128 v[168:171], v172 offset:2048
	ds_read_b128 v[172:175], v172 offset:3072
	s_add_u32 s30, s30, 0x400000
	s_addc_u32 s31, s31, 0
	s_mov_b32 m0, s39
	v_lshl_add_u64 v[212:213], s[30:31], 0, v[134:135]
	ds_read_b128 v[188:191], v151 offset:32768
	ds_read_b128 v[206:209], v151 offset:33792
	ds_read_b128 v[218:221], v151 offset:34816
	ds_read_b128 v[222:225], v151 offset:35840
	ds_read_b128 v[226:229], v151 offset:36864
	ds_read_b128 v[230:233], v151 offset:37888
	ds_read_b128 v[234:237], v151 offset:38912
	ds_read_b128 v[238:241], v151 offset:39936
	global_load_lds_dwordx4 v[212:213], off
	s_mov_b32 m0, s40
	v_lshl_add_u64 v[212:213], s[30:31], 0, v[136:137]
	global_load_lds_dwordx4 v[212:213], off
	s_waitcnt vmcnt(8)
	s_waitcnt lgkmcnt(0)
	s_setprio 1
	s_barrier
	v_mfma_f32_16x16x32_bf16 v[126:129], v[130:133], v[188:191], v[126:129]
	v_mfma_f32_16x16x32_bf16 v[122:125], v[152:155], v[188:191], v[122:125]
	v_mfma_f32_16x16x32_bf16 v[110:113], v[130:133], v[218:221], v[110:113]
	v_mfma_f32_16x16x32_bf16 v[106:109], v[152:155], v[218:221], v[106:109]
	v_mfma_f32_16x16x32_bf16 v[94:97], v[130:133], v[226:229], v[94:97]
	v_mfma_f32_16x16x32_bf16 v[90:93], v[152:155], v[226:229], v[90:93]
	v_mfma_f32_16x16x32_bf16 v[78:81], v[130:133], v[234:237], v[78:81]
	v_mfma_f32_16x16x32_bf16 v[74:77], v[152:155], v[234:237], v[74:77]
	v_mfma_f32_16x16x32_bf16 v[126:129], v[142:145], v[206:209], v[126:129]
	v_mfma_f32_16x16x32_bf16 v[122:125], v[156:159], v[206:209], v[122:125]
	v_mfma_f32_16x16x32_bf16 v[110:113], v[142:145], v[222:225], v[110:113]
	v_mfma_f32_16x16x32_bf16 v[106:109], v[156:159], v[222:225], v[106:109]
	v_mfma_f32_16x16x32_bf16 v[94:97], v[142:145], v[230:233], v[94:97]
	v_mfma_f32_16x16x32_bf16 v[90:93], v[156:159], v[230:233], v[90:93]
	v_mfma_f32_16x16x32_bf16 v[78:81], v[142:145], v[238:241], v[78:81]
	v_mfma_f32_16x16x32_bf16 v[74:77], v[156:159], v[238:241], v[74:77]
	v_mfma_f32_16x16x32_bf16 v[118:121], v[160:163], v[188:191], v[118:121]
	v_mfma_f32_16x16x32_bf16 v[114:117], v[168:171], v[188:191], v[114:117]
	v_mfma_f32_16x16x32_bf16 v[102:105], v[160:163], v[218:221], v[102:105]
	v_mfma_f32_16x16x32_bf16 v[98:101], v[168:171], v[218:221], v[98:101]
	v_mfma_f32_16x16x32_bf16 v[86:89], v[160:163], v[226:229], v[86:89]
	v_mfma_f32_16x16x32_bf16 v[82:85], v[168:171], v[226:229], v[82:85]
	v_mfma_f32_16x16x32_bf16 v[70:73], v[160:163], v[234:237], v[70:73]
	v_mfma_f32_16x16x32_bf16 v[66:69], v[168:171], v[234:237], v[66:69]
	v_mfma_f32_16x16x32_bf16 v[118:121], v[164:167], v[206:209], v[118:121]
	v_mfma_f32_16x16x32_bf16 v[114:117], v[172:175], v[206:209], v[114:117]
	v_mfma_f32_16x16x32_bf16 v[102:105], v[164:167], v[222:225], v[102:105]
	v_mfma_f32_16x16x32_bf16 v[98:101], v[172:175], v[222:225], v[98:101]
	v_mfma_f32_16x16x32_bf16 v[86:89], v[164:167], v[230:233], v[86:89]
	v_mfma_f32_16x16x32_bf16 v[82:85], v[172:175], v[230:233], v[82:85]
	v_mfma_f32_16x16x32_bf16 v[70:73], v[164:167], v[238:241], v[70:73]
	v_mfma_f32_16x16x32_bf16 v[66:69], v[172:175], v[238:241], v[66:69]
	s_barrier
; #define PG8_STAGE(bufoff, gbase, voff) do { _Pragma("unroll") for (int _i = 0; _i < 2; ++_i) \
;         __builtin_amdgcn_global_load_lds((const unsigned*)((const char*)(gbase) + (voff)[_i]), (PG8_LAS unsigned*)(lds + (bufoff) + ldsw + _i * 8192), 16, 0, 0); } while (0)
; #define PG8_LDA(dst, b, h) do { _Pragma("unroll") for (int m = 0; m < 4; ++m) _Pragma("unroll") for (int k = 0; k < 2; ++k) dst[m][k] = *(const PG8_LAS bf16x8*)(lds + PG8_SA(b, h) + aoff + m * 2048 + k * 1024); } while (0)
; #define PG8_MMA(ai, bj, At, Bt) do { __builtin_amdgcn_s_setprio(1); _Pragma("unroll") for (int m = 0; m < 4; ++m) _Pragma("unroll") for (int n = 0; n < 2; ++n) _Pragma("unroll") for (int k = 0; k < 2; ++k) \
;         acc[ai][bj][m][n] = __builtin_amdgcn_mfma_f32_16x16x32_bf16(Bt[n][k], At[m][k], acc[ai][bj][m][n], 0, 0, 0); __builtin_amdgcn_s_setprio(0); } while (0)
; #define PG8_WAIT_V(n) asm volatile("s_waitcnt vmcnt(" #n ")" ::: "memory")
; #define PG8_WAIT_L(n) asm volatile("s_waitcnt lgkmcnt(" #n ")" ::: "memory")
; #define PG8_BAR __builtin_amdgcn_s_barrier()
; #define PG8_SCHED __builtin_amdgcn_sched_barrier(0)
; template <class Epi, class Sched, bool ALIGN_EPI, int LMASK = -1, int LMASKB = LMASK>
; __device__ __forceinline__ void gemm_phase(PG8_LAS unsigned char* lds, const Gemm g, const Sched& S, const Epi& E) {
;     ...
;             PG8_LDA(At, 1, 1); PG8_STAGE(PG8_SB(1, 0), b3, voffB); PG8_STAGE(PG8_SB(1, 1), b3 + hstepB, voffB); PG8_STAGE(PG8_SA(1, 0), a3, voffA);
;             PG8_WAIT_V(8); PG8_WAIT_L(0); PG8_BAR; PG8_MMA(1, 0, At, B0); PG8_MMA(1, 1, At, B1); PG8_BAR; PG8_SCHED;
;         }
	s_setprio 0
	s_add_i32 s30, s51, s38
	v_lshl_add_u64 v[146:147], v[146:147], 0, s[80:81]
	s_mov_b32 m0, s30
	ds_read_b128 v[188:191], v151 offset:49152
	ds_read_b128 v[206:209], v151 offset:50176
	ds_read_b128 v[218:221], v151 offset:51200
	ds_read_b128 v[222:225], v151 offset:52224
	ds_read_b128 v[226:229], v151 offset:53248
	ds_read_b128 v[230:233], v151 offset:54272
	ds_read_b128 v[234:237], v151 offset:55296
	ds_read_b128 v[238:241], v151 offset:56320
	global_load_lds_dwordx4 v[146:147], off
	s_add_i32 m0, s30, 0x2000
	s_add_u32 s2, s2, 0x400800
	v_lshl_add_u64 v[146:147], v[176:177], 0, s[80:81]
	s_addc_u32 s3, s3, 0
	s_add_i32 s30, s52, s38
	global_load_lds_dwordx4 v[146:147], off
	s_mov_b32 m0, s30
	v_lshl_add_u64 v[146:147], s[2:3], 0, v[134:135]
	global_load_lds_dwordx4 v[146:147], off
	s_add_i32 m0, s30, 0x2000
	v_lshl_add_u64 v[146:147], s[2:3], 0, v[136:137]
	global_load_lds_dwordx4 v[146:147], off
	s_mov_b32 m0, s41
	v_lshl_add_u64 v[146:147], v[194:195], 0, s[80:81]
	global_load_lds_dwordx4 v[146:147], off
	s_mov_b32 m0, s42
	v_lshl_add_u64 v[146:147], v[210:211], 0, s[80:81]
	global_load_lds_dwordx4 v[146:147], off
	s_waitcnt vmcnt(8)
	s_waitcnt lgkmcnt(0)
	s_setprio 1
	s_barrier
	v_mfma_f32_16x16x32_bf16 v[62:65], v[130:133], v[188:191], v[62:65]
	v_mfma_f32_16x16x32_bf16 v[58:61], v[152:155], v[188:191], v[58:61]
	v_mfma_f32_16x16x32_bf16 v[46:49], v[130:133], v[218:221], v[46:49]
	v_mfma_f32_16x16x32_bf16 v[42:45], v[152:155], v[218:221], v[42:45]
	v_mfma_f32_16x16x32_bf16 v[30:33], v[130:133], v[226:229], v[30:33]
	v_mfma_f32_16x16x32_bf16 v[26:29], v[152:155], v[226:229], v[26:29]
	v_mfma_f32_16x16x32_bf16 v[14:17], v[130:133], v[234:237], v[14:17]
	v_mfma_f32_16x16x32_bf16 v[10:13], v[152:155], v[234:237], v[10:13]
	v_mfma_f32_16x16x32_bf16 v[62:65], v[142:145], v[206:209], v[62:65]
	v_mfma_f32_16x16x32_bf16 v[58:61], v[156:159], v[206:209], v[58:61]
	v_mfma_f32_16x16x32_bf16 v[46:49], v[142:145], v[222:225], v[46:49]
	v_mfma_f32_16x16x32_bf16 v[42:45], v[156:159], v[222:225], v[42:45]
	v_mfma_f32_16x16x32_bf16 v[30:33], v[142:145], v[230:233], v[30:33]
	v_mfma_f32_16x16x32_bf16 v[26:29], v[156:159], v[230:233], v[26:29]
	v_mfma_f32_16x16x32_bf16 v[14:17], v[142:145], v[238:241], v[14:17]
	v_mfma_f32_16x16x32_bf16 v[10:13], v[156:159], v[238:241], v[10:13]
	v_mfma_f32_16x16x32_bf16 v[54:57], v[160:163], v[188:191], v[54:57]
	v_mfma_f32_16x16x32_bf16 v[50:53], v[168:171], v[188:191], v[50:53]
	v_mfma_f32_16x16x32_bf16 v[38:41], v[160:163], v[218:221], v[38:41]
	v_mfma_f32_16x16x32_bf16 v[34:37], v[168:171], v[218:221], v[34:37]
	v_mfma_f32_16x16x32_bf16 v[22:25], v[160:163], v[226:229], v[22:25]
	v_mfma_f32_16x16x32_bf16 v[18:21], v[168:171], v[226:229], v[18:21]
	v_mfma_f32_16x16x32_bf16 v[6:9], v[160:163], v[234:237], v[6:9]
	v_mfma_f32_16x16x32_bf16 v[2:5], v[168:171], v[234:237], v[2:5]
	v_mfma_f32_16x16x32_bf16 v[54:57], v[164:167], v[206:209], v[54:57]
	v_mfma_f32_16x16x32_bf16 v[50:53], v[172:175], v[206:209], v[50:53]
	v_mfma_f32_16x16x32_bf16 v[38:41], v[164:167], v[222:225], v[38:41]
	v_mfma_f32_16x16x32_bf16 v[34:37], v[172:175], v[222:225], v[34:37]
	v_mfma_f32_16x16x32_bf16 v[22:25], v[164:167], v[230:233], v[22:25]
	v_mfma_f32_16x16x32_bf16 v[18:21], v[172:175], v[230:233], v[18:21]
	v_mfma_f32_16x16x32_bf16 v[6:9], v[164:167], v[238:241], v[6:9]
	v_mfma_f32_16x16x32_bf16 v[2:5], v[172:175], v[238:241], v[2:5]
	s_barrier
	s_setprio 0
	s_add_i32 s50, s50, 2
	s_add_u32 s28, s28, 0x1000
	s_addc_u32 s29, s29, 0
	s_add_u32 s48, s48, 0x1000
	s_addc_u32 s49, s49, 0
	s_cmpk_gt_u32 s50, 0xfd
	s_cbranch_scc0 .LBB0_761
	s_and_b64 vcc, exec, s[14:15]
	s_cbranch_vccz .LBB0_764
	s_barrier
